# nt (streaming) cache policy on GEMM epilogue stores, on top of the DMA-in-MFMA-block placement
# speedup vs baseline: 1.0024x; 1.0024x over previous
; __device__ __forceinline__ unsigned cvt_pk_bf16(float lo, float hi) { unsigned r; asm volatile("v_cvt_pk_bf16_f32 %0, %1, %2" : "=v"(r) : "v"(lo), "v"(hi)); return r; }
; __device__ __forceinline__ float silu_f(float v) { return v * __builtin_amdgcn_rcpf(1.0f + __expf(-v)); }
;     __device__ __forceinline__ void operator()(const f32x4 (&acc)[2][2][4][2], const Unit& u, int wr, int wc, int fr, int fq) const {
;     ...
;                 const int r = row0 + ai * HALF + m * 16; const float rs = rsv[ai][m];
;                 if (pn == 8) {
;                     if (wc == 0) { const f32x4 v0 = acc[ai][0][m][0] * rs, v1 = acc[ai][0][m][1] * rs; u32x4 w; w.x = cvt_pk_bf16(v0[0], v0[1]); w.y = cvt_pk_bf16(v0[2], v0[3]); w.z = cvt_pk_bf16(v1[0], v1[1]); w.w = cvt_pk_bf16(v1[2], v1[3]); *(u32x4*)(DEC + (size_t)r * 32 + 8 * fq) = w; }
;                 } else {
;                     bf16_t* rowp = Z + (size_t)r * ZW + pn * BM + wc * 32 + 8 * fq;
; #pragma unroll
;                     for (int bj = 0; bj < 2; ++bj) { f32x4 v0 = acc[ai][bj][m][0] * rs, v1 = acc[ai][bj][m][1] * rs;
;                         if (pn >= 4 && pn < 6) {
; #pragma unroll
;                             for (int j = 0; j < 4; ++j) { v0[j] = silu_f(v0[j]); v1[j] = silu_f(v1[j]); } }
;                         u32x4 w; w.x = cvt_pk_bf16(v0[0], v0[1]); w.y = cvt_pk_bf16(v0[2], v0[3]); w.z = cvt_pk_bf16(v1[0], v1[1]); w.w = cvt_pk_bf16(v1[2], v1[3]);
;                         *(u32x4*)(rowp + bj * HALF) = w; }
.LBB0_134:
	v_mov_b64_e32 v[130:131], s[60:61]
	v_mad_i64_i32 v[130:131], s[14:15], v180, s1, v[130:131]
	v_lshl_add_u64 v[130:131], s[96:97], 1, v[130:131]
	s_lshl_b32 s76, s7, 1
	v_mov_b32_e32 v142, v188
	v_mov_b32_e32 v143, v188
	v_lshl_add_u64 v[130:131], v[130:131], 0, s[76:77]
	v_lshlrev_b32_e32 v152, 1, v170
	v_cvt_pk_bf16_f32 v146, v134, v135
	v_cvt_pk_bf16_f32 v147, v132, v133
	v_mov_b32_e32 v132, v188
	v_mov_b32_e32 v133, v188
	v_lshl_add_u64 v[130:131], v[130:131], 0, v[152:153]
	v_pk_mul_f32 v[126:127], v[126:127], v[132:133]
	v_pk_mul_f32 v[124:125], v[124:125], v[142:143]
	v_pk_mul_f32 v[122:123], v[122:123], v[132:133]
	s_and_b64 vcc, exec, s[42:43]
	v_pk_mul_f32 v[120:121], v[120:121], v[142:143]
	v_cvt_pk_bf16_f32 v148, v138, v139
	v_cvt_pk_bf16_f32 v149, v140, v141
	global_store_dwordx4 v[130:131], v[146:149], off nt
	s_cbranch_vccnz .LBB0_136
	v_mul_f32_e32 v133, 0xbfb8aa3b, v120
	v_exp_f32_e32 v133, v133
	v_mul_f32_e32 v132, 0xbfb8aa3b, v124
	v_exp_f32_e32 v132, v132
	v_mul_f32_e32 v139, 0xbfb8aa3b, v122
	v_add_f32_e32 v133, 1.0, v133
	v_rcp_f32_e32 v134, v133
	v_mul_f32_e32 v133, 0xbfb8aa3b, v125
	v_exp_f32_e32 v133, v133
	v_add_f32_e32 v132, 1.0, v132
	v_exp_f32_e32 v139, v139
	v_rcp_f32_e32 v132, v132
	v_add_f32_e32 v133, 1.0, v133
	v_rcp_f32_e32 v133, v133
	v_add_f32_e32 v139, 1.0, v139
	v_mul_f32_e32 v135, 0xbfb8aa3b, v121
	v_mul_f32_e32 v138, 0xbfb8aa3b, v126
	v_rcp_f32_e32 v140, v139
	v_mul_f32_e32 v139, 0xbfb8aa3b, v127
	v_pk_mul_f32 v[124:125], v[124:125], v[132:133]
	v_mul_f32_e32 v132, 0xbfb8aa3b, v123
	v_exp_f32_e32 v135, v135
	v_exp_f32_e32 v138, v138
	v_exp_f32_e32 v139, v139
	v_exp_f32_e32 v132, v132
	v_add_f32_e32 v135, 1.0, v135
	v_add_f32_e32 v138, 1.0, v138
	v_add_f32_e32 v139, 1.0, v139
	v_add_f32_e32 v132, 1.0, v132
	v_rcp_f32_e32 v135, v135
	v_rcp_f32_e32 v138, v138
	v_rcp_f32_e32 v139, v139
	v_rcp_f32_e32 v141, v132
	v_pk_mul_f32 v[120:121], v[120:121], v[134:135]
	v_pk_mul_f32 v[126:127], v[126:127], v[138:139]
	v_pk_mul_f32 v[122:123], v[122:123], v[140:141]
.LBB0_136:
	s_mov_b64 s[44:45], 0
	v_cvt_pk_bf16_f32 v124, v124, v125
	v_cvt_pk_bf16_f32 v125, v126, v127
	v_cvt_pk_bf16_f32 v126, v120, v121
	v_cvt_pk_bf16_f32 v127, v122, v123
	global_store_dwordx4 v[130:131], v[124:127], off offset:256 nt
.LBB0_137:
	v_cndmask_b32_e64 v120, 0, 1, s[70:71]
	s_and_b64 vcc, exec, s[44:45]
	v_cmp_ne_u32_e64 s[44:45], 1, v120
	s_cbranch_vccz .LBB0_140
	s_and_b64 vcc, exec, s[44:45]
	s_cbranch_vccnz .LBB0_140
	s_waitcnt lgkmcnt(0)
	v_pk_mul_f32 v[116:117], v[116:117], v[188:189] op_sel_hi:[1,0]
	v_ashrrev_i32_e32 v181, 31, v180
	v_pk_mul_f32 v[120:121], v[114:115], v[188:189] op_sel_hi:[1,0]
	v_pk_mul_f32 v[114:115], v[112:113], v[188:189] op_sel_hi:[1,0]
	v_cvt_pk_bf16_f32 v112, v116, v117
	v_lshlrev_b64 v[116:117], 6, v[180:181]
	v_lshl_add_u64 v[116:117], v[172:173], 0, v[116:117]
	v_pk_mul_f32 v[118:119], v[118:119], v[188:189] op_sel_hi:[1,0]
	s_nop 0
	v_cvt_pk_bf16_f32 v113, v118, v119
	v_cvt_pk_bf16_f32 v114, v114, v115
	v_cvt_pk_bf16_f32 v115, v120, v121
	global_store_dwordx4 v[116:117], v[112:115], off nt

; __device__ __forceinline__ unsigned cvt_pk_bf16(float lo, float hi) { unsigned r; asm volatile("v_cvt_pk_bf16_f32 %0, %1, %2" : "=v"(r) : "v"(lo), "v"(hi)); return r; }
; __device__ __forceinline__ float silu_f(float v) { return v * __builtin_amdgcn_rcpf(1.0f + __expf(-v)); }
;     __device__ __forceinline__ void operator()(const f32x4 (&acc)[2][2][4][2], const Unit& u, int wr, int wc, int fr, int fq) const {
;     ...
;                 const int r = row0 + ai * HALF + m * 16; const float rs = rsv[ai][m];
;                 if (pn == 8) {
;                     if (wc == 0) { const f32x4 v0 = acc[ai][0][m][0] * rs, v1 = acc[ai][0][m][1] * rs; u32x4 w; w.x = cvt_pk_bf16(v0[0], v0[1]); w.y = cvt_pk_bf16(v0[2], v0[3]); w.z = cvt_pk_bf16(v1[0], v1[1]); w.w = cvt_pk_bf16(v1[2], v1[3]); *(u32x4*)(DEC + (size_t)r * 32 + 8 * fq) = w; }
;                 } else {
;                     bf16_t* rowp = Z + (size_t)r * ZW + pn * BM + wc * 32 + 8 * fq;
; #pragma unroll
;                     for (int bj = 0; bj < 2; ++bj) { f32x4 v0 = acc[ai][bj][m][0] * rs, v1 = acc[ai][bj][m][1] * rs;
;                         if (pn >= 4 && pn < 6) {
; #pragma unroll
;                             for (int j = 0; j < 4; ++j) { v0[j] = silu_f(v0[j]); v1[j] = silu_f(v1[j]); } }
;                         u32x4 w; w.x = cvt_pk_bf16(v0[0], v0[1]); w.y = cvt_pk_bf16(v0[2], v0[3]); w.z = cvt_pk_bf16(v1[0], v1[1]); w.w = cvt_pk_bf16(v1[2], v1[3]);
;                         *(u32x4*)(rowp + bj * HALF) = w; }
.LBB0_143:
	v_mov_b64_e32 v[112:113], s[60:61]
	v_mad_i64_i32 v[112:113], s[14:15], v186, s1, v[112:113]
	v_lshl_add_u64 v[112:113], s[96:97], 1, v[112:113]
	s_lshl_b32 s76, s7, 1
	v_mov_b32_e32 v122, v189
	v_mov_b32_e32 v123, v189
	v_lshl_add_u64 v[112:113], v[112:113], 0, s[76:77]
	v_lshlrev_b32_e32 v152, 1, v170
	v_cvt_pk_bf16_f32 v116, v116, v117
	v_cvt_pk_bf16_f32 v117, v114, v115
	v_mov_b32_e32 v114, v189
	v_mov_b32_e32 v115, v189
	v_lshl_add_u64 v[112:113], v[112:113], 0, v[152:153]
	v_pk_mul_f32 v[110:111], v[110:111], v[114:115]
	v_pk_mul_f32 v[108:109], v[108:109], v[122:123]
	v_pk_mul_f32 v[106:107], v[106:107], v[114:115]
	s_and_b64 vcc, exec, s[42:43]
	v_pk_mul_f32 v[104:105], v[104:105], v[122:123]
	v_cvt_pk_bf16_f32 v118, v118, v119
	v_cvt_pk_bf16_f32 v119, v120, v121
	global_store_dwordx4 v[112:113], v[116:119], off nt
	s_cbranch_vccnz .LBB0_145
	v_mul_f32_e32 v115, 0xbfb8aa3b, v104
	v_exp_f32_e32 v115, v115
	v_mul_f32_e32 v114, 0xbfb8aa3b, v108
	v_exp_f32_e32 v114, v114
	v_mul_f32_e32 v119, 0xbfb8aa3b, v106
	v_add_f32_e32 v115, 1.0, v115
	v_rcp_f32_e32 v116, v115
	v_mul_f32_e32 v115, 0xbfb8aa3b, v109
	v_exp_f32_e32 v115, v115
	v_add_f32_e32 v114, 1.0, v114
	v_exp_f32_e32 v119, v119
	v_rcp_f32_e32 v114, v114
	v_add_f32_e32 v115, 1.0, v115
	v_rcp_f32_e32 v115, v115
	v_add_f32_e32 v119, 1.0, v119
	v_mul_f32_e32 v117, 0xbfb8aa3b, v105
	v_mul_f32_e32 v118, 0xbfb8aa3b, v110
	v_rcp_f32_e32 v120, v119
	v_mul_f32_e32 v119, 0xbfb8aa3b, v111
	v_pk_mul_f32 v[108:109], v[108:109], v[114:115]
	v_mul_f32_e32 v114, 0xbfb8aa3b, v107
	v_exp_f32_e32 v117, v117
	v_exp_f32_e32 v118, v118
	v_exp_f32_e32 v119, v119
	v_exp_f32_e32 v114, v114
	v_add_f32_e32 v117, 1.0, v117
	v_add_f32_e32 v118, 1.0, v118
	v_add_f32_e32 v119, 1.0, v119
	v_add_f32_e32 v114, 1.0, v114
	v_rcp_f32_e32 v117, v117
	v_rcp_f32_e32 v118, v118
	v_rcp_f32_e32 v119, v119
	v_rcp_f32_e32 v121, v114
	v_pk_mul_f32 v[104:105], v[104:105], v[116:117]
	v_pk_mul_f32 v[110:111], v[110:111], v[118:119]
	v_pk_mul_f32 v[106:107], v[106:107], v[120:121]
.LBB0_145:
	s_mov_b64 s[98:99], 0
	v_cvt_pk_bf16_f32 v108, v108, v109
	v_cvt_pk_bf16_f32 v109, v110, v111
	v_cvt_pk_bf16_f32 v110, v104, v105
	v_cvt_pk_bf16_f32 v111, v106, v107
	global_store_dwordx4 v[112:113], v[108:111], off offset:256 nt

; __device__ __forceinline__ unsigned cvt_pk_bf16(float lo, float hi) { unsigned r; asm volatile("v_cvt_pk_bf16_f32 %0, %1, %2" : "=v"(r) : "v"(lo), "v"(hi)); return r; }
; __device__ __forceinline__ float silu_f(float v) { return v * __builtin_amdgcn_rcpf(1.0f + __expf(-v)); }
;     __device__ __forceinline__ void operator()(const f32x4 (&acc)[2][2][4][2], const Unit& u, int wr, int wc, int fr, int fq) const {
;     ...
;                 const int r = row0 + ai * HALF + m * 16; const float rs = rsv[ai][m];
;                 if (pn == 8) {
;                     if (wc == 0) { const f32x4 v0 = acc[ai][0][m][0] * rs, v1 = acc[ai][0][m][1] * rs; u32x4 w; w.x = cvt_pk_bf16(v0[0], v0[1]); w.y = cvt_pk_bf16(v0[2], v0[3]); w.z = cvt_pk_bf16(v1[0], v1[1]); w.w = cvt_pk_bf16(v1[2], v1[3]); *(u32x4*)(DEC + (size_t)r * 32 + 8 * fq) = w; }
;                 } else {
;                     bf16_t* rowp = Z + (size_t)r * ZW + pn * BM + wc * 32 + 8 * fq;
; #pragma unroll
;                     for (int bj = 0; bj < 2; ++bj) { f32x4 v0 = acc[ai][bj][m][0] * rs, v1 = acc[ai][bj][m][1] * rs;
;                         if (pn >= 4 && pn < 6) {
; #pragma unroll
;                             for (int j = 0; j < 4; ++j) { v0[j] = silu_f(v0[j]); v1[j] = silu_f(v1[j]); } }
;                         u32x4 w; w.x = cvt_pk_bf16(v0[0], v0[1]); w.y = cvt_pk_bf16(v0[2], v0[3]); w.z = cvt_pk_bf16(v1[0], v1[1]); w.w = cvt_pk_bf16(v1[2], v1[3]);
;                         *(u32x4*)(rowp + bj * HALF) = w; }
.LBB0_151:
	v_mov_b64_e32 v[96:97], s[60:61]
	v_mad_i64_i32 v[96:97], s[14:15], v184, s1, v[96:97]
	v_lshl_add_u64 v[96:97], s[96:97], 1, v[96:97]
	s_lshl_b32 s76, s7, 1
	v_mov_b32_e32 v106, v144
	v_mov_b32_e32 v107, v144
	v_lshl_add_u64 v[96:97], v[96:97], 0, s[76:77]
	v_lshlrev_b32_e32 v152, 1, v170
	v_cvt_pk_bf16_f32 v100, v100, v101
	v_cvt_pk_bf16_f32 v101, v98, v99
	v_mov_b32_e32 v98, v144
	v_mov_b32_e32 v99, v144
	v_lshl_add_u64 v[96:97], v[96:97], 0, v[152:153]
	v_pk_mul_f32 v[94:95], v[94:95], v[98:99]
	v_pk_mul_f32 v[92:93], v[92:93], v[106:107]
	v_pk_mul_f32 v[90:91], v[90:91], v[98:99]
	s_and_b64 vcc, exec, s[42:43]
	v_pk_mul_f32 v[88:89], v[88:89], v[106:107]
	v_cvt_pk_bf16_f32 v102, v102, v103
	v_cvt_pk_bf16_f32 v103, v104, v105
	global_store_dwordx4 v[96:97], v[100:103], off nt
	s_cbranch_vccnz .LBB0_153
	v_mul_f32_e32 v99, 0xbfb8aa3b, v88
	v_exp_f32_e32 v99, v99
	v_mul_f32_e32 v98, 0xbfb8aa3b, v92
	v_exp_f32_e32 v98, v98
	v_mul_f32_e32 v103, 0xbfb8aa3b, v90
	v_add_f32_e32 v99, 1.0, v99
	v_rcp_f32_e32 v100, v99
	v_mul_f32_e32 v99, 0xbfb8aa3b, v93
	v_exp_f32_e32 v99, v99
	v_add_f32_e32 v98, 1.0, v98
	v_exp_f32_e32 v103, v103
	v_rcp_f32_e32 v98, v98
	v_add_f32_e32 v99, 1.0, v99
	v_rcp_f32_e32 v99, v99
	v_add_f32_e32 v103, 1.0, v103
	v_mul_f32_e32 v101, 0xbfb8aa3b, v89
	v_mul_f32_e32 v102, 0xbfb8aa3b, v94
	v_rcp_f32_e32 v104, v103
	v_mul_f32_e32 v103, 0xbfb8aa3b, v95
	v_pk_mul_f32 v[92:93], v[92:93], v[98:99]
	v_mul_f32_e32 v98, 0xbfb8aa3b, v91
	v_exp_f32_e32 v101, v101
	v_exp_f32_e32 v102, v102
	v_exp_f32_e32 v103, v103
	v_exp_f32_e32 v98, v98
	v_add_f32_e32 v101, 1.0, v101
	v_add_f32_e32 v102, 1.0, v102
	v_add_f32_e32 v103, 1.0, v103
	v_add_f32_e32 v98, 1.0, v98
	v_rcp_f32_e32 v101, v101
	v_rcp_f32_e32 v102, v102
	v_rcp_f32_e32 v103, v103
	v_rcp_f32_e32 v105, v98
	v_pk_mul_f32 v[88:89], v[88:89], v[100:101]
	v_pk_mul_f32 v[94:95], v[94:95], v[102:103]
	v_pk_mul_f32 v[90:91], v[90:91], v[104:105]
.LBB0_153:
	s_mov_b64 s[98:99], 0
	v_cvt_pk_bf16_f32 v92, v92, v93
	v_cvt_pk_bf16_f32 v93, v94, v95
	v_cvt_pk_bf16_f32 v94, v88, v89
	v_cvt_pk_bf16_f32 v95, v90, v91
	global_store_dwordx4 v[96:97], v[92:95], off offset:256 nt

; __device__ __forceinline__ unsigned cvt_pk_bf16(float lo, float hi) { unsigned r; asm volatile("v_cvt_pk_bf16_f32 %0, %1, %2" : "=v"(r) : "v"(lo), "v"(hi)); return r; }
; __device__ __forceinline__ float silu_f(float v) { return v * __builtin_amdgcn_rcpf(1.0f + __expf(-v)); }
;     __device__ __forceinline__ void operator()(const f32x4 (&acc)[2][2][4][2], const Unit& u, int wr, int wc, int fr, int fq) const {
;     ...
;                 const int r = row0 + ai * HALF + m * 16; const float rs = rsv[ai][m];
;                 if (pn == 8) {
;                     if (wc == 0) { const f32x4 v0 = acc[ai][0][m][0] * rs, v1 = acc[ai][0][m][1] * rs; u32x4 w; w.x = cvt_pk_bf16(v0[0], v0[1]); w.y = cvt_pk_bf16(v0[2], v0[3]); w.z = cvt_pk_bf16(v1[0], v1[1]); w.w = cvt_pk_bf16(v1[2], v1[3]); *(u32x4*)(DEC + (size_t)r * 32 + 8 * fq) = w; }
;                 } else {
;                     bf16_t* rowp = Z + (size_t)r * ZW + pn * BM + wc * 32 + 8 * fq;
; #pragma unroll
;                     for (int bj = 0; bj < 2; ++bj) { f32x4 v0 = acc[ai][bj][m][0] * rs, v1 = acc[ai][bj][m][1] * rs;
;                         if (pn >= 4 && pn < 6) {
; #pragma unroll
;                             for (int j = 0; j < 4; ++j) { v0[j] = silu_f(v0[j]); v1[j] = silu_f(v1[j]); } }
;                         u32x4 w; w.x = cvt_pk_bf16(v0[0], v0[1]); w.y = cvt_pk_bf16(v0[2], v0[3]); w.z = cvt_pk_bf16(v1[0], v1[1]); w.w = cvt_pk_bf16(v1[2], v1[3]);
;                         *(u32x4*)(rowp + bj * HALF) = w; }
.LBB0_159:
	v_mov_b64_e32 v[80:81], s[60:61]
	v_mad_i64_i32 v[80:81], s[14:15], v182, s1, v[80:81]
	v_lshl_add_u64 v[80:81], s[96:97], 1, v[80:81]
	s_lshl_b32 s76, s7, 1
	v_mov_b32_e32 v90, v145
	v_mov_b32_e32 v91, v145
	v_lshl_add_u64 v[80:81], v[80:81], 0, s[76:77]
	v_lshlrev_b32_e32 v152, 1, v170
	v_cvt_pk_bf16_f32 v84, v84, v85
	v_cvt_pk_bf16_f32 v85, v82, v83
	v_mov_b32_e32 v82, v145
	v_mov_b32_e32 v83, v145
	v_lshl_add_u64 v[80:81], v[80:81], 0, v[152:153]
	v_pk_mul_f32 v[78:79], v[78:79], v[82:83]
	v_pk_mul_f32 v[76:77], v[76:77], v[90:91]
	v_pk_mul_f32 v[74:75], v[74:75], v[82:83]
	s_and_b64 vcc, exec, s[42:43]
	v_pk_mul_f32 v[72:73], v[72:73], v[90:91]
	v_cvt_pk_bf16_f32 v86, v86, v87
	v_cvt_pk_bf16_f32 v87, v88, v89
	global_store_dwordx4 v[80:81], v[84:87], off nt
	s_cbranch_vccnz .LBB0_161
	v_mul_f32_e32 v83, 0xbfb8aa3b, v72
	v_exp_f32_e32 v83, v83
	v_mul_f32_e32 v82, 0xbfb8aa3b, v76
	v_exp_f32_e32 v82, v82
	v_mul_f32_e32 v87, 0xbfb8aa3b, v74
	v_add_f32_e32 v83, 1.0, v83
	v_rcp_f32_e32 v84, v83
	v_mul_f32_e32 v83, 0xbfb8aa3b, v77
	v_exp_f32_e32 v83, v83
	v_add_f32_e32 v82, 1.0, v82
	v_exp_f32_e32 v87, v87
	v_rcp_f32_e32 v82, v82
	v_add_f32_e32 v83, 1.0, v83
	v_rcp_f32_e32 v83, v83
	v_add_f32_e32 v87, 1.0, v87
	v_mul_f32_e32 v85, 0xbfb8aa3b, v73
	v_mul_f32_e32 v86, 0xbfb8aa3b, v78
	v_rcp_f32_e32 v88, v87
	v_mul_f32_e32 v87, 0xbfb8aa3b, v79
	v_pk_mul_f32 v[76:77], v[76:77], v[82:83]
	v_mul_f32_e32 v82, 0xbfb8aa3b, v75
	v_exp_f32_e32 v85, v85
	v_exp_f32_e32 v86, v86
	v_exp_f32_e32 v87, v87
	v_exp_f32_e32 v82, v82
	v_add_f32_e32 v85, 1.0, v85
	v_add_f32_e32 v86, 1.0, v86
	v_add_f32_e32 v87, 1.0, v87
	v_add_f32_e32 v82, 1.0, v82
	v_rcp_f32_e32 v85, v85
	v_rcp_f32_e32 v86, v86
	v_rcp_f32_e32 v87, v87
	v_rcp_f32_e32 v89, v82
	v_pk_mul_f32 v[72:73], v[72:73], v[84:85]
	v_pk_mul_f32 v[78:79], v[78:79], v[86:87]
	v_pk_mul_f32 v[74:75], v[74:75], v[88:89]
.LBB0_161:
	s_mov_b64 s[98:99], 0
	v_cvt_pk_bf16_f32 v76, v76, v77
	v_cvt_pk_bf16_f32 v77, v78, v79
	v_cvt_pk_bf16_f32 v78, v72, v73
	v_cvt_pk_bf16_f32 v79, v74, v75
	global_store_dwordx4 v[80:81], v[76:79], off offset:256 nt

; __device__ __forceinline__ unsigned cvt_pk_bf16(float lo, float hi) { unsigned r; asm volatile("v_cvt_pk_bf16_f32 %0, %1, %2" : "=v"(r) : "v"(lo), "v"(hi)); return r; }
; __device__ __forceinline__ float silu_f(float v) { return v * __builtin_amdgcn_rcpf(1.0f + __expf(-v)); }
;     __device__ __forceinline__ void operator()(const f32x4 (&acc)[2][2][4][2], const Unit& u, int wr, int wc, int fr, int fq) const {
;     ...
;                 const int r = row0 + ai * HALF + m * 16; const float rs = rsv[ai][m];
;                 if (pn == 8) {
;                     if (wc == 0) { const f32x4 v0 = acc[ai][0][m][0] * rs, v1 = acc[ai][0][m][1] * rs; u32x4 w; w.x = cvt_pk_bf16(v0[0], v0[1]); w.y = cvt_pk_bf16(v0[2], v0[3]); w.z = cvt_pk_bf16(v1[0], v1[1]); w.w = cvt_pk_bf16(v1[2], v1[3]); *(u32x4*)(DEC + (size_t)r * 32 + 8 * fq) = w; }
;                 } else {
;                     bf16_t* rowp = Z + (size_t)r * ZW + pn * BM + wc * 32 + 8 * fq;
; #pragma unroll
;                     for (int bj = 0; bj < 2; ++bj) { f32x4 v0 = acc[ai][bj][m][0] * rs, v1 = acc[ai][bj][m][1] * rs;
;                         if (pn >= 4 && pn < 6) {
; #pragma unroll
;                             for (int j = 0; j < 4; ++j) { v0[j] = silu_f(v0[j]); v1[j] = silu_f(v1[j]); } }
;                         u32x4 w; w.x = cvt_pk_bf16(v0[0], v0[1]); w.y = cvt_pk_bf16(v0[2], v0[3]); w.z = cvt_pk_bf16(v1[0], v1[1]); w.w = cvt_pk_bf16(v1[2], v1[3]);
;                         *(u32x4*)(rowp + bj * HALF) = w; }
.LBB0_167:
	v_mov_b64_e32 v[66:67], s[60:61]
	v_mad_i64_i32 v[66:67], s[14:15], v64, s1, v[66:67]
	v_lshl_add_u64 v[66:67], s[96:97], 1, v[66:67]
	s_lshl_b32 s76, s7, 1
	v_mov_b32_e32 v76, v136
	v_mov_b32_e32 v77, v136
	v_lshl_add_u64 v[66:67], v[66:67], 0, s[76:77]
	v_lshlrev_b32_e32 v152, 1, v170
	v_cvt_pk_bf16_f32 v70, v70, v71
	v_cvt_pk_bf16_f32 v71, v68, v69
	v_mov_b32_e32 v68, v136
	v_mov_b32_e32 v69, v136
	v_lshl_add_u64 v[66:67], v[66:67], 0, v[152:153]
	v_pk_mul_f32 v[62:63], v[62:63], v[68:69]
	v_pk_mul_f32 v[60:61], v[60:61], v[76:77]
	v_pk_mul_f32 v[58:59], v[58:59], v[68:69]
	s_and_b64 vcc, exec, s[42:43]
	v_pk_mul_f32 v[56:57], v[56:57], v[76:77]
	v_cvt_pk_bf16_f32 v72, v72, v73
	v_cvt_pk_bf16_f32 v73, v74, v75
	global_store_dwordx4 v[66:67], v[70:73], off nt
	s_cbranch_vccnz .LBB0_169
	v_mul_f32_e32 v65, 0xbfb8aa3b, v60
	v_exp_f32_e32 v65, v65
	s_nop 0
	v_add_f32_e32 v65, 1.0, v65
	v_rcp_f32_e32 v68, v65
	v_mul_f32_e32 v65, 0xbfb8aa3b, v56
	v_exp_f32_e32 v65, v65
	s_nop 0
	v_add_f32_e32 v65, 1.0, v65
	v_rcp_f32_e32 v70, v65
	v_mul_f32_e32 v65, 0xbfb8aa3b, v61
	v_exp_f32_e32 v65, v65
	s_nop 0
	v_add_f32_e32 v65, 1.0, v65
	v_rcp_f32_e32 v69, v65
	v_mul_f32_e32 v65, 0xbfb8aa3b, v57
	v_exp_f32_e32 v65, v65
	v_pk_mul_f32 v[60:61], v[60:61], v[68:69]
	v_add_f32_e32 v65, 1.0, v65
	v_rcp_f32_e32 v71, v65
	v_mul_f32_e32 v65, 0xbfb8aa3b, v62
	v_exp_f32_e32 v65, v65
	v_pk_mul_f32 v[56:57], v[56:57], v[70:71]
	v_add_f32_e32 v65, 1.0, v65
	v_rcp_f32_e32 v72, v65
	v_mul_f32_e32 v65, 0xbfb8aa3b, v58
	v_exp_f32_e32 v65, v65
	s_nop 0
	v_add_f32_e32 v65, 1.0, v65
	v_rcp_f32_e32 v74, v65
	v_mul_f32_e32 v65, 0xbfb8aa3b, v63
	v_exp_f32_e32 v65, v65
	s_nop 0
	v_add_f32_e32 v65, 1.0, v65
	v_rcp_f32_e32 v73, v65
	v_mul_f32_e32 v65, 0xbfb8aa3b, v59
	v_exp_f32_e32 v65, v65
	v_pk_mul_f32 v[62:63], v[62:63], v[72:73]
	v_add_f32_e32 v65, 1.0, v65
	v_rcp_f32_e32 v75, v65
	s_nop 0
	v_pk_mul_f32 v[58:59], v[58:59], v[74:75]
.LBB0_169:
	s_mov_b64 s[98:99], 0
	v_cvt_pk_bf16_f32 v60, v60, v61
	v_cvt_pk_bf16_f32 v61, v62, v63
	v_cvt_pk_bf16_f32 v62, v56, v57
	v_cvt_pk_bf16_f32 v63, v58, v59
	global_store_dwordx4 v[66:67], v[60:63], off offset:256 nt

; __device__ __forceinline__ unsigned cvt_pk_bf16(float lo, float hi) { unsigned r; asm volatile("v_cvt_pk_bf16_f32 %0, %1, %2" : "=v"(r) : "v"(lo), "v"(hi)); return r; }
; __device__ __forceinline__ float silu_f(float v) { return v * __builtin_amdgcn_rcpf(1.0f + __expf(-v)); }
;     __device__ __forceinline__ void operator()(const f32x4 (&acc)[2][2][4][2], const Unit& u, int wr, int wc, int fr, int fq) const {
;     ...
;                 const int r = row0 + ai * HALF + m * 16; const float rs = rsv[ai][m];
;                 if (pn == 8) {
;                     if (wc == 0) { const f32x4 v0 = acc[ai][0][m][0] * rs, v1 = acc[ai][0][m][1] * rs; u32x4 w; w.x = cvt_pk_bf16(v0[0], v0[1]); w.y = cvt_pk_bf16(v0[2], v0[3]); w.z = cvt_pk_bf16(v1[0], v1[1]); w.w = cvt_pk_bf16(v1[2], v1[3]); *(u32x4*)(DEC + (size_t)r * 32 + 8 * fq) = w; }
;                 } else {
;                     bf16_t* rowp = Z + (size_t)r * ZW + pn * BM + wc * 32 + 8 * fq;
; #pragma unroll
;                     for (int bj = 0; bj < 2; ++bj) { f32x4 v0 = acc[ai][bj][m][0] * rs, v1 = acc[ai][bj][m][1] * rs;
;                         if (pn >= 4 && pn < 6) {
; #pragma unroll
;                             for (int j = 0; j < 4; ++j) { v0[j] = silu_f(v0[j]); v1[j] = silu_f(v1[j]); } }
;                         u32x4 w; w.x = cvt_pk_bf16(v0[0], v0[1]); w.y = cvt_pk_bf16(v0[2], v0[3]); w.z = cvt_pk_bf16(v1[0], v1[1]); w.w = cvt_pk_bf16(v1[2], v1[3]);
;                         *(u32x4*)(rowp + bj * HALF) = w; }
.LBB0_175:
	v_mov_b64_e32 v[50:51], s[60:61]
	v_mad_i64_i32 v[50:51], s[14:15], v48, s1, v[50:51]
	v_lshl_add_u64 v[50:51], s[96:97], 1, v[50:51]
	s_lshl_b32 s76, s7, 1
	v_mov_b32_e32 v60, v137
	v_mov_b32_e32 v61, v137
	v_lshl_add_u64 v[50:51], v[50:51], 0, s[76:77]
	v_lshlrev_b32_e32 v152, 1, v170
	v_cvt_pk_bf16_f32 v54, v54, v55
	v_cvt_pk_bf16_f32 v55, v52, v53
	v_mov_b32_e32 v52, v137
	v_mov_b32_e32 v53, v137
	v_lshl_add_u64 v[50:51], v[50:51], 0, v[152:153]
	v_pk_mul_f32 v[46:47], v[46:47], v[52:53]
	v_pk_mul_f32 v[44:45], v[44:45], v[60:61]
	v_pk_mul_f32 v[42:43], v[42:43], v[52:53]
	s_and_b64 vcc, exec, s[42:43]
	v_pk_mul_f32 v[40:41], v[40:41], v[60:61]
	v_cvt_pk_bf16_f32 v56, v56, v57
	v_cvt_pk_bf16_f32 v57, v58, v59
	global_store_dwordx4 v[50:51], v[54:57], off nt
	s_cbranch_vccnz .LBB0_177
	v_mul_f32_e32 v49, 0xbfb8aa3b, v44
	v_exp_f32_e32 v49, v49
	s_nop 0
	v_add_f32_e32 v49, 1.0, v49
	v_rcp_f32_e32 v52, v49
	v_mul_f32_e32 v49, 0xbfb8aa3b, v40
	v_exp_f32_e32 v49, v49
	s_nop 0
	v_add_f32_e32 v49, 1.0, v49
	v_rcp_f32_e32 v54, v49
	v_mul_f32_e32 v49, 0xbfb8aa3b, v45
	v_exp_f32_e32 v49, v49
	s_nop 0
	v_add_f32_e32 v49, 1.0, v49
	v_rcp_f32_e32 v53, v49
	v_mul_f32_e32 v49, 0xbfb8aa3b, v41
	v_exp_f32_e32 v49, v49
	v_pk_mul_f32 v[44:45], v[44:45], v[52:53]
	v_add_f32_e32 v49, 1.0, v49
	v_rcp_f32_e32 v55, v49
	v_mul_f32_e32 v49, 0xbfb8aa3b, v46
	v_exp_f32_e32 v49, v49
	v_pk_mul_f32 v[40:41], v[40:41], v[54:55]
	v_add_f32_e32 v49, 1.0, v49
	v_rcp_f32_e32 v56, v49
	v_mul_f32_e32 v49, 0xbfb8aa3b, v42
	v_exp_f32_e32 v49, v49
	s_nop 0
	v_add_f32_e32 v49, 1.0, v49
	v_rcp_f32_e32 v58, v49
	v_mul_f32_e32 v49, 0xbfb8aa3b, v47
	v_exp_f32_e32 v49, v49
	s_nop 0
	v_add_f32_e32 v49, 1.0, v49
	v_rcp_f32_e32 v57, v49
	v_mul_f32_e32 v49, 0xbfb8aa3b, v43
	v_exp_f32_e32 v49, v49
	v_pk_mul_f32 v[46:47], v[46:47], v[56:57]
	v_add_f32_e32 v49, 1.0, v49
	v_rcp_f32_e32 v59, v49
	s_nop 0
	v_pk_mul_f32 v[42:43], v[42:43], v[58:59]
.LBB0_177:
	s_mov_b64 s[98:99], 0
	v_cvt_pk_bf16_f32 v44, v44, v45
	v_cvt_pk_bf16_f32 v45, v46, v47
	v_cvt_pk_bf16_f32 v46, v40, v41
	v_cvt_pk_bf16_f32 v47, v42, v43
	global_store_dwordx4 v[50:51], v[44:47], off offset:256 nt

; __device__ __forceinline__ unsigned cvt_pk_bf16(float lo, float hi) { unsigned r; asm volatile("v_cvt_pk_bf16_f32 %0, %1, %2" : "=v"(r) : "v"(lo), "v"(hi)); return r; }
; __device__ __forceinline__ float silu_f(float v) { return v * __builtin_amdgcn_rcpf(1.0f + __expf(-v)); }
;     __device__ __forceinline__ void operator()(const f32x4 (&acc)[2][2][4][2], const Unit& u, int wr, int wc, int fr, int fq) const {
;     ...
;                 const int r = row0 + ai * HALF + m * 16; const float rs = rsv[ai][m];
;                 if (pn == 8) {
;                     if (wc == 0) { const f32x4 v0 = acc[ai][0][m][0] * rs, v1 = acc[ai][0][m][1] * rs; u32x4 w; w.x = cvt_pk_bf16(v0[0], v0[1]); w.y = cvt_pk_bf16(v0[2], v0[3]); w.z = cvt_pk_bf16(v1[0], v1[1]); w.w = cvt_pk_bf16(v1[2], v1[3]); *(u32x4*)(DEC + (size_t)r * 32 + 8 * fq) = w; }
;                 } else {
;                     bf16_t* rowp = Z + (size_t)r * ZW + pn * BM + wc * 32 + 8 * fq;
; #pragma unroll
;                     for (int bj = 0; bj < 2; ++bj) { f32x4 v0 = acc[ai][bj][m][0] * rs, v1 = acc[ai][bj][m][1] * rs;
;                         if (pn >= 4 && pn < 6) {
; #pragma unroll
;                             for (int j = 0; j < 4; ++j) { v0[j] = silu_f(v0[j]); v1[j] = silu_f(v1[j]); } }
;                         u32x4 w; w.x = cvt_pk_bf16(v0[0], v0[1]); w.y = cvt_pk_bf16(v0[2], v0[3]); w.z = cvt_pk_bf16(v1[0], v1[1]); w.w = cvt_pk_bf16(v1[2], v1[3]);
;                         *(u32x4*)(rowp + bj * HALF) = w; }
.LBB0_183:
	v_mov_b64_e32 v[34:35], s[60:61]
	v_mad_i64_i32 v[34:35], s[14:15], v32, s1, v[34:35]
	v_lshl_add_u64 v[34:35], s[96:97], 1, v[34:35]
	s_lshl_b32 s76, s7, 1
	v_mov_b32_e32 v44, v128
	v_mov_b32_e32 v45, v128
	v_lshl_add_u64 v[34:35], v[34:35], 0, s[76:77]
	v_lshlrev_b32_e32 v152, 1, v170
	v_cvt_pk_bf16_f32 v38, v38, v39
	v_cvt_pk_bf16_f32 v39, v36, v37
	v_mov_b32_e32 v36, v128
	v_mov_b32_e32 v37, v128
	v_lshl_add_u64 v[34:35], v[34:35], 0, v[152:153]
	v_pk_mul_f32 v[30:31], v[30:31], v[36:37]
	v_pk_mul_f32 v[28:29], v[28:29], v[44:45]
	v_pk_mul_f32 v[26:27], v[26:27], v[36:37]
	s_and_b64 vcc, exec, s[42:43]
	v_pk_mul_f32 v[24:25], v[24:25], v[44:45]
	v_cvt_pk_bf16_f32 v40, v40, v41
	v_cvt_pk_bf16_f32 v41, v42, v43
	global_store_dwordx4 v[34:35], v[38:41], off nt
	s_cbranch_vccnz .LBB0_185
	v_mul_f32_e32 v33, 0xbfb8aa3b, v28
	v_exp_f32_e32 v33, v33
	s_nop 0
	v_add_f32_e32 v33, 1.0, v33
	v_rcp_f32_e32 v36, v33
	v_mul_f32_e32 v33, 0xbfb8aa3b, v24
	v_exp_f32_e32 v33, v33
	s_nop 0
	v_add_f32_e32 v33, 1.0, v33
	v_rcp_f32_e32 v38, v33
	v_mul_f32_e32 v33, 0xbfb8aa3b, v29
	v_exp_f32_e32 v33, v33
	s_nop 0
	v_add_f32_e32 v33, 1.0, v33
	v_rcp_f32_e32 v37, v33
	v_mul_f32_e32 v33, 0xbfb8aa3b, v25
	v_exp_f32_e32 v33, v33
	v_pk_mul_f32 v[28:29], v[28:29], v[36:37]
	v_add_f32_e32 v33, 1.0, v33
	v_rcp_f32_e32 v39, v33
	v_mul_f32_e32 v33, 0xbfb8aa3b, v30
	v_exp_f32_e32 v33, v33
	v_pk_mul_f32 v[24:25], v[24:25], v[38:39]
	v_add_f32_e32 v33, 1.0, v33
	v_rcp_f32_e32 v40, v33
	v_mul_f32_e32 v33, 0xbfb8aa3b, v26
	v_exp_f32_e32 v33, v33
	s_nop 0
	v_add_f32_e32 v33, 1.0, v33
	v_rcp_f32_e32 v42, v33
	v_mul_f32_e32 v33, 0xbfb8aa3b, v31
	v_exp_f32_e32 v33, v33
	s_nop 0
	v_add_f32_e32 v33, 1.0, v33
	v_rcp_f32_e32 v41, v33
	v_mul_f32_e32 v33, 0xbfb8aa3b, v27
	v_exp_f32_e32 v33, v33
	v_pk_mul_f32 v[30:31], v[30:31], v[40:41]
	v_add_f32_e32 v33, 1.0, v33
	v_rcp_f32_e32 v43, v33
	s_nop 0
	v_pk_mul_f32 v[26:27], v[26:27], v[42:43]
.LBB0_185:
	s_mov_b64 s[98:99], 0
	v_cvt_pk_bf16_f32 v28, v28, v29
	v_cvt_pk_bf16_f32 v29, v30, v31
	v_cvt_pk_bf16_f32 v30, v24, v25
	v_cvt_pk_bf16_f32 v31, v26, v27
	global_store_dwordx4 v[34:35], v[28:31], off offset:256 nt

; __device__ __forceinline__ unsigned cvt_pk_bf16(float lo, float hi) { unsigned r; asm volatile("v_cvt_pk_bf16_f32 %0, %1, %2" : "=v"(r) : "v"(lo), "v"(hi)); return r; }
; __device__ __forceinline__ float silu_f(float v) { return v * __builtin_amdgcn_rcpf(1.0f + __expf(-v)); }
;     __device__ __forceinline__ void operator()(const f32x4 (&acc)[2][2][4][2], const Unit& u, int wr, int wc, int fr, int fq) const {
;     ...
;                 const int r = row0 + ai * HALF + m * 16; const float rs = rsv[ai][m];
;                 if (pn == 8) {
;                     if (wc == 0) { const f32x4 v0 = acc[ai][0][m][0] * rs, v1 = acc[ai][0][m][1] * rs; u32x4 w; w.x = cvt_pk_bf16(v0[0], v0[1]); w.y = cvt_pk_bf16(v0[2], v0[3]); w.z = cvt_pk_bf16(v1[0], v1[1]); w.w = cvt_pk_bf16(v1[2], v1[3]); *(u32x4*)(DEC + (size_t)r * 32 + 8 * fq) = w; }
;                 } else {
;                     bf16_t* rowp = Z + (size_t)r * ZW + pn * BM + wc * 32 + 8 * fq;
; #pragma unroll
;                     for (int bj = 0; bj < 2; ++bj) { f32x4 v0 = acc[ai][bj][m][0] * rs, v1 = acc[ai][bj][m][1] * rs;
;                         if (pn >= 4 && pn < 6) {
; #pragma unroll
;                             for (int j = 0; j < 4; ++j) { v0[j] = silu_f(v0[j]); v1[j] = silu_f(v1[j]); } }
;                         u32x4 w; w.x = cvt_pk_bf16(v0[0], v0[1]); w.y = cvt_pk_bf16(v0[2], v0[3]); w.z = cvt_pk_bf16(v1[0], v1[1]); w.w = cvt_pk_bf16(v1[2], v1[3]);
;                         *(u32x4*)(rowp + bj * HALF) = w; }
.LBB0_191:
	v_mov_b64_e32 v[18:19], s[60:61]
	v_mad_i64_i32 v[18:19], s[14:15], v16, s1, v[18:19]
	v_lshl_add_u64 v[18:19], s[96:97], 1, v[18:19]
	s_lshl_b32 s76, s7, 1
	v_mov_b32_e32 v28, v129
	v_mov_b32_e32 v29, v129
	v_lshl_add_u64 v[18:19], v[18:19], 0, s[76:77]
	v_lshlrev_b32_e32 v152, 1, v170
	v_cvt_pk_bf16_f32 v22, v22, v23
	v_cvt_pk_bf16_f32 v23, v20, v21
	v_mov_b32_e32 v20, v129
	v_mov_b32_e32 v21, v129
	v_lshl_add_u64 v[18:19], v[18:19], 0, v[152:153]
	v_pk_mul_f32 v[14:15], v[14:15], v[20:21]
	v_pk_mul_f32 v[12:13], v[12:13], v[28:29]
	v_pk_mul_f32 v[10:11], v[10:11], v[20:21]
	s_and_b64 vcc, exec, s[42:43]
	v_pk_mul_f32 v[8:9], v[8:9], v[28:29]
	v_cvt_pk_bf16_f32 v24, v24, v25
	v_cvt_pk_bf16_f32 v25, v26, v27
	global_store_dwordx4 v[18:19], v[22:25], off nt
	s_cbranch_vccnz .LBB0_193
	v_mul_f32_e32 v17, 0xbfb8aa3b, v12
	v_exp_f32_e32 v17, v17
	s_nop 0
	v_add_f32_e32 v17, 1.0, v17
	v_rcp_f32_e32 v20, v17
	v_mul_f32_e32 v17, 0xbfb8aa3b, v8
	v_exp_f32_e32 v17, v17
	s_nop 0
	v_add_f32_e32 v17, 1.0, v17
	v_rcp_f32_e32 v22, v17
	v_mul_f32_e32 v17, 0xbfb8aa3b, v13
	v_exp_f32_e32 v17, v17
	s_nop 0
	v_add_f32_e32 v17, 1.0, v17
	v_rcp_f32_e32 v21, v17
	v_mul_f32_e32 v17, 0xbfb8aa3b, v9
	v_exp_f32_e32 v17, v17
	v_pk_mul_f32 v[12:13], v[12:13], v[20:21]
	v_add_f32_e32 v17, 1.0, v17
	v_rcp_f32_e32 v23, v17
	v_mul_f32_e32 v17, 0xbfb8aa3b, v14
	v_exp_f32_e32 v17, v17
	v_pk_mul_f32 v[8:9], v[8:9], v[22:23]
	v_add_f32_e32 v17, 1.0, v17
	v_rcp_f32_e32 v24, v17
	v_mul_f32_e32 v17, 0xbfb8aa3b, v10
	v_exp_f32_e32 v17, v17
	s_nop 0
	v_add_f32_e32 v17, 1.0, v17
	v_rcp_f32_e32 v26, v17
	v_mul_f32_e32 v17, 0xbfb8aa3b, v15
	v_exp_f32_e32 v17, v17
	s_nop 0
	v_add_f32_e32 v17, 1.0, v17
	v_rcp_f32_e32 v25, v17
	v_mul_f32_e32 v17, 0xbfb8aa3b, v11
	v_exp_f32_e32 v17, v17
	v_pk_mul_f32 v[14:15], v[14:15], v[24:25]
	v_add_f32_e32 v17, 1.0, v17
	v_rcp_f32_e32 v27, v17
	s_nop 0
	v_pk_mul_f32 v[10:11], v[10:11], v[26:27]
.LBB0_193:
	s_mov_b64 s[46:47], 0
	v_cvt_pk_bf16_f32 v12, v12, v13
	v_cvt_pk_bf16_f32 v13, v14, v15
	v_cvt_pk_bf16_f32 v14, v8, v9
	v_cvt_pk_bf16_f32 v15, v10, v11
	global_store_dwordx4 v[18:19], v[12:15], off offset:256 nt

; __device__ __forceinline__ unsigned cvt_pk_bf16(float lo, float hi) { unsigned r; asm volatile("v_cvt_pk_bf16_f32 %0, %1, %2" : "=v"(r) : "v"(lo), "v"(hi)); return r; }
;     __device__ __forceinline__ void operator()(const f32x4 (&acc)[2][2][4][2], const Unit& u, int wr, int wc, int fr, int fq) const {
;     ...
;                 const int r = row0 + ai * HALF + m * 16; const float rs = rsv[ai][m];
;                 if (pn == 8) {
;                     if (wc == 0) { const f32x4 v0 = acc[ai][0][m][0] * rs, v1 = acc[ai][0][m][1] * rs; u32x4 w; w.x = cvt_pk_bf16(v0[0], v0[1]); w.y = cvt_pk_bf16(v0[2], v0[3]); w.z = cvt_pk_bf16(v1[0], v1[1]); w.w = cvt_pk_bf16(v1[2], v1[3]); *(u32x4*)(DEC + (size_t)r * 32 + 8 * fq) = w; }
.LBB0_199:
	s_waitcnt lgkmcnt(0)
	v_pk_mul_f32 v[100:101], v[100:101], v[188:189] op_sel:[0,1]
	v_ashrrev_i32_e32 v187, 31, v186
	v_pk_mul_f32 v[104:105], v[98:99], v[188:189] op_sel:[0,1]
	v_pk_mul_f32 v[98:99], v[96:97], v[188:189] op_sel:[0,1]
	v_cvt_pk_bf16_f32 v96, v100, v101
	v_lshlrev_b64 v[100:101], 6, v[186:187]
	v_lshl_add_u64 v[100:101], v[172:173], 0, v[100:101]
	v_pk_mul_f32 v[102:103], v[102:103], v[188:189] op_sel:[0,1]
	s_nop 0
	v_cvt_pk_bf16_f32 v97, v102, v103
	v_cvt_pk_bf16_f32 v98, v98, v99
	v_cvt_pk_bf16_f32 v99, v104, v105
	global_store_dwordx4 v[100:101], v[96:99], off nt
	s_and_b64 vcc, exec, s[46:47]
	s_mov_b64 s[98:99], -1
	s_cbranch_vccz .LBB0_149
	s_branch .LBB0_154
.LBB0_200:
	s_waitcnt lgkmcnt(0)
	v_pk_mul_f32 v[84:85], v[84:85], v[144:145] op_sel_hi:[1,0]
	v_ashrrev_i32_e32 v185, 31, v184
	v_pk_mul_f32 v[88:89], v[82:83], v[144:145] op_sel_hi:[1,0]
	v_pk_mul_f32 v[82:83], v[80:81], v[144:145] op_sel_hi:[1,0]
	v_cvt_pk_bf16_f32 v80, v84, v85
	v_lshlrev_b64 v[84:85], 6, v[184:185]
	v_lshl_add_u64 v[84:85], v[172:173], 0, v[84:85]
	v_pk_mul_f32 v[86:87], v[86:87], v[144:145] op_sel_hi:[1,0]
	s_nop 0
	v_cvt_pk_bf16_f32 v81, v86, v87
	v_cvt_pk_bf16_f32 v82, v82, v83
	v_cvt_pk_bf16_f32 v83, v88, v89
	global_store_dwordx4 v[84:85], v[80:83], off nt
	s_and_b64 vcc, exec, s[46:47]
	s_mov_b64 s[98:99], -1
	s_cbranch_vccz .LBB0_157
	s_branch .LBB0_162
.LBB0_201:
	s_waitcnt lgkmcnt(0)
	v_pk_mul_f32 v[68:69], v[68:69], v[144:145] op_sel:[0,1]
	v_ashrrev_i32_e32 v183, 31, v182
	v_pk_mul_f32 v[72:73], v[66:67], v[144:145] op_sel:[0,1]
	v_pk_mul_f32 v[66:67], v[64:65], v[144:145] op_sel:[0,1]
	v_cvt_pk_bf16_f32 v64, v68, v69
	v_lshlrev_b64 v[68:69], 6, v[182:183]
	v_lshl_add_u64 v[68:69], v[172:173], 0, v[68:69]
	v_pk_mul_f32 v[70:71], v[70:71], v[144:145] op_sel:[0,1]
	s_nop 0
	v_cvt_pk_bf16_f32 v65, v70, v71
	v_cvt_pk_bf16_f32 v66, v66, v67
	v_cvt_pk_bf16_f32 v67, v72, v73
	global_store_dwordx4 v[68:69], v[64:67], off nt
	s_nop 1
	v_add_u32_e32 v64, 0x80, v180
	s_and_b64 vcc, exec, s[46:47]
	s_mov_b64 s[98:99], -1
	s_cbranch_vccz .LBB0_165
	s_branch .LBB0_170
.LBB0_202:
	s_waitcnt lgkmcnt(0)
	v_pk_mul_f32 v[52:53], v[52:53], v[136:137] op_sel_hi:[1,0]
	v_ashrrev_i32_e32 v65, 31, v64
	v_pk_mul_f32 v[56:57], v[50:51], v[136:137] op_sel_hi:[1,0]
	v_pk_mul_f32 v[50:51], v[48:49], v[136:137] op_sel_hi:[1,0]
	v_cvt_pk_bf16_f32 v48, v52, v53
	v_lshlrev_b64 v[52:53], 6, v[64:65]
	v_lshl_add_u64 v[52:53], v[172:173], 0, v[52:53]
	v_pk_mul_f32 v[54:55], v[54:55], v[136:137] op_sel_hi:[1,0]
	s_nop 0
	v_cvt_pk_bf16_f32 v49, v54, v55
	v_cvt_pk_bf16_f32 v50, v50, v51
	v_cvt_pk_bf16_f32 v51, v56, v57
	global_store_dwordx4 v[52:53], v[48:51], off nt
	s_nop 1
	v_add_u32_e32 v48, 0x90, v180
	s_and_b64 vcc, exec, s[46:47]
	s_mov_b64 s[98:99], -1
	s_cbranch_vccz .LBB0_173
	s_branch .LBB0_178
.LBB0_203:
	s_waitcnt lgkmcnt(0)
	v_pk_mul_f32 v[36:37], v[36:37], v[136:137] op_sel:[0,1]
	v_ashrrev_i32_e32 v49, 31, v48
	v_pk_mul_f32 v[40:41], v[34:35], v[136:137] op_sel:[0,1]
	v_pk_mul_f32 v[34:35], v[32:33], v[136:137] op_sel:[0,1]
	v_cvt_pk_bf16_f32 v32, v36, v37
	v_lshlrev_b64 v[36:37], 6, v[48:49]
	v_lshl_add_u64 v[36:37], v[172:173], 0, v[36:37]
	v_pk_mul_f32 v[38:39], v[38:39], v[136:137] op_sel:[0,1]
	s_nop 0
	v_cvt_pk_bf16_f32 v33, v38, v39
	v_cvt_pk_bf16_f32 v34, v34, v35
	v_cvt_pk_bf16_f32 v35, v40, v41
	global_store_dwordx4 v[36:37], v[32:35], off nt
	s_nop 1
	v_add_u32_e32 v32, 0xa0, v180
	s_and_b64 vcc, exec, s[46:47]
	s_mov_b64 s[98:99], -1
	s_cbranch_vccz .LBB0_181
	s_branch .LBB0_186
.LBB0_204:
	s_waitcnt lgkmcnt(0)
	v_pk_mul_f32 v[20:21], v[20:21], v[128:129] op_sel_hi:[1,0]
	v_ashrrev_i32_e32 v33, 31, v32
	v_pk_mul_f32 v[24:25], v[18:19], v[128:129] op_sel_hi:[1,0]
	v_pk_mul_f32 v[18:19], v[16:17], v[128:129] op_sel_hi:[1,0]
	v_cvt_pk_bf16_f32 v16, v20, v21
	v_lshlrev_b64 v[20:21], 6, v[32:33]
	v_lshl_add_u64 v[20:21], v[172:173], 0, v[20:21]
	v_pk_mul_f32 v[22:23], v[22:23], v[128:129] op_sel_hi:[1,0]
	s_nop 0
	v_cvt_pk_bf16_f32 v17, v22, v23
	v_cvt_pk_bf16_f32 v18, v18, v19
	v_cvt_pk_bf16_f32 v19, v24, v25
	global_store_dwordx4 v[20:21], v[16:19], off nt
	s_nop 1
	v_add_u32_e32 v16, 0xb0, v180
	s_and_b64 vcc, exec, s[46:47]
	s_mov_b64 s[46:47], -1
	s_cbranch_vccz .LBB0_189
	s_branch .LBB0_194
.LBB0_205:
	s_waitcnt lgkmcnt(0)
	v_pk_mul_f32 v[4:5], v[4:5], v[128:129] op_sel:[0,1]
	v_ashrrev_i32_e32 v17, 31, v16
	v_pk_mul_f32 v[8:9], v[2:3], v[128:129] op_sel:[0,1]
	v_pk_mul_f32 v[2:3], v[0:1], v[128:129] op_sel:[0,1]
	v_cvt_pk_bf16_f32 v0, v4, v5
	v_lshlrev_b64 v[4:5], 6, v[16:17]
	v_lshl_add_u64 v[4:5], v[172:173], 0, v[4:5]
	v_pk_mul_f32 v[6:7], v[6:7], v[128:129] op_sel:[0,1]
	s_nop 0
	v_cvt_pk_bf16_f32 v1, v6, v7
	v_cvt_pk_bf16_f32 v2, v2, v3
	v_cvt_pk_bf16_f32 v3, v8, v9
	global_store_dwordx4 v[4:5], v[0:3], off nt
	s_andn2_b64 vcc, exec, s[54:55]
	s_mov_b64 s[42:43], -1
	s_cbranch_vccnz .LBB0_113
	s_branch .LBB0_197

; __device__ __forceinline__ float bflo(unsigned w) { return __uint_as_float(w << 16); }
; template <bool RD32>
; __device__ __forceinline__ void res_rows(const float* __restrict__ xold32, const bf16_t* __restrict__ xoldb, bf16_t* __restrict__ xb, float* __restrict__ ssq, const f32x4 (&acc)[2][2][4][2], int row0, int col0, int slot) {
;     f32x4 xo[2][2][2];
;     float ssv[8];
;     auto ld = [&](size_t o, f32x4& a, f32x4& b) { if (RD32) { a = *(const f32x4*)(xold32 + o); b = *(const f32x4*)(xold32 + o + 4); }
;         else { const u32x4 w = *(const u32x4*)(xoldb + o); a = (f32x4){bflo(w.x), bfhi(w.x), bflo(w.y), bfhi(w.y)}; b = (f32x4){bflo(w.z), bfhi(w.z), bflo(w.w), bfhi(w.w)}; } };
; #pragma unroll
;     for (int bj = 0; bj < 2; ++bj) ld((size_t)row0 * D + col0 + bj * HALF, xo[0][bj][0], xo[0][bj][1]);
; #pragma unroll
;     for (int idx = 0; idx < 8; ++idx) {
;         const int ai = idx >> 2, m = idx & 3; const int r = row0 + ai * HALF + m * 16; const size_t off = (size_t)r * D + col0;
;         if (idx < 7) { const int ai2 = (idx + 1) >> 2, m2 = (idx + 1) & 3; const size_t off2 = (size_t)(row0 + ai2 * HALF + m2 * 16) * D + col0;
; #pragma unroll
;             for (int bj = 0; bj < 2; ++bj) ld(off2 + bj * HALF, xo[(idx + 1) & 1][bj][0], xo[(idx + 1) & 1][bj][1]); }
;         float ss = 0.f;
; #pragma unroll
;         for (int bj = 0; bj < 2; ++bj) { const f32x4 x0 = xo[idx & 1][bj][0] + acc[ai][bj][m][0], x1 = xo[idx & 1][bj][1] + acc[ai][bj][m][1];
;             u32x4 w; w.x = cvt_pk_bf16(x0[0], x0[1]); w.y = cvt_pk_bf16(x0[2], x0[3]); w.z = cvt_pk_bf16(x1[0], x1[1]); w.w = cvt_pk_bf16(x1[2], x1[3]);
;             *(u32x4*)(xb + off + bj * HALF) = w;
;             ss += ((x0[0] * x0[0] + x0[1] * x0[1]) + (x0[2] * x0[2] + x0[3] * x0[3])) + ((x1[0] * x1[0] + x1[1] * x1[1]) + (x1[2] * x1[2] + x1[3] * x1[3])); }
;         ss += __shfl_xor(ss, 16); ss += __shfl_xor(ss, 32);
;         ssv[idx] = ss;
;     }
;     const int fq = slot >> 6;
; #pragma unroll
;     for (int j = 0; j < 2; ++j) { const float v = fq == 0 ? ssv[j] : fq == 1 ? ssv[2 + j] : fq == 2 ? ssv[4 + j] : ssv[6 + j]; const int idx = 2 * fq + j;
;         ssq[(size_t)(row0 + (idx >> 2) * HALF + (idx & 3) * 16) * 16 + (slot & 15)] = v; }
; }
;     __device__ __forceinline__ void operator()(const f32x4 (&acc)[2][2][4][2], const Unit& u, int wr, int wc, int fr, int fq) const {
.LBB0_421:
	v_lshl_add_u32 v166, s5, 8, v217
	v_lshl_or_b32 v132, s4, 8, v219
	v_lshl_or_b32 v222, s4, 2, v220
	v_ashrrev_i32_e32 v167, 31, v166
	v_or_b32_e32 v223, s95, v222
	v_ashrrev_i32_e32 v133, 31, v132
	s_andn2_b64 vcc, exec, s[48:49]
	v_lshlrev_b64 v[174:175], 11, v[166:167]
	v_or_b32_e32 v172, 16, v166
	v_or_b32_e32 v170, 32, v166
	v_or_b32_e32 v168, 48, v166
	s_cbranch_vccnz .LBB0_436
	v_lshl_add_u64 v[128:129], s[58:59], 0, v[174:175]
	v_lshlrev_b64 v[134:135], 1, v[132:133]
	v_lshl_add_u64 v[136:137], v[128:129], 0, v[134:135]
	global_load_dwordx4 v[128:131], v[136:137], off
	v_ashrrev_i32_e32 v173, 31, v172
	v_ashrrev_i32_e32 v171, 31, v170
	s_mov_b64 s[4:5], 0x40000
	s_waitcnt vmcnt(0)
	v_lshlrev_b32_e32 v138, 16, v128
	v_and_b32_e32 v139, 0xffff0000, v128
	v_lshlrev_b32_e32 v140, 16, v129
	v_and_b32_e32 v141, 0xffff0000, v129
	v_lshlrev_b32_e32 v142, 16, v130
	v_and_b32_e32 v143, 0xffff0000, v130
	v_lshlrev_b32_e32 v176, 16, v131
	v_and_b32_e32 v177, 0xffff0000, v131
	global_load_dwordx4 v[128:131], v[136:137], off offset:256
	v_pk_add_f32 v[140:141], v[126:127], v[140:141]
	v_pk_add_f32 v[138:139], v[124:125], v[138:139]
	v_pk_add_f32 v[176:177], v[122:123], v[176:177]
	v_pk_add_f32 v[142:143], v[120:121], v[142:143]
	s_waitcnt vmcnt(0)
	v_lshlrev_b32_e32 v178, 16, v128
	v_and_b32_e32 v179, 0xffff0000, v128
	v_lshlrev_b32_e32 v180, 16, v129
	v_and_b32_e32 v181, 0xffff0000, v129
	v_lshlrev_b32_e32 v182, 16, v130
	v_and_b32_e32 v183, 0xffff0000, v130
	v_lshlrev_b32_e32 v202, 16, v131
	v_and_b32_e32 v203, 0xffff0000, v131
	v_lshl_add_u64 v[130:131], s[58:59], 0, v[134:135]
	v_lshlrev_b64 v[128:129], 11, v[172:173]
	v_lshl_add_u64 v[184:185], v[130:131], 0, v[128:129]
	global_load_dwordx4 v[134:137], v[184:185], off
	v_lshl_add_u64 v[128:129], v[130:131], 0, v[174:175]
	s_waitcnt vmcnt(0)
	v_lshlrev_b32_e32 v186, 16, v134
	v_and_b32_e32 v187, 0xffff0000, v134
	v_lshlrev_b32_e32 v190, 16, v135
	v_and_b32_e32 v191, 0xffff0000, v135
	v_lshlrev_b32_e32 v188, 16, v136
	v_and_b32_e32 v189, 0xffff0000, v136
	v_lshlrev_b32_e32 v192, 16, v137
	v_and_b32_e32 v193, 0xffff0000, v137
	global_load_dwordx4 v[134:137], v[184:185], off offset:256
	v_pk_add_f32 v[190:191], v[110:111], v[190:191]
	v_pk_add_f32 v[192:193], v[106:107], v[192:193]
	s_waitcnt vmcnt(0)
	v_lshlrev_b32_e32 v194, 16, v134
	v_and_b32_e32 v195, 0xffff0000, v134
	v_lshlrev_b32_e32 v198, 16, v135
	v_and_b32_e32 v199, 0xffff0000, v135
	v_cvt_pk_bf16_f32 v134, v138, v139
	v_cvt_pk_bf16_f32 v135, v140, v141
	v_lshlrev_b32_e32 v196, 16, v136
	v_and_b32_e32 v197, 0xffff0000, v136
	v_lshlrev_b32_e32 v200, 16, v137
	v_and_b32_e32 v201, 0xffff0000, v137
	v_cvt_pk_bf16_f32 v136, v142, v143
	v_cvt_pk_bf16_f32 v137, v176, v177
	global_store_dwordx4 v[128:129], v[134:137], off nt
	v_pk_add_f32 v[196:197], v[96:97], v[196:197]
	s_nop 0
	v_mul_f32_e32 v134, v139, v139
	v_mul_f32_e32 v135, v141, v141
	v_fmac_f32_e32 v134, v138, v138
	v_fmac_f32_e32 v135, v140, v140
	v_add_f32_e32 v134, v134, v135
	v_mul_f32_e32 v135, v143, v143
	v_mul_f32_e32 v136, v177, v177
	v_fmac_f32_e32 v135, v142, v142
	v_fmac_f32_e32 v136, v176, v176
	v_add_f32_e32 v135, v135, v136
	v_add_f32_e32 v152, v134, v135
	v_pk_add_f32 v[138:139], v[118:119], v[180:181]
	v_pk_add_f32 v[140:141], v[116:117], v[178:179]
	v_pk_add_f32 v[142:143], v[114:115], v[202:203]
	v_cvt_pk_bf16_f32 v134, v140, v141
	v_cvt_pk_bf16_f32 v135, v138, v139
	v_pk_add_f32 v[176:177], v[112:113], v[182:183]
	s_nop 0
	v_cvt_pk_bf16_f32 v136, v176, v177
	v_cvt_pk_bf16_f32 v137, v142, v143
	global_store_dwordx4 v[128:129], v[134:137], off offset:256 nt
	s_nop 1
	v_mul_f32_e32 v134, v141, v141
	v_mul_f32_e32 v135, v139, v139
	v_fmac_f32_e32 v134, v140, v140
	v_fmac_f32_e32 v135, v138, v138
	v_add_f32_e32 v134, v134, v135
	v_mul_f32_e32 v135, v177, v177
	v_mul_f32_e32 v136, v143, v143
	v_fmac_f32_e32 v135, v176, v176
	v_fmac_f32_e32 v136, v142, v142
	v_add_f32_e32 v135, v135, v136
	v_and_b32_e32 v136, 64, v209
	v_add_f32_e32 v134, v134, v135
	v_xor_b32_e32 v135, 16, v209
	v_add_u32_e32 v136, 64, v136
	v_cmp_lt_i32_e32 vcc, v135, v136
	v_add_f32_e32 v134, v152, v134
	s_nop 0
	v_cndmask_b32_e32 v135, v209, v135, vcc
	v_lshlrev_b32_e32 v152, 2, v135
	ds_bpermute_b32 v135, v152, v134
	s_waitcnt lgkmcnt(0)
	v_add_f32_e32 v173, v134, v135
	v_xor_b32_e32 v134, 32, v209
	v_cmp_lt_i32_e32 vcc, v134, v136
	s_nop 1
	v_cndmask_b32_e32 v134, v209, v134, vcc
	v_lshlrev_b32_e32 v225, 2, v134
	v_lshlrev_b64 v[134:135], 11, v[170:171]
	v_lshl_add_u64 v[134:135], v[130:131], 0, v[134:135]
	global_load_dwordx4 v[136:139], v[134:135], off
	global_load_dwordx4 v[202:205], v[134:135], off offset:256
	v_mul_f32_e32 v171, v191, v191
	v_fmac_f32_e32 v171, v190, v190
	ds_bpermute_b32 v224, v225, v173
	s_waitcnt vmcnt(1)
	v_lshlrev_b32_e32 v176, 16, v138
	v_and_b32_e32 v177, 0xffff0000, v138
	v_lshlrev_b32_e32 v180, 16, v139
	v_and_b32_e32 v181, 0xffff0000, v139
	s_waitcnt vmcnt(0)
; __device__ __forceinline__ unsigned cvt_pk_bf16(float lo, float hi) { unsigned r; asm volatile("v_cvt_pk_bf16_f32 %0, %1, %2" : "=v"(r) : "v"(lo), "v"(hi)); return r; }
; __device__ __forceinline__ float bflo(unsigned w) { return __uint_as_float(w << 16); }
; __device__ __forceinline__ float bfhi(unsigned w) { return __uint_as_float(w & 0xffff0000u); }
; template <bool RD32>
; __device__ __forceinline__ void res_rows(const float* __restrict__ xold32, const bf16_t* __restrict__ xoldb, bf16_t* __restrict__ xb, float* __restrict__ ssq, const f32x4 (&acc)[2][2][4][2], int row0, int col0, int slot) {
;     ...
;     auto ld = [&](size_t o, f32x4& a, f32x4& b) { if (RD32) { a = *(const f32x4*)(xold32 + o); b = *(const f32x4*)(xold32 + o + 4); }
;         else { const u32x4 w = *(const u32x4*)(xoldb + o); a = (f32x4){bflo(w.x), bfhi(w.x), bflo(w.y), bfhi(w.y)}; b = (f32x4){bflo(w.z), bfhi(w.z), bflo(w.w), bfhi(w.w)}; } };
; #pragma unroll
;     for (int bj = 0; bj < 2; ++bj) ld((size_t)row0 * D + col0 + bj * HALF, xo[0][bj][0], xo[0][bj][1]);
; #pragma unroll
;     for (int idx = 0; idx < 8; ++idx) {
;         const int ai = idx >> 2, m = idx & 3; const int r = row0 + ai * HALF + m * 16; const size_t off = (size_t)r * D + col0;
;         if (idx < 7) { const int ai2 = (idx + 1) >> 2, m2 = (idx + 1) & 3; const size_t off2 = (size_t)(row0 + ai2 * HALF + m2 * 16) * D + col0;
; #pragma unroll
;             for (int bj = 0; bj < 2; ++bj) ld(off2 + bj * HALF, xo[(idx + 1) & 1][bj][0], xo[(idx + 1) & 1][bj][1]); }
;         float ss = 0.f;
; #pragma unroll
;         for (int bj = 0; bj < 2; ++bj) { const f32x4 x0 = xo[idx & 1][bj][0] + acc[ai][bj][m][0], x1 = xo[idx & 1][bj][1] + acc[ai][bj][m][1];
;             u32x4 w; w.x = cvt_pk_bf16(x0[0], x0[1]); w.y = cvt_pk_bf16(x0[2], x0[3]); w.z = cvt_pk_bf16(x1[0], x1[1]); w.w = cvt_pk_bf16(x1[2], x1[3]);
;             *(u32x4*)(xb + off + bj * HALF) = w;
;             ss += ((x0[0] * x0[0] + x0[1] * x0[1]) + (x0[2] * x0[2] + x0[3] * x0[3])) + ((x1[0] * x1[0] + x1[1] * x1[1]) + (x1[2] * x1[2] + x1[3] * x1[3])); }
;         ss += __shfl_xor(ss, 16); ss += __shfl_xor(ss, 32);
;         ssv[idx] = ss;
	v_lshlrev_b32_e32 v138, 16, v202
	v_and_b32_e32 v139, 0xffff0000, v202
	v_lshlrev_b32_e32 v142, 16, v203
	v_and_b32_e32 v143, 0xffff0000, v203
	v_pk_add_f32 v[202:203], v[108:109], v[186:187]
	v_lshlrev_b32_e32 v178, 16, v136
	v_mul_f32_e32 v169, v203, v203
	v_and_b32_e32 v179, 0xffff0000, v136
	v_lshlrev_b32_e32 v182, 16, v137
	v_and_b32_e32 v183, 0xffff0000, v137
	v_lshlrev_b32_e32 v136, 16, v204
	v_and_b32_e32 v137, 0xffff0000, v204
	v_lshlrev_b32_e32 v140, 16, v205
	v_and_b32_e32 v141, 0xffff0000, v205
	v_pk_add_f32 v[204:205], v[104:105], v[188:189]
	v_cvt_pk_bf16_f32 v186, v202, v203
	v_fmac_f32_e32 v169, v202, v202
	v_cvt_pk_bf16_f32 v187, v190, v191
	v_cvt_pk_bf16_f32 v188, v204, v205
	v_cvt_pk_bf16_f32 v189, v192, v193
	global_store_dwordx4 v[184:185], v[186:189], off nt
	v_add_f32_e32 v169, v169, v171
	v_mul_f32_e32 v171, v205, v205
	v_mul_f32_e32 v186, v193, v193
	v_fmac_f32_e32 v171, v204, v204
	v_fmac_f32_e32 v186, v192, v192
	v_add_f32_e32 v171, v171, v186
	v_pk_add_f32 v[190:191], v[102:103], v[198:199]
	v_pk_add_f32 v[192:193], v[100:101], v[194:195]
	v_add_f32_e32 v169, v169, v171
	v_pk_add_f32 v[194:195], v[98:99], v[200:201]
	v_cvt_pk_bf16_f32 v186, v192, v193
	v_cvt_pk_bf16_f32 v187, v190, v191
	v_cvt_pk_bf16_f32 v188, v196, v197
	v_mul_f32_e32 v171, v193, v193
	v_cvt_pk_bf16_f32 v189, v194, v195
	global_store_dwordx4 v[184:185], v[186:189], off offset:256 nt
	v_mul_f32_e32 v184, v191, v191
	v_fmac_f32_e32 v171, v192, v192
	v_fmac_f32_e32 v184, v190, v190
	v_add_f32_e32 v171, v171, v184
	v_mul_f32_e32 v184, v197, v197
	v_mul_f32_e32 v185, v195, v195
	v_fmac_f32_e32 v184, v196, v196
	v_fmac_f32_e32 v185, v194, v194
	v_add_f32_e32 v184, v184, v185
	v_add_f32_e32 v171, v171, v184
	v_add_f32_e32 v169, v169, v171
	ds_bpermute_b32 v171, v152, v169
	v_pk_add_f32 v[182:183], v[94:95], v[182:183]
	v_pk_add_f32 v[194:195], v[92:93], v[178:179]
	v_pk_add_f32 v[180:181], v[90:91], v[180:181]
	v_pk_add_f32 v[142:143], v[86:87], v[142:143]
	s_waitcnt lgkmcnt(0)
	v_add_f32_e32 v171, v169, v171
	v_ashrrev_i32_e32 v169, 31, v168
	v_lshlrev_b64 v[184:185], 11, v[168:169]
	v_lshl_add_u64 v[130:131], v[130:131], 0, v[184:185]
	global_load_dwordx4 v[184:187], v[130:131], off
	global_load_dwordx4 v[202:205], v[130:131], off offset:256
	v_mul_f32_e32 v169, v195, v195
	v_fmac_f32_e32 v169, v194, v194
	v_pk_add_f32 v[140:141], v[82:83], v[140:141]
	ds_bpermute_b32 v226, v225, v171
	s_waitcnt vmcnt(1)
	v_lshlrev_b32_e32 v192, 16, v186
	v_and_b32_e32 v193, 0xffff0000, v186
	v_lshlrev_b32_e32 v198, 16, v187
	v_and_b32_e32 v199, 0xffff0000, v187
	s_waitcnt vmcnt(0)
	v_lshlrev_b32_e32 v186, 16, v202
	v_and_b32_e32 v187, 0xffff0000, v202
	v_lshlrev_b32_e32 v190, 16, v203
	v_and_b32_e32 v191, 0xffff0000, v203
	v_pk_add_f32 v[202:203], v[88:89], v[176:177]
	v_cvt_pk_bf16_f32 v176, v194, v195
	v_cvt_pk_bf16_f32 v177, v182, v183
	v_lshlrev_b32_e32 v196, 16, v184
	v_cvt_pk_bf16_f32 v178, v202, v203
	v_cvt_pk_bf16_f32 v179, v180, v181
	global_store_dwordx4 v[134:135], v[176:179], off nt
	v_and_b32_e32 v197, 0xffff0000, v184
	v_lshlrev_b32_e32 v200, 16, v185
	v_mul_f32_e32 v176, v183, v183
	v_fmac_f32_e32 v176, v182, v182
	v_add_f32_e32 v169, v169, v176
	v_mul_f32_e32 v176, v203, v203
	v_mul_f32_e32 v177, v181, v181
	v_fmac_f32_e32 v176, v202, v202
	v_fmac_f32_e32 v177, v180, v180
	v_add_f32_e32 v176, v176, v177
	v_add_f32_e32 v169, v169, v176
	v_pk_add_f32 v[176:177], v[84:85], v[138:139]
	v_pk_add_f32 v[178:179], v[80:81], v[136:137]
	v_cvt_pk_bf16_f32 v136, v176, v177
	v_cvt_pk_bf16_f32 v137, v142, v143
	v_and_b32_e32 v201, 0xffff0000, v185
	v_cvt_pk_bf16_f32 v138, v178, v179
	v_cvt_pk_bf16_f32 v139, v140, v141
	global_store_dwordx4 v[134:135], v[136:139], off offset:256 nt
	v_mul_f32_e32 v134, v177, v177
	v_mul_f32_e32 v135, v143, v143
	v_fmac_f32_e32 v134, v176, v176
	v_fmac_f32_e32 v135, v142, v142
	v_add_f32_e32 v134, v134, v135
	v_mul_f32_e32 v135, v179, v179
	v_mul_f32_e32 v136, v141, v141
	v_fmac_f32_e32 v135, v178, v178
	v_fmac_f32_e32 v136, v140, v140
	v_add_f32_e32 v135, v135, v136
	v_add_f32_e32 v134, v134, v135
	v_add_f32_e32 v134, v169, v134
	ds_bpermute_b32 v135, v152, v134
	v_lshlrev_b32_e32 v184, 16, v204
	v_and_b32_e32 v185, 0xffff0000, v204
	v_lshlrev_b32_e32 v188, 16, v205
	v_and_b32_e32 v189, 0xffff0000, v205
	s_waitcnt lgkmcnt(0)
	v_add_f32_e32 v169, v134, v135
	v_lshl_add_u64 v[134:135], v[128:129], 0, s[4:5]
	s_mov_b32 s4, 0x40000
	v_add_co_u32_e32 v136, vcc, s4, v128
	global_load_dwordx4 v[202:205], v[134:135], off offset:256
	s_nop 0
	v_addc_co_u32_e32 v137, vcc, 0, v129, vcc
	global_load_dwordx4 v[138:141], v[136:137], off
	v_pk_add_f32 v[192:193], v[72:73], v[192:193]
	v_pk_add_f32 v[200:201], v[78:79], v[200:201]
	v_pk_add_f32 v[190:191], v[70:71], v[190:191]
	v_pk_add_f32 v[188:189], v[66:67], v[188:189]
	s_mov_b64 s[4:5], 0x48000
	ds_bpermute_b32 v227, v225, v169
	s_waitcnt vmcnt(1)
	v_lshlrev_b32_e32 v176, 16, v203
	v_and_b32_e32 v177, 0xffff0000, v203
	v_lshlrev_b32_e32 v142, 16, v205
	s_waitcnt vmcnt(0)
; __device__ __forceinline__ unsigned cvt_pk_bf16(float lo, float hi) { unsigned r; asm volatile("v_cvt_pk_bf16_f32 %0, %1, %2" : "=v"(r) : "v"(lo), "v"(hi)); return r; }
; __device__ __forceinline__ float bflo(unsigned w) { return __uint_as_float(w << 16); }
; __device__ __forceinline__ float bfhi(unsigned w) { return __uint_as_float(w & 0xffff0000u); }
; template <bool RD32>
; __device__ __forceinline__ void res_rows(const float* __restrict__ xold32, const bf16_t* __restrict__ xoldb, bf16_t* __restrict__ xb, float* __restrict__ ssq, const f32x4 (&acc)[2][2][4][2], int row0, int col0, int slot) {
;     ...
;     auto ld = [&](size_t o, f32x4& a, f32x4& b) { if (RD32) { a = *(const f32x4*)(xold32 + o); b = *(const f32x4*)(xold32 + o + 4); }
;         else { const u32x4 w = *(const u32x4*)(xoldb + o); a = (f32x4){bflo(w.x), bfhi(w.x), bflo(w.y), bfhi(w.y)}; b = (f32x4){bflo(w.z), bfhi(w.z), bflo(w.w), bfhi(w.w)}; } };
; #pragma unroll
;     for (int bj = 0; bj < 2; ++bj) ld((size_t)row0 * D + col0 + bj * HALF, xo[0][bj][0], xo[0][bj][1]);
; #pragma unroll
;     for (int idx = 0; idx < 8; ++idx) {
;         const int ai = idx >> 2, m = idx & 3; const int r = row0 + ai * HALF + m * 16; const size_t off = (size_t)r * D + col0;
;         if (idx < 7) { const int ai2 = (idx + 1) >> 2, m2 = (idx + 1) & 3; const size_t off2 = (size_t)(row0 + ai2 * HALF + m2 * 16) * D + col0;
; #pragma unroll
;             for (int bj = 0; bj < 2; ++bj) ld(off2 + bj * HALF, xo[(idx + 1) & 1][bj][0], xo[(idx + 1) & 1][bj][1]); }
;         float ss = 0.f;
; #pragma unroll
;         for (int bj = 0; bj < 2; ++bj) { const f32x4 x0 = xo[idx & 1][bj][0] + acc[ai][bj][m][0], x1 = xo[idx & 1][bj][1] + acc[ai][bj][m][1];
;             u32x4 w; w.x = cvt_pk_bf16(x0[0], x0[1]); w.y = cvt_pk_bf16(x0[2], x0[3]); w.z = cvt_pk_bf16(x1[0], x1[1]); w.w = cvt_pk_bf16(x1[2], x1[3]);
;             *(u32x4*)(xb + off + bj * HALF) = w;
;             ss += ((x0[0] * x0[0] + x0[1] * x0[1]) + (x0[2] * x0[2] + x0[3] * x0[3])) + ((x1[0] * x1[0] + x1[1] * x1[1]) + (x1[2] * x1[2] + x1[3] * x1[3])); }
;         ss += __shfl_xor(ss, 16); ss += __shfl_xor(ss, 32);
;         ssv[idx] = ss;
	v_lshlrev_b32_e32 v180, 16, v138
	v_and_b32_e32 v181, 0xffff0000, v138
	v_lshlrev_b32_e32 v194, 16, v139
	v_and_b32_e32 v195, 0xffff0000, v139
	v_lshlrev_b32_e32 v178, 16, v140
	v_and_b32_e32 v179, 0xffff0000, v140
	v_lshlrev_b32_e32 v182, 16, v141
	v_and_b32_e32 v183, 0xffff0000, v141
	v_lshlrev_b32_e32 v140, 16, v202
	v_and_b32_e32 v141, 0xffff0000, v202
	v_lshlrev_b32_e32 v138, 16, v204
	v_and_b32_e32 v139, 0xffff0000, v204
	v_and_b32_e32 v143, 0xffff0000, v205
	v_pk_add_f32 v[202:203], v[76:77], v[196:197]
	v_pk_add_f32 v[204:205], v[74:75], v[198:199]
	v_cvt_pk_bf16_f32 v196, v202, v203
	v_cvt_pk_bf16_f32 v197, v200, v201
	v_cvt_pk_bf16_f32 v198, v192, v193
	v_mul_f32_e32 v193, v193, v193
	v_cvt_pk_bf16_f32 v199, v204, v205
	global_store_dwordx4 v[130:131], v[196:199], off nt
	v_fmac_f32_e32 v193, v192, v192
	v_mul_f32_e32 v192, v205, v205
	v_mul_f32_e32 v196, v203, v203
	v_mul_f32_e32 v197, v201, v201
	v_fmac_f32_e32 v196, v202, v202
	v_fmac_f32_e32 v197, v200, v200
	v_fmac_f32_e32 v192, v204, v204
	v_add_f32_e32 v196, v196, v197
	v_add_f32_e32 v192, v193, v192
	v_add_f32_e32 v198, v196, v192
	v_pk_add_f32 v[192:193], v[68:69], v[186:187]
	v_pk_add_f32 v[196:197], v[64:65], v[184:185]
	v_cvt_pk_bf16_f32 v184, v192, v193
	v_cvt_pk_bf16_f32 v185, v190, v191
	v_pk_add_f32 v[182:183], v[58:59], v[182:183]
	v_cvt_pk_bf16_f32 v186, v196, v197
	v_cvt_pk_bf16_f32 v187, v188, v189
	global_store_dwordx4 v[130:131], v[184:187], off offset:256 nt
	v_mul_f32_e32 v130, v193, v193
	v_mul_f32_e32 v131, v191, v191
	v_fmac_f32_e32 v130, v192, v192
	v_fmac_f32_e32 v131, v190, v190
	v_add_f32_e32 v130, v130, v131
	v_mul_f32_e32 v131, v197, v197
	v_mul_f32_e32 v184, v189, v189
	v_fmac_f32_e32 v131, v196, v196
	v_fmac_f32_e32 v184, v188, v188
	v_add_f32_e32 v131, v131, v184
	v_add_f32_e32 v130, v130, v131
	v_add_f32_e32 v130, v198, v130
	ds_bpermute_b32 v131, v152, v130
	v_pk_add_f32 v[184:185], v[62:63], v[194:195]
	v_pk_add_f32 v[194:195], v[60:61], v[180:181]
	v_pk_add_f32 v[176:177], v[54:55], v[176:177]
	v_pk_add_f32 v[140:141], v[52:53], v[140:141]
	s_waitcnt lgkmcnt(0)
	v_add_f32_e32 v228, v130, v131
	v_lshl_add_u64 v[130:131], v[128:129], 0, s[4:5]
	s_mov_b32 s4, 0x48000
	v_add_co_u32_e32 v186, vcc, s4, v128
	global_load_dwordx4 v[230:233], v[130:131], off offset:256
	s_nop 0
	v_addc_co_u32_e32 v187, vcc, 0, v129, vcc
	global_load_dwordx4 v[188:191], v[186:187], off
	v_pk_add_f32 v[142:143], v[50:51], v[142:143]
	s_mov_b64 s[4:5], 0x50000
	ds_bpermute_b32 v229, v225, v228
	s_waitcnt vmcnt(1)
	v_lshlrev_b32_e32 v196, 16, v231
	v_and_b32_e32 v197, 0xffff0000, v231
	v_lshlrev_b32_e32 v192, 16, v233
	s_waitcnt vmcnt(0)
	v_lshlrev_b32_e32 v198, 16, v190
	v_and_b32_e32 v199, 0xffff0000, v190
	v_lshlrev_b32_e32 v202, 16, v191
	v_and_b32_e32 v203, 0xffff0000, v191
	v_lshlrev_b32_e32 v190, 16, v230
	v_and_b32_e32 v191, 0xffff0000, v230
	v_pk_add_f32 v[230:231], v[56:57], v[178:179]
	v_cvt_pk_bf16_f32 v178, v194, v195
	v_cvt_pk_bf16_f32 v179, v184, v185
	v_lshlrev_b32_e32 v200, 16, v188
	v_cvt_pk_bf16_f32 v180, v230, v231
	v_cvt_pk_bf16_f32 v181, v182, v183
	global_store_dwordx4 v[136:137], v[178:181], off nt
	v_mul_f32_e32 v136, v195, v195
	v_mul_f32_e32 v137, v185, v185
	v_fmac_f32_e32 v136, v194, v194
	v_fmac_f32_e32 v137, v184, v184
	v_add_f32_e32 v136, v136, v137
	v_mul_f32_e32 v137, v231, v231
	v_mul_f32_e32 v178, v183, v183
	v_fmac_f32_e32 v137, v230, v230
	v_fmac_f32_e32 v178, v182, v182
	v_add_f32_e32 v137, v137, v178
	v_add_f32_e32 v180, v136, v137
	v_pk_add_f32 v[178:179], v[48:49], v[138:139]
	v_cvt_pk_bf16_f32 v136, v140, v141
	v_cvt_pk_bf16_f32 v137, v176, v177
	v_and_b32_e32 v201, 0xffff0000, v188
	v_cvt_pk_bf16_f32 v138, v178, v179
	v_cvt_pk_bf16_f32 v139, v142, v143
	global_store_dwordx4 v[134:135], v[136:139], off offset:256 nt
	v_mul_f32_e32 v134, v141, v141
	v_mul_f32_e32 v135, v177, v177
	v_fmac_f32_e32 v134, v140, v140
	v_fmac_f32_e32 v135, v176, v176
	v_add_f32_e32 v134, v134, v135
	v_mul_f32_e32 v135, v179, v179
	v_mul_f32_e32 v136, v143, v143
	v_fmac_f32_e32 v135, v178, v178
	v_fmac_f32_e32 v136, v142, v142
	v_add_f32_e32 v135, v135, v136
	v_add_f32_e32 v134, v134, v135
	v_add_f32_e32 v134, v180, v134
	ds_bpermute_b32 v135, v152, v134
	v_lshlrev_b32_e32 v204, 16, v189
	v_and_b32_e32 v205, 0xffff0000, v189
	v_lshlrev_b32_e32 v188, 16, v232
	v_and_b32_e32 v189, 0xffff0000, v232
	s_waitcnt lgkmcnt(0)
	v_add_f32_e32 v230, v134, v135
	v_lshl_add_u64 v[134:135], v[128:129], 0, s[4:5]
	s_mov_b32 s4, 0x50000
	v_add_co_u32_e32 v136, vcc, s4, v128
	v_and_b32_e32 v193, 0xffff0000, v233
	s_nop 0
	v_addc_co_u32_e32 v137, vcc, 0, v129, vcc
	global_load_dwordx4 v[176:179], v[136:137], off
	global_load_dwordx4 v[232:235], v[134:135], off offset:256
	v_pk_add_f32 v[194:195], v[46:47], v[204:205]
	v_pk_add_f32 v[204:205], v[44:45], v[200:201]
	v_pk_add_f32 v[202:203], v[42:43], v[202:203]
	v_pk_add_f32 v[190:191], v[36:37], v[190:191]
	v_pk_add_f32 v[192:193], v[34:35], v[192:193]
	s_mov_b64 s[4:5], 0x58000
	ds_bpermute_b32 v231, v225, v230
	s_waitcnt vmcnt(1)
	v_lshlrev_b32_e32 v140, 16, v176
	s_waitcnt vmcnt(0)
; __device__ __forceinline__ unsigned cvt_pk_bf16(float lo, float hi) { unsigned r; asm volatile("v_cvt_pk_bf16_f32 %0, %1, %2" : "=v"(r) : "v"(lo), "v"(hi)); return r; }
; __device__ __forceinline__ float bflo(unsigned w) { return __uint_as_float(w << 16); }
; template <bool RD32>
; __device__ __forceinline__ void res_rows(const float* __restrict__ xold32, const bf16_t* __restrict__ xoldb, bf16_t* __restrict__ xb, float* __restrict__ ssq, const f32x4 (&acc)[2][2][4][2], int row0, int col0, int slot) {
;     ...
;     auto ld = [&](size_t o, f32x4& a, f32x4& b) { if (RD32) { a = *(const f32x4*)(xold32 + o); b = *(const f32x4*)(xold32 + o + 4); }
;         else { const u32x4 w = *(const u32x4*)(xoldb + o); a = (f32x4){bflo(w.x), bfhi(w.x), bflo(w.y), bfhi(w.y)}; b = (f32x4){bflo(w.z), bfhi(w.z), bflo(w.w), bfhi(w.w)}; } };
; #pragma unroll
;     for (int bj = 0; bj < 2; ++bj) ld((size_t)row0 * D + col0 + bj * HALF, xo[0][bj][0], xo[0][bj][1]);
; #pragma unroll
;     for (int idx = 0; idx < 8; ++idx) {
;         const int ai = idx >> 2, m = idx & 3; const int r = row0 + ai * HALF + m * 16; const size_t off = (size_t)r * D + col0;
;         if (idx < 7) { const int ai2 = (idx + 1) >> 2, m2 = (idx + 1) & 3; const size_t off2 = (size_t)(row0 + ai2 * HALF + m2 * 16) * D + col0;
; #pragma unroll
;             for (int bj = 0; bj < 2; ++bj) ld(off2 + bj * HALF, xo[(idx + 1) & 1][bj][0], xo[(idx + 1) & 1][bj][1]); }
;         float ss = 0.f;
; #pragma unroll
;         for (int bj = 0; bj < 2; ++bj) { const f32x4 x0 = xo[idx & 1][bj][0] + acc[ai][bj][m][0], x1 = xo[idx & 1][bj][1] + acc[ai][bj][m][1];
;             u32x4 w; w.x = cvt_pk_bf16(x0[0], x0[1]); w.y = cvt_pk_bf16(x0[2], x0[3]); w.z = cvt_pk_bf16(x1[0], x1[1]); w.w = cvt_pk_bf16(x1[2], x1[3]);
;             *(u32x4*)(xb + off + bj * HALF) = w;
;             ss += ((x0[0] * x0[0] + x0[1] * x0[1]) + (x0[2] * x0[2] + x0[3] * x0[3])) + ((x1[0] * x1[0] + x1[1] * x1[1]) + (x1[2] * x1[2] + x1[3] * x1[3])); }
;         ss += __shfl_xor(ss, 16); ss += __shfl_xor(ss, 32);
;         ssv[idx] = ss;
;     }
;     const int fq = slot >> 6;
; #pragma unroll
;     for (int j = 0; j < 2; ++j) { const float v = fq == 0 ? ssv[j] : fq == 1 ? ssv[2 + j] : fq == 2 ? ssv[4 + j] : ssv[6 + j]; const int idx = 2 * fq + j;
;         ssq[(size_t)(row0 + (idx >> 2) * HALF + (idx & 3) * 16) * 16 + (slot & 15)] = v; }
; }
	v_lshlrev_b32_e32 v180, 16, v232
	v_and_b32_e32 v181, 0xffff0000, v232
	v_lshlrev_b32_e32 v184, 16, v233
	v_and_b32_e32 v185, 0xffff0000, v233
	v_pk_add_f32 v[232:233], v[40:41], v[198:199]
	v_cvt_pk_bf16_f32 v198, v204, v205
	v_cvt_pk_bf16_f32 v199, v194, v195
	v_and_b32_e32 v141, 0xffff0000, v176
	v_cvt_pk_bf16_f32 v200, v232, v233
	v_cvt_pk_bf16_f32 v201, v202, v203
	global_store_dwordx4 v[186:187], v[198:201], off nt
	v_mul_f32_e32 v186, v205, v205
	v_mul_f32_e32 v187, v195, v195
	v_fmac_f32_e32 v186, v204, v204
	v_fmac_f32_e32 v187, v194, v194
	v_add_f32_e32 v186, v186, v187
	v_mul_f32_e32 v187, v233, v233
	v_mul_f32_e32 v194, v203, v203
	v_fmac_f32_e32 v187, v232, v232
	v_fmac_f32_e32 v194, v202, v202
	v_add_f32_e32 v187, v187, v194
	v_pk_add_f32 v[194:195], v[38:39], v[196:197]
	v_add_f32_e32 v198, v186, v187
	v_pk_add_f32 v[196:197], v[32:33], v[188:189]
	v_cvt_pk_bf16_f32 v186, v190, v191
	v_cvt_pk_bf16_f32 v187, v194, v195
	v_lshlrev_b32_e32 v176, 16, v177
	v_cvt_pk_bf16_f32 v188, v196, v197
	v_cvt_pk_bf16_f32 v189, v192, v193
	global_store_dwordx4 v[130:131], v[186:189], off offset:256 nt
	v_mul_f32_e32 v130, v191, v191
	v_mul_f32_e32 v131, v195, v195
	v_fmac_f32_e32 v130, v190, v190
	v_fmac_f32_e32 v131, v194, v194
	v_add_f32_e32 v130, v130, v131
	v_mul_f32_e32 v131, v197, v197
	v_mul_f32_e32 v186, v193, v193
	v_fmac_f32_e32 v131, v196, v196
	v_fmac_f32_e32 v186, v192, v192
	v_add_f32_e32 v131, v131, v186
	v_add_f32_e32 v130, v130, v131
	v_add_f32_e32 v130, v198, v130
	ds_bpermute_b32 v131, v152, v130
	v_lshl_add_u64 v[186:187], v[128:129], 0, s[4:5]
	s_mov_b32 s4, 0x58000
	v_add_co_u32_e32 v188, vcc, s4, v128
	s_waitcnt lgkmcnt(0)
	v_add_f32_e32 v198, v130, v131
	v_addc_co_u32_e32 v189, vcc, 0, v129, vcc
	global_load_dwordx4 v[128:131], v[188:189], off
	v_and_b32_e32 v177, 0xffff0000, v177
	v_lshlrev_b32_e32 v138, 16, v178
	v_and_b32_e32 v139, 0xffff0000, v178
	v_lshlrev_b32_e32 v142, 16, v179
	v_and_b32_e32 v143, 0xffff0000, v179
	v_pk_add_f32 v[176:177], v[30:31], v[176:177]
	v_pk_add_f32 v[140:141], v[28:29], v[140:141]
	v_pk_add_f32 v[142:143], v[26:27], v[142:143]
	v_pk_add_f32 v[138:139], v[24:25], v[138:139]
	v_lshlrev_b32_e32 v178, 16, v234
	v_and_b32_e32 v179, 0xffff0000, v234
	v_lshlrev_b32_e32 v182, 16, v235
	v_and_b32_e32 v183, 0xffff0000, v235
	ds_bpermute_b32 v199, v225, v198
	v_cmp_lt_u32_e32 vcc, 63, v222
	s_waitcnt vmcnt(0)
	v_lshlrev_b32_e32 v192, 16, v128
	v_and_b32_e32 v193, 0xffff0000, v128
	v_lshlrev_b32_e32 v196, 16, v129
	v_and_b32_e32 v197, 0xffff0000, v129
	v_lshlrev_b32_e32 v190, 16, v130
	v_and_b32_e32 v191, 0xffff0000, v130
	v_lshlrev_b32_e32 v194, 16, v131
	v_and_b32_e32 v195, 0xffff0000, v131
	global_load_dwordx4 v[128:131], v[186:187], off offset:256
	s_waitcnt vmcnt(0)
	v_lshlrev_b32_e32 v200, 16, v128
	v_and_b32_e32 v201, 0xffff0000, v128
	v_lshlrev_b32_e32 v202, 16, v129
	v_and_b32_e32 v203, 0xffff0000, v129
	v_cvt_pk_bf16_f32 v128, v140, v141
	v_cvt_pk_bf16_f32 v129, v176, v177
	v_lshlrev_b32_e32 v204, 16, v130
	v_and_b32_e32 v205, 0xffff0000, v130
	v_lshlrev_b32_e32 v232, 16, v131
	v_and_b32_e32 v233, 0xffff0000, v131
	v_cvt_pk_bf16_f32 v130, v138, v139
	v_cvt_pk_bf16_f32 v131, v142, v143
	global_store_dwordx4 v[136:137], v[128:131], off nt
	v_pk_add_f32 v[136:137], v[22:23], v[184:185]
	s_nop 0
	v_mul_f32_e32 v128, v141, v141
	v_mul_f32_e32 v129, v177, v177
	v_fmac_f32_e32 v128, v140, v140
	v_fmac_f32_e32 v129, v176, v176
	v_add_f32_e32 v128, v128, v129
	v_mul_f32_e32 v129, v139, v139
	v_mul_f32_e32 v130, v143, v143
	v_fmac_f32_e32 v129, v138, v138
	v_fmac_f32_e32 v130, v142, v142
	v_add_f32_e32 v129, v129, v130
	v_add_f32_e32 v176, v128, v129
	v_pk_add_f32 v[138:139], v[20:21], v[180:181]
	v_pk_add_f32 v[140:141], v[18:19], v[182:183]
	v_cvt_pk_bf16_f32 v128, v138, v139
	v_cvt_pk_bf16_f32 v129, v136, v137
	v_pk_add_f32 v[142:143], v[16:17], v[178:179]
	s_nop 0
	v_cvt_pk_bf16_f32 v130, v142, v143
	v_cvt_pk_bf16_f32 v131, v140, v141
	global_store_dwordx4 v[134:135], v[128:131], off offset:256 nt
	s_nop 1
	v_mul_f32_e32 v128, v139, v139
	v_mul_f32_e32 v129, v137, v137
	v_fmac_f32_e32 v128, v138, v138
	v_fmac_f32_e32 v129, v136, v136
	v_add_f32_e32 v128, v128, v129
	v_mul_f32_e32 v129, v143, v143
	v_mul_f32_e32 v130, v141, v141
	v_fmac_f32_e32 v129, v142, v142
	v_fmac_f32_e32 v130, v140, v140
	v_add_f32_e32 v129, v129, v130
	v_add_f32_e32 v128, v128, v129
	v_add_f32_e32 v128, v176, v128
	ds_bpermute_b32 v129, v152, v128
	v_pk_add_f32 v[130:131], v[14:15], v[196:197]
	v_pk_add_f32 v[140:141], v[12:13], v[192:193]
	v_pk_add_f32 v[142:143], v[10:11], v[194:195]
	v_cvt_pk_bf16_f32 v136, v140, v141
	s_waitcnt lgkmcnt(0)
	v_add_f32_e32 v129, v128, v129
	v_cvt_pk_bf16_f32 v137, v130, v131
	v_mul_f32_e32 v128, v141, v141
	v_mul_f32_e32 v131, v131, v131
	v_pk_add_f32 v[176:177], v[8:9], v[190:191]
	v_fmac_f32_e32 v128, v140, v140
	v_fmac_f32_e32 v131, v130, v130
	v_add_f32_e32 v128, v128, v131
	v_mul_f32_e32 v130, v177, v177
	v_mul_f32_e32 v131, v143, v143
	v_fmac_f32_e32 v130, v176, v176
	v_fmac_f32_e32 v131, v142, v142
	v_add_f32_e32 v130, v130, v131
	v_add_f32_e32 v128, v128, v130
	v_pk_add_f32 v[130:131], v[6:7], v[202:203]
	v_pk_add_f32 v[140:141], v[4:5], v[200:201]
	v_cvt_pk_bf16_f32 v138, v176, v177
	v_cvt_pk_bf16_f32 v139, v142, v143
	global_store_dwordx4 v[188:189], v[136:139], off nt
	v_mul_f32_e32 v134, v141, v141
	v_pk_add_f32 v[142:143], v[2:3], v[232:233]
	v_cvt_pk_bf16_f32 v136, v140, v141
	v_cvt_pk_bf16_f32 v137, v130, v131
	v_mul_f32_e32 v131, v131, v131
	v_pk_add_f32 v[176:177], v[0:1], v[204:205]
	v_fmac_f32_e32 v134, v140, v140
	v_fmac_f32_e32 v131, v130, v130
	v_add_f32_e32 v130, v134, v131
	v_mul_f32_e32 v131, v177, v177
	v_mul_f32_e32 v134, v143, v143
	v_fmac_f32_e32 v131, v176, v176
	v_fmac_f32_e32 v134, v142, v142
	v_add_f32_e32 v131, v131, v134
	v_add_f32_e32 v130, v130, v131
	v_add_f32_e32 v128, v128, v130
	ds_bpermute_b32 v130, v152, v128
	v_cvt_pk_bf16_f32 v138, v176, v177
	v_cvt_pk_bf16_f32 v139, v142, v143
	global_store_dwordx4 v[186:187], v[136:139], off offset:256 nt
	ds_bpermute_b32 v135, v225, v129
	s_waitcnt lgkmcnt(1)
	v_add_f32_e32 v136, v128, v130
	ds_bpermute_b32 v137, v225, v136
	v_and_b32_e32 v130, 15, v223
	v_and_b32_e32 v128, 0xffffff80, v222
	v_lshlrev_b32_e32 v152, 2, v130
	v_add_u32_e32 v128, v166, v128
	v_lshl_add_u64 v[130:131], s[18:19], 0, v[152:153]
	s_and_saveexec_b64 s[4:5], vcc
	s_xor_b64 s[24:25], exec, s[4:5]
	s_cbranch_execz .LBB0_433
	v_ashrrev_i32_e32 v138, 6, v222
	v_cmp_lt_i32_e32 vcc, 1, v138
	s_mov_b64 s[36:37], 0
	s_and_saveexec_b64 s[4:5], vcc
	s_xor_b64 s[38:39], exec, s[4:5]
	s_cbranch_execnz .LBB0_454
	s_or_saveexec_b64 s[38:39], s[38:39]
	v_cmp_ne_u32_e32 vcc, 1, v138
	s_xor_b64 exec, exec, s[38:39]
	s_cbranch_execnz .LBB0_457

; __device__ __forceinline__ unsigned cvt_pk_bf16(float lo, float hi) { unsigned r; asm volatile("v_cvt_pk_bf16_f32 %0, %1, %2" : "=v"(r) : "v"(lo), "v"(hi)); return r; }
; __device__ __forceinline__ float bflo(unsigned w) { return __uint_as_float(w << 16); }
; __device__ __forceinline__ float bfhi(unsigned w) { return __uint_as_float(w & 0xffff0000u); }
; template <bool RD32>
; __device__ __forceinline__ void res_rows(const float* __restrict__ xold32, const bf16_t* __restrict__ xoldb, bf16_t* __restrict__ xb, float* __restrict__ ssq, const f32x4 (&acc)[2][2][4][2], int row0, int col0, int slot) {
;     ...
;     auto ld = [&](size_t o, f32x4& a, f32x4& b) { if (RD32) { a = *(const f32x4*)(xold32 + o); b = *(const f32x4*)(xold32 + o + 4); }
;         else { const u32x4 w = *(const u32x4*)(xoldb + o); a = (f32x4){bflo(w.x), bfhi(w.x), bflo(w.y), bfhi(w.y)}; b = (f32x4){bflo(w.z), bfhi(w.z), bflo(w.w), bfhi(w.w)}; } };
; #pragma unroll
;     for (int bj = 0; bj < 2; ++bj) ld((size_t)row0 * D + col0 + bj * HALF, xo[0][bj][0], xo[0][bj][1]);
; #pragma unroll
;     for (int idx = 0; idx < 8; ++idx) {
;         const int ai = idx >> 2, m = idx & 3; const int r = row0 + ai * HALF + m * 16; const size_t off = (size_t)r * D + col0;
;         if (idx < 7) { const int ai2 = (idx + 1) >> 2, m2 = (idx + 1) & 3; const size_t off2 = (size_t)(row0 + ai2 * HALF + m2 * 16) * D + col0;
; #pragma unroll
;             for (int bj = 0; bj < 2; ++bj) ld(off2 + bj * HALF, xo[(idx + 1) & 1][bj][0], xo[(idx + 1) & 1][bj][1]); }
;         float ss = 0.f;
; #pragma unroll
;         for (int bj = 0; bj < 2; ++bj) { const f32x4 x0 = xo[idx & 1][bj][0] + acc[ai][bj][m][0], x1 = xo[idx & 1][bj][1] + acc[ai][bj][m][1];
;             u32x4 w; w.x = cvt_pk_bf16(x0[0], x0[1]); w.y = cvt_pk_bf16(x0[2], x0[3]); w.z = cvt_pk_bf16(x1[0], x1[1]); w.w = cvt_pk_bf16(x1[2], x1[3]);
;             *(u32x4*)(xb + off + bj * HALF) = w;
;             ss += ((x0[0] * x0[0] + x0[1] * x0[1]) + (x0[2] * x0[2] + x0[3] * x0[3])) + ((x1[0] * x1[0] + x1[1] * x1[1]) + (x1[2] * x1[2] + x1[3] * x1[3])); }
;         ss += __shfl_xor(ss, 16); ss += __shfl_xor(ss, 32);
;         ssv[idx] = ss;
.LBB0_436:
.LBB0_437:
	v_readlane_b32 s4, v248, 0
	v_lshlrev_b64 v[128:129], 12, v[166:167]
	v_readlane_b32 s5, v248, 1
	v_lshlrev_b64 v[130:131], 2, v[132:133]
	v_ashrrev_i32_e32 v173, 31, v172
	v_lshl_add_u64 v[128:129], s[4:5], 0, v[128:129]
	v_lshl_add_u64 v[128:129], v[128:129], 0, v[130:131]
	global_load_dwordx4 v[180:183], v[128:129], off offset:16
	global_load_dwordx4 v[184:187], v[128:129], off
	global_load_dwordx4 v[188:191], v[128:129], off offset:528
	global_load_dwordx4 v[192:195], v[128:129], off offset:512
	v_lshl_add_u64 v[178:179], s[4:5], 0, v[130:131]
	v_lshlrev_b64 v[128:129], 12, v[172:173]
	v_lshl_add_u64 v[176:177], v[132:133], 1, s[58:59]
	v_lshl_add_u64 v[132:133], v[178:179], 0, v[128:129]
	s_waitcnt lgkmcnt(0)
	global_load_dwordx4 v[136:139], v[132:133], off offset:16
	global_load_dwordx4 v[140:143], v[132:133], off
	global_load_dwordx4 v[128:131], v[132:133], off offset:528
	s_nop 0
	global_load_dwordx4 v[132:135], v[132:133], off offset:512
	v_lshl_add_u64 v[174:175], v[176:177], 0, v[174:175]
	v_ashrrev_i32_e32 v171, 31, v170
	v_lshlrev_b64 v[172:173], 11, v[172:173]
	v_lshl_add_u64 v[172:173], v[176:177], 0, v[172:173]
	v_ashrrev_i32_e32 v169, 31, v168
	v_readlane_b32 s18, v248, 14
	v_readlane_b32 s19, v248, 15
	v_readlane_b32 s18, v246, 41
	v_readlane_b32 s19, v246, 42
	v_readlane_b32 s6, v248, 2
	v_readlane_b32 s7, v248, 3
	v_readlane_b32 s8, v248, 4
	v_readlane_b32 s9, v248, 5
	v_readlane_b32 s10, v248, 6
	v_readlane_b32 s11, v248, 7
	v_readlane_b32 s12, v248, 8
	v_readlane_b32 s13, v248, 9
	v_readlane_b32 s14, v248, 10
	v_readlane_b32 s15, v248, 11
	v_readlane_b32 s16, v248, 12
	v_readlane_b32 s17, v248, 13
	s_waitcnt vmcnt(0)
	v_pk_add_f32 v[180:181], v[120:121], v[180:181]
	v_pk_add_f32 v[126:127], v[126:127], v[186:187]
	v_pk_add_f32 v[124:125], v[124:125], v[184:185]
	v_pk_add_f32 v[182:183], v[122:123], v[182:183]
	v_cvt_pk_bf16_f32 v120, v124, v125
	v_cvt_pk_bf16_f32 v121, v126, v127
	v_cvt_pk_bf16_f32 v122, v180, v181
	v_pk_add_f32 v[118:119], v[118:119], v[194:195]
	v_cvt_pk_bf16_f32 v123, v182, v183
	global_store_dwordx4 v[174:175], v[120:123], off nt
	v_pk_add_f32 v[116:117], v[116:117], v[192:193]
	v_pk_add_f32 v[110:111], v[110:111], v[142:143]
	v_mul_f32_e32 v120, v125, v125
	v_mul_f32_e32 v121, v127, v127
	v_fmac_f32_e32 v120, v124, v124
	v_fmac_f32_e32 v121, v126, v126
	v_add_f32_e32 v120, v120, v121
	v_mul_f32_e32 v121, v181, v181
	v_mul_f32_e32 v122, v183, v183
	v_fmac_f32_e32 v121, v180, v180
	v_fmac_f32_e32 v122, v182, v182
	v_add_f32_e32 v121, v121, v122
	v_pk_add_f32 v[122:123], v[112:113], v[188:189]
	v_cvt_pk_bf16_f32 v112, v116, v117
	v_cvt_pk_bf16_f32 v113, v118, v119
	v_add_f32_e32 v124, v120, v121
	v_pk_add_f32 v[120:121], v[114:115], v[190:191]
	v_cvt_pk_bf16_f32 v114, v122, v123
	v_pk_add_f32 v[108:109], v[108:109], v[140:141]
	v_cvt_pk_bf16_f32 v115, v120, v121
	global_store_dwordx4 v[174:175], v[112:115], off offset:256 nt
	v_pk_add_f32 v[136:137], v[104:105], v[136:137]
	v_pk_add_f32 v[138:139], v[106:107], v[138:139]
	v_mul_f32_e32 v112, v117, v117
	v_mul_f32_e32 v113, v119, v119
	v_fmac_f32_e32 v112, v116, v116
	v_fmac_f32_e32 v113, v118, v118
	v_add_f32_e32 v112, v112, v113
	v_mul_f32_e32 v113, v123, v123
	v_mul_f32_e32 v114, v121, v121
	v_fmac_f32_e32 v113, v122, v122
	v_fmac_f32_e32 v114, v120, v120
	v_add_f32_e32 v113, v113, v114
	v_and_b32_e32 v114, 64, v209
	v_add_f32_e32 v112, v112, v113
	v_xor_b32_e32 v113, 16, v209
	v_add_u32_e32 v114, 64, v114
	v_cmp_lt_i32_e32 vcc, v113, v114
	v_add_f32_e32 v112, v124, v112
	v_pk_add_f32 v[102:103], v[102:103], v[134:135]
	v_cndmask_b32_e32 v113, v209, v113, vcc
	v_lshlrev_b32_e32 v152, 2, v113
	ds_bpermute_b32 v113, v152, v112
	v_pk_add_f32 v[100:101], v[100:101], v[132:133]
	s_waitcnt lgkmcnt(0)
	v_add_f32_e32 v174, v112, v113
	v_xor_b32_e32 v112, 32, v209
	v_cmp_lt_i32_e32 vcc, v112, v114
	s_nop 1
	v_cndmask_b32_e32 v112, v209, v112, vcc
	v_lshlrev_b32_e32 v180, 2, v112
	v_lshlrev_b64 v[112:113], 12, v[170:171]
	v_lshl_add_u64 v[116:117], v[178:179], 0, v[112:113]
	global_load_dwordx4 v[120:123], v[116:117], off offset:16
	global_load_dwordx4 v[124:127], v[116:117], off
	global_load_dwordx4 v[112:115], v[116:117], off offset:528
	s_nop 0
	global_load_dwordx4 v[116:119], v[116:117], off offset:512
	v_cvt_pk_bf16_f32 v104, v108, v109
	v_cvt_pk_bf16_f32 v105, v110, v111
	v_cvt_pk_bf16_f32 v106, v136, v137
	v_cvt_pk_bf16_f32 v107, v138, v139
	global_store_dwordx4 v[172:173], v[104:107], off nt
	ds_bpermute_b32 v175, v180, v174
	v_cmp_lt_u32_e32 vcc, 63, v222
	v_mul_f32_e32 v104, v109, v109
	v_mul_f32_e32 v105, v111, v111
	v_fmac_f32_e32 v104, v108, v108
	v_fmac_f32_e32 v105, v110, v110
	v_add_f32_e32 v104, v104, v105
	v_mul_f32_e32 v105, v137, v137
	v_mul_f32_e32 v106, v139, v139
	v_fmac_f32_e32 v105, v136, v136
	v_fmac_f32_e32 v106, v138, v138
	v_add_f32_e32 v105, v105, v106
	v_pk_add_f32 v[106:107], v[96:97], v[128:129]
	v_cvt_pk_bf16_f32 v96, v100, v101
	v_cvt_pk_bf16_f32 v97, v102, v103
	v_add_f32_e32 v108, v104, v105
	v_pk_add_f32 v[104:105], v[98:99], v[130:131]
	v_cvt_pk_bf16_f32 v98, v106, v107
	v_lshlrev_b64 v[130:131], 11, v[170:171]
	v_cvt_pk_bf16_f32 v99, v104, v105
	global_store_dwordx4 v[172:173], v[96:99], off offset:256 nt
	v_lshl_add_u64 v[130:131], v[176:177], 0, v[130:131]
	s_waitcnt vmcnt(5)
	v_pk_add_f32 v[120:121], v[88:89], v[120:121]
	v_mul_f32_e32 v96, v101, v101
	v_mul_f32_e32 v97, v103, v103
	v_fmac_f32_e32 v96, v100, v100
	v_fmac_f32_e32 v97, v102, v102
	v_add_f32_e32 v96, v96, v97
	v_mul_f32_e32 v97, v107, v107
	v_mul_f32_e32 v98, v105, v105
	v_fmac_f32_e32 v97, v106, v106
	v_fmac_f32_e32 v98, v104, v104
	v_add_f32_e32 v97, v97, v98
	v_add_f32_e32 v96, v96, v97
	v_add_f32_e32 v96, v108, v96
	ds_bpermute_b32 v97, v152, v96
	s_waitcnt vmcnt(4)
; __device__ __forceinline__ unsigned cvt_pk_bf16(float lo, float hi) { unsigned r; asm volatile("v_cvt_pk_bf16_f32 %0, %1, %2" : "=v"(r) : "v"(lo), "v"(hi)); return r; }
; __device__ __forceinline__ float bflo(unsigned w) { return __uint_as_float(w << 16); }
; __device__ __forceinline__ float bfhi(unsigned w) { return __uint_as_float(w & 0xffff0000u); }
; template <bool RD32>
; __device__ __forceinline__ void res_rows(const float* __restrict__ xold32, const bf16_t* __restrict__ xoldb, bf16_t* __restrict__ xb, float* __restrict__ ssq, const f32x4 (&acc)[2][2][4][2], int row0, int col0, int slot) {
;     ...
;     auto ld = [&](size_t o, f32x4& a, f32x4& b) { if (RD32) { a = *(const f32x4*)(xold32 + o); b = *(const f32x4*)(xold32 + o + 4); }
;         else { const u32x4 w = *(const u32x4*)(xoldb + o); a = (f32x4){bflo(w.x), bfhi(w.x), bflo(w.y), bfhi(w.y)}; b = (f32x4){bflo(w.z), bfhi(w.z), bflo(w.w), bfhi(w.w)}; } };
; #pragma unroll
;     for (int bj = 0; bj < 2; ++bj) ld((size_t)row0 * D + col0 + bj * HALF, xo[0][bj][0], xo[0][bj][1]);
; #pragma unroll
;     for (int idx = 0; idx < 8; ++idx) {
;         const int ai = idx >> 2, m = idx & 3; const int r = row0 + ai * HALF + m * 16; const size_t off = (size_t)r * D + col0;
;         if (idx < 7) { const int ai2 = (idx + 1) >> 2, m2 = (idx + 1) & 3; const size_t off2 = (size_t)(row0 + ai2 * HALF + m2 * 16) * D + col0;
; #pragma unroll
;             for (int bj = 0; bj < 2; ++bj) ld(off2 + bj * HALF, xo[(idx + 1) & 1][bj][0], xo[(idx + 1) & 1][bj][1]); }
;         float ss = 0.f;
; #pragma unroll
;         for (int bj = 0; bj < 2; ++bj) { const f32x4 x0 = xo[idx & 1][bj][0] + acc[ai][bj][m][0], x1 = xo[idx & 1][bj][1] + acc[ai][bj][m][1];
;             u32x4 w; w.x = cvt_pk_bf16(x0[0], x0[1]); w.y = cvt_pk_bf16(x0[2], x0[3]); w.z = cvt_pk_bf16(x1[0], x1[1]); w.w = cvt_pk_bf16(x1[2], x1[3]);
;             *(u32x4*)(xb + off + bj * HALF) = w;
;             ss += ((x0[0] * x0[0] + x0[1] * x0[1]) + (x0[2] * x0[2] + x0[3] * x0[3])) + ((x1[0] * x1[0] + x1[1] * x1[1]) + (x1[2] * x1[2] + x1[3] * x1[3])); }
;         ss += __shfl_xor(ss, 16); ss += __shfl_xor(ss, 32);
;         ssv[idx] = ss;
	v_pk_add_f32 v[94:95], v[94:95], v[126:127]
	v_pk_add_f32 v[92:93], v[92:93], v[124:125]
	v_pk_add_f32 v[122:123], v[90:91], v[122:123]
	s_waitcnt vmcnt(2)
	v_pk_add_f32 v[86:87], v[86:87], v[118:119]
	s_waitcnt lgkmcnt(0)
	v_add_f32_e32 v129, v96, v97
	v_lshlrev_b64 v[96:97], 12, v[168:169]
	v_lshl_add_u64 v[100:101], v[178:179], 0, v[96:97]
	global_load_dwordx4 v[104:107], v[100:101], off offset:16
	global_load_dwordx4 v[108:111], v[100:101], off
	global_load_dwordx4 v[96:99], v[100:101], off offset:528
	s_nop 0
	global_load_dwordx4 v[100:103], v[100:101], off offset:512
	v_cvt_pk_bf16_f32 v88, v92, v93
	v_cvt_pk_bf16_f32 v89, v94, v95
	v_cvt_pk_bf16_f32 v90, v120, v121
	v_cvt_pk_bf16_f32 v91, v122, v123
	global_store_dwordx4 v[130:131], v[88:91], off nt
	v_pk_add_f32 v[84:85], v[84:85], v[116:117]
	v_lshlrev_b64 v[116:117], 11, v[168:169]
	v_mul_f32_e32 v88, v93, v93
	v_mul_f32_e32 v89, v95, v95
	v_fmac_f32_e32 v88, v92, v92
	v_fmac_f32_e32 v89, v94, v94
	v_add_f32_e32 v88, v88, v89
	v_mul_f32_e32 v89, v121, v121
	v_mul_f32_e32 v90, v123, v123
	v_fmac_f32_e32 v89, v120, v120
	v_fmac_f32_e32 v90, v122, v122
	v_add_f32_e32 v89, v89, v90
	v_pk_add_f32 v[90:91], v[80:81], v[112:113]
	v_cvt_pk_bf16_f32 v80, v84, v85
	v_cvt_pk_bf16_f32 v81, v86, v87
	v_add_f32_e32 v92, v88, v89
	v_pk_add_f32 v[88:89], v[82:83], v[114:115]
	v_cvt_pk_bf16_f32 v82, v90, v91
	v_add_u32_e32 v112, 0x80, v166
	v_cvt_pk_bf16_f32 v83, v88, v89
	global_store_dwordx4 v[130:131], v[80:83], off offset:256 nt
	v_ashrrev_i32_e32 v113, 31, v112
	v_lshl_add_u64 v[116:117], v[176:177], 0, v[116:117]
	v_mul_f32_e32 v80, v85, v85
	v_mul_f32_e32 v81, v87, v87
	v_fmac_f32_e32 v80, v84, v84
	v_fmac_f32_e32 v81, v86, v86
	v_add_f32_e32 v80, v80, v81
	v_mul_f32_e32 v81, v91, v91
	v_mul_f32_e32 v82, v89, v89
	v_fmac_f32_e32 v81, v90, v90
	v_fmac_f32_e32 v82, v88, v88
	v_add_f32_e32 v81, v81, v82
	v_add_f32_e32 v80, v80, v81
	v_add_f32_e32 v80, v92, v80
	ds_bpermute_b32 v81, v152, v80
	ds_bpermute_b32 v132, v180, v129
	s_waitcnt lgkmcnt(1)
	v_add_f32_e32 v114, v80, v81
	v_lshlrev_b64 v[80:81], 12, v[112:113]
	v_lshl_add_u64 v[84:85], v[178:179], 0, v[80:81]
	global_load_dwordx4 v[88:91], v[84:85], off offset:16
	global_load_dwordx4 v[92:95], v[84:85], off
	global_load_dwordx4 v[80:83], v[84:85], off offset:528
	s_nop 0
	global_load_dwordx4 v[84:87], v[84:85], off offset:512
	ds_bpermute_b32 v115, v180, v114
	s_waitcnt vmcnt(9)
	v_pk_add_f32 v[104:105], v[72:73], v[104:105]
	s_waitcnt vmcnt(8)
	v_pk_add_f32 v[78:79], v[78:79], v[110:111]
	v_pk_add_f32 v[76:77], v[76:77], v[108:109]
	v_pk_add_f32 v[106:107], v[74:75], v[106:107]
	v_cvt_pk_bf16_f32 v72, v76, v77
	v_cvt_pk_bf16_f32 v73, v78, v79
	v_cvt_pk_bf16_f32 v74, v104, v105
	s_waitcnt vmcnt(6)
	v_pk_add_f32 v[70:71], v[70:71], v[102:103]
	v_cvt_pk_bf16_f32 v75, v106, v107
	global_store_dwordx4 v[116:117], v[72:75], off nt
	v_pk_add_f32 v[68:69], v[68:69], v[100:101]
	s_waitcnt vmcnt(4)
	v_pk_add_f32 v[88:89], v[56:57], v[88:89]
	v_mul_f32_e32 v72, v77, v77
	v_mul_f32_e32 v73, v79, v79
	v_fmac_f32_e32 v72, v76, v76
	v_fmac_f32_e32 v73, v78, v78
	v_add_f32_e32 v72, v72, v73
	v_mul_f32_e32 v73, v105, v105
	v_mul_f32_e32 v74, v107, v107
	v_fmac_f32_e32 v73, v104, v104
	v_fmac_f32_e32 v74, v106, v106
	v_add_f32_e32 v73, v73, v74
	v_pk_add_f32 v[74:75], v[64:65], v[96:97]
	v_cvt_pk_bf16_f32 v64, v68, v69
	v_cvt_pk_bf16_f32 v65, v70, v71
	v_add_f32_e32 v76, v72, v73
	v_pk_add_f32 v[72:73], v[66:67], v[98:99]
	v_cvt_pk_bf16_f32 v66, v74, v75
	v_add_u32_e32 v96, 0x90, v166
	v_cvt_pk_bf16_f32 v67, v72, v73
	global_store_dwordx4 v[116:117], v[64:67], off offset:256 nt
	v_ashrrev_i32_e32 v97, 31, v96
	v_lshlrev_b64 v[98:99], 11, v[112:113]
	v_mul_f32_e32 v64, v69, v69
	v_mul_f32_e32 v65, v71, v71
	v_fmac_f32_e32 v64, v68, v68
	v_fmac_f32_e32 v65, v70, v70
	v_add_f32_e32 v64, v64, v65
	v_mul_f32_e32 v65, v75, v75
	v_mul_f32_e32 v66, v73, v73
	v_fmac_f32_e32 v65, v74, v74
	v_fmac_f32_e32 v66, v72, v72
	v_add_f32_e32 v65, v65, v66
	v_add_f32_e32 v64, v64, v65
	v_add_f32_e32 v64, v76, v64
	ds_bpermute_b32 v65, v152, v64
	v_lshl_add_u64 v[98:99], v[176:177], 0, v[98:99]
	s_waitcnt vmcnt(4)
	v_pk_add_f32 v[62:63], v[62:63], v[94:95]
	v_pk_add_f32 v[60:61], v[60:61], v[92:93]
	v_pk_add_f32 v[90:91], v[58:59], v[90:91]
	s_waitcnt lgkmcnt(0)
	v_add_f32_e32 v100, v64, v65
	v_lshlrev_b64 v[64:65], 12, v[96:97]
	v_lshl_add_u64 v[68:69], v[178:179], 0, v[64:65]
	global_load_dwordx4 v[72:75], v[68:69], off offset:16
	global_load_dwordx4 v[76:79], v[68:69], off
	global_load_dwordx4 v[64:67], v[68:69], off offset:528
	s_nop 0
	global_load_dwordx4 v[68:71], v[68:69], off offset:512
	v_cvt_pk_bf16_f32 v56, v60, v61
	v_cvt_pk_bf16_f32 v57, v62, v63
	v_cvt_pk_bf16_f32 v58, v88, v89
	v_cvt_pk_bf16_f32 v59, v90, v91
	global_store_dwordx4 v[98:99], v[56:59], off nt
	s_waitcnt vmcnt(7)
	v_pk_add_f32 v[54:55], v[54:55], v[86:87]
	v_pk_add_f32 v[52:53], v[52:53], v[84:85]
	v_mul_f32_e32 v56, v61, v61
	v_mul_f32_e32 v57, v63, v63
	v_fmac_f32_e32 v56, v60, v60
	v_fmac_f32_e32 v57, v62, v62
	v_add_f32_e32 v56, v56, v57
	v_mul_f32_e32 v57, v89, v89
	v_mul_f32_e32 v58, v91, v91
	v_fmac_f32_e32 v57, v88, v88
	v_fmac_f32_e32 v58, v90, v90
	v_add_f32_e32 v57, v57, v58
	v_pk_add_f32 v[58:59], v[48:49], v[80:81]
	v_cvt_pk_bf16_f32 v48, v52, v53
	v_cvt_pk_bf16_f32 v49, v54, v55
	v_add_f32_e32 v60, v56, v57
	v_pk_add_f32 v[56:57], v[50:51], v[82:83]
	v_cvt_pk_bf16_f32 v50, v58, v59
	v_add_u32_e32 v80, 0xa0, v166
	v_cvt_pk_bf16_f32 v51, v56, v57
	global_store_dwordx4 v[98:99], v[48:51], off offset:256 nt
	v_ashrrev_i32_e32 v81, 31, v80
	v_lshlrev_b64 v[84:85], 11, v[96:97]
	v_mul_f32_e32 v48, v53, v53
	v_mul_f32_e32 v49, v55, v55
	v_fmac_f32_e32 v48, v52, v52
	v_fmac_f32_e32 v49, v54, v54
	v_add_f32_e32 v48, v48, v49
	v_mul_f32_e32 v49, v59, v59
	v_mul_f32_e32 v50, v57, v57
	v_fmac_f32_e32 v49, v58, v58
	v_fmac_f32_e32 v50, v56, v56
	v_add_f32_e32 v49, v49, v50
	v_add_f32_e32 v48, v48, v49
	v_add_f32_e32 v48, v60, v48
	ds_bpermute_b32 v49, v152, v48
	v_lshl_add_u64 v[84:85], v[176:177], 0, v[84:85]
	ds_bpermute_b32 v101, v180, v100
	s_waitcnt lgkmcnt(1)
; __device__ __forceinline__ unsigned cvt_pk_bf16(float lo, float hi) { unsigned r; asm volatile("v_cvt_pk_bf16_f32 %0, %1, %2" : "=v"(r) : "v"(lo), "v"(hi)); return r; }
; __device__ __forceinline__ float bflo(unsigned w) { return __uint_as_float(w << 16); }
; template <bool RD32>
; __device__ __forceinline__ void res_rows(const float* __restrict__ xold32, const bf16_t* __restrict__ xoldb, bf16_t* __restrict__ xb, float* __restrict__ ssq, const f32x4 (&acc)[2][2][4][2], int row0, int col0, int slot) {
;     ...
;     auto ld = [&](size_t o, f32x4& a, f32x4& b) { if (RD32) { a = *(const f32x4*)(xold32 + o); b = *(const f32x4*)(xold32 + o + 4); }
;         else { const u32x4 w = *(const u32x4*)(xoldb + o); a = (f32x4){bflo(w.x), bfhi(w.x), bflo(w.y), bfhi(w.y)}; b = (f32x4){bflo(w.z), bfhi(w.z), bflo(w.w), bfhi(w.w)}; } };
; #pragma unroll
;     for (int bj = 0; bj < 2; ++bj) ld((size_t)row0 * D + col0 + bj * HALF, xo[0][bj][0], xo[0][bj][1]);
; #pragma unroll
;     for (int idx = 0; idx < 8; ++idx) {
;         const int ai = idx >> 2, m = idx & 3; const int r = row0 + ai * HALF + m * 16; const size_t off = (size_t)r * D + col0;
;         if (idx < 7) { const int ai2 = (idx + 1) >> 2, m2 = (idx + 1) & 3; const size_t off2 = (size_t)(row0 + ai2 * HALF + m2 * 16) * D + col0;
; #pragma unroll
;             for (int bj = 0; bj < 2; ++bj) ld(off2 + bj * HALF, xo[(idx + 1) & 1][bj][0], xo[(idx + 1) & 1][bj][1]); }
;         float ss = 0.f;
; #pragma unroll
;         for (int bj = 0; bj < 2; ++bj) { const f32x4 x0 = xo[idx & 1][bj][0] + acc[ai][bj][m][0], x1 = xo[idx & 1][bj][1] + acc[ai][bj][m][1];
;             u32x4 w; w.x = cvt_pk_bf16(x0[0], x0[1]); w.y = cvt_pk_bf16(x0[2], x0[3]); w.z = cvt_pk_bf16(x1[0], x1[1]); w.w = cvt_pk_bf16(x1[2], x1[3]);
;             *(u32x4*)(xb + off + bj * HALF) = w;
;             ss += ((x0[0] * x0[0] + x0[1] * x0[1]) + (x0[2] * x0[2] + x0[3] * x0[3])) + ((x1[0] * x1[0] + x1[1] * x1[1]) + (x1[2] * x1[2] + x1[3] * x1[3])); }
;         ss += __shfl_xor(ss, 16); ss += __shfl_xor(ss, 32);
;         ssv[idx] = ss;
;     }
;     const int fq = slot >> 6;
; #pragma unroll
;     for (int j = 0; j < 2; ++j) { const float v = fq == 0 ? ssv[j] : fq == 1 ? ssv[2 + j] : fq == 2 ? ssv[4 + j] : ssv[6 + j]; const int idx = 2 * fq + j;
;         ssq[(size_t)(row0 + (idx >> 2) * HALF + (idx & 3) * 16) * 16 + (slot & 15)] = v; }
; }
	v_add_f32_e32 v82, v48, v49
	v_lshlrev_b64 v[48:49], 12, v[80:81]
	v_lshl_add_u64 v[60:61], v[178:179], 0, v[48:49]
	global_load_dwordx4 v[48:51], v[60:61], off offset:16
	global_load_dwordx4 v[52:55], v[60:61], off
	global_load_dwordx4 v[56:59], v[60:61], off offset:528
	s_nop 0
	global_load_dwordx4 v[60:63], v[60:61], off offset:512
	ds_bpermute_b32 v83, v180, v82
	s_waitcnt vmcnt(9)
	v_pk_add_f32 v[72:73], v[40:41], v[72:73]
	s_waitcnt vmcnt(8)
	v_pk_add_f32 v[46:47], v[46:47], v[78:79]
	v_pk_add_f32 v[44:45], v[44:45], v[76:77]
	v_pk_add_f32 v[74:75], v[42:43], v[74:75]
	v_cvt_pk_bf16_f32 v40, v44, v45
	v_cvt_pk_bf16_f32 v41, v46, v47
	v_cvt_pk_bf16_f32 v42, v72, v73
	s_waitcnt vmcnt(6)
	v_pk_add_f32 v[38:39], v[38:39], v[70:71]
	v_cvt_pk_bf16_f32 v43, v74, v75
	global_store_dwordx4 v[84:85], v[40:43], off nt
	v_pk_add_f32 v[36:37], v[36:37], v[68:69]
	v_lshlrev_b64 v[68:69], 11, v[80:81]
	v_mul_f32_e32 v40, v45, v45
	v_mul_f32_e32 v41, v47, v47
	v_fmac_f32_e32 v40, v44, v44
	v_fmac_f32_e32 v41, v46, v46
	v_add_f32_e32 v40, v40, v41
	v_mul_f32_e32 v41, v73, v73
	v_mul_f32_e32 v42, v75, v75
	v_fmac_f32_e32 v41, v72, v72
	v_fmac_f32_e32 v42, v74, v74
	v_add_f32_e32 v41, v41, v42
	v_pk_add_f32 v[42:43], v[32:33], v[64:65]
	v_cvt_pk_bf16_f32 v32, v36, v37
	v_cvt_pk_bf16_f32 v33, v38, v39
	v_add_f32_e32 v44, v40, v41
	v_pk_add_f32 v[40:41], v[34:35], v[66:67]
	v_cvt_pk_bf16_f32 v34, v42, v43
	v_lshl_add_u64 v[68:69], v[176:177], 0, v[68:69]
	v_cvt_pk_bf16_f32 v35, v40, v41
	global_store_dwordx4 v[84:85], v[32:35], off offset:256 nt
	s_waitcnt vmcnt(5)
	v_pk_add_f32 v[48:49], v[24:25], v[48:49]
	v_mul_f32_e32 v32, v37, v37
	v_mul_f32_e32 v33, v39, v39
	v_fmac_f32_e32 v32, v36, v36
	v_fmac_f32_e32 v33, v38, v38
	v_add_f32_e32 v32, v32, v33
	v_mul_f32_e32 v33, v43, v43
	v_mul_f32_e32 v34, v41, v41
	v_fmac_f32_e32 v33, v42, v42
	v_fmac_f32_e32 v34, v40, v40
	v_add_f32_e32 v33, v33, v34
	v_add_f32_e32 v32, v32, v33
	v_add_f32_e32 v32, v44, v32
	ds_bpermute_b32 v33, v152, v32
	v_add_u32_e32 v44, 0xb0, v166
	v_ashrrev_i32_e32 v45, 31, v44
	s_waitcnt vmcnt(4)
	v_pk_add_f32 v[30:31], v[30:31], v[54:55]
	v_pk_add_f32 v[28:29], v[28:29], v[52:53]
	s_waitcnt lgkmcnt(0)
	v_add_f32_e32 v46, v32, v33
	v_lshlrev_b64 v[32:33], 12, v[44:45]
	v_lshl_add_u64 v[64:65], v[178:179], 0, v[32:33]
	global_load_dwordx4 v[36:39], v[64:65], off offset:16
	global_load_dwordx4 v[40:43], v[64:65], off
	global_load_dwordx4 v[32:35], v[64:65], off offset:528
	s_nop 0
	global_load_dwordx4 v[64:67], v[64:65], off offset:512
	v_cvt_pk_bf16_f32 v24, v28, v29
	v_cvt_pk_bf16_f32 v25, v30, v31
	v_pk_add_f32 v[50:51], v[26:27], v[50:51]
	v_cvt_pk_bf16_f32 v26, v48, v49
	s_waitcnt vmcnt(6)
	v_pk_add_f32 v[22:23], v[22:23], v[62:63]
	v_cvt_pk_bf16_f32 v27, v50, v51
	global_store_dwordx4 v[68:69], v[24:27], off nt
	v_pk_add_f32 v[20:21], v[20:21], v[60:61]
	ds_bpermute_b32 v47, v180, v46
	v_mul_f32_e32 v24, v29, v29
	v_mul_f32_e32 v25, v31, v31
	v_fmac_f32_e32 v24, v28, v28
	v_fmac_f32_e32 v25, v30, v30
	v_add_f32_e32 v24, v24, v25
	v_mul_f32_e32 v25, v49, v49
	v_mul_f32_e32 v26, v51, v51
	v_fmac_f32_e32 v25, v48, v48
	v_fmac_f32_e32 v26, v50, v50
	v_add_f32_e32 v25, v25, v26
	v_pk_add_f32 v[26:27], v[16:17], v[56:57]
	v_cvt_pk_bf16_f32 v16, v20, v21
	v_cvt_pk_bf16_f32 v17, v22, v23
	v_add_f32_e32 v28, v24, v25
	v_pk_add_f32 v[24:25], v[18:19], v[58:59]
	v_cvt_pk_bf16_f32 v18, v26, v27
	s_waitcnt vmcnt(3)
	v_pk_add_f32 v[14:15], v[14:15], v[42:43]
	v_cvt_pk_bf16_f32 v19, v24, v25
	global_store_dwordx4 v[68:69], v[16:19], off offset:256 nt
	v_pk_add_f32 v[12:13], v[12:13], v[40:41]
	s_waitcnt vmcnt(2)
	v_pk_add_f32 v[6:7], v[6:7], v[66:67]
	v_mul_f32_e32 v16, v21, v21
	v_mul_f32_e32 v17, v23, v23
	v_fmac_f32_e32 v16, v20, v20
	v_fmac_f32_e32 v17, v22, v22
	v_add_f32_e32 v16, v16, v17
	v_mul_f32_e32 v17, v27, v27
	v_mul_f32_e32 v18, v25, v25
	v_fmac_f32_e32 v17, v26, v26
	v_fmac_f32_e32 v18, v24, v24
	v_add_f32_e32 v17, v17, v18
	v_lshlrev_b64 v[18:19], 11, v[44:45]
	v_lshl_add_u64 v[18:19], v[176:177], 0, v[18:19]
	v_pk_add_f32 v[22:23], v[8:9], v[36:37]
	v_cvt_pk_bf16_f32 v8, v12, v13
	v_cvt_pk_bf16_f32 v9, v14, v15
	v_pk_add_f32 v[20:21], v[10:11], v[38:39]
	v_cvt_pk_bf16_f32 v10, v22, v23
	v_pk_add_f32 v[4:5], v[4:5], v[64:65]
	v_cvt_pk_bf16_f32 v11, v20, v21
	global_store_dwordx4 v[18:19], v[8:11], off nt
	v_add_f32_e32 v16, v16, v17
	v_add_f32_e32 v16, v28, v16
	v_mul_f32_e32 v8, v13, v13
	v_mul_f32_e32 v9, v15, v15
	v_fmac_f32_e32 v8, v12, v12
	v_fmac_f32_e32 v9, v14, v14
	v_add_f32_e32 v8, v8, v9
	v_mul_f32_e32 v9, v23, v23
	v_mul_f32_e32 v10, v21, v21
	v_fmac_f32_e32 v9, v22, v22
	v_fmac_f32_e32 v10, v20, v20
	v_add_f32_e32 v9, v9, v10
	v_pk_add_f32 v[10:11], v[0:1], v[32:33]
	v_cvt_pk_bf16_f32 v0, v4, v5
	v_cvt_pk_bf16_f32 v1, v6, v7
	v_add_f32_e32 v12, v8, v9
	v_pk_add_f32 v[8:9], v[2:3], v[34:35]
	v_cvt_pk_bf16_f32 v2, v10, v11
	ds_bpermute_b32 v17, v152, v16
	v_cvt_pk_bf16_f32 v3, v8, v9
	global_store_dwordx4 v[18:19], v[0:3], off offset:256 nt
	s_waitcnt lgkmcnt(0)
	v_add_f32_e32 v16, v16, v17
	v_mul_f32_e32 v0, v5, v5
	v_mul_f32_e32 v1, v7, v7
	v_fmac_f32_e32 v0, v4, v4
	v_fmac_f32_e32 v1, v6, v6
	v_add_f32_e32 v0, v0, v1
	v_mul_f32_e32 v1, v11, v11
	v_mul_f32_e32 v2, v9, v9
	v_fmac_f32_e32 v1, v10, v10
	v_fmac_f32_e32 v2, v8, v8
	v_add_f32_e32 v1, v1, v2
	v_add_f32_e32 v0, v0, v1
	v_add_f32_e32 v0, v12, v0
	ds_bpermute_b32 v1, v152, v0
	ds_bpermute_b32 v17, v180, v16
	v_and_b32_e32 v2, 0xffffff80, v222
	v_add_u32_e32 v128, v166, v2
	v_and_b32_e32 v2, 15, v223
	s_waitcnt lgkmcnt(1)
	v_add_f32_e32 v0, v0, v1
	ds_bpermute_b32 v1, v180, v0
	v_lshlrev_b32_e32 v152, 2, v2
	v_lshl_add_u64 v[130:131], s[18:19], 0, v[152:153]
	s_and_saveexec_b64 s[4:5], vcc
	s_xor_b64 s[24:25], exec, s[4:5]
	s_cbranch_execz .LBB0_448
	v_ashrrev_i32_e32 v2, 6, v222
	v_cmp_lt_i32_e32 vcc, 1, v2
	s_mov_b64 s[36:37], 0
	s_and_saveexec_b64 s[4:5], vcc
	s_xor_b64 s[38:39], exec, s[4:5]
	s_cbranch_execnz .LBB0_461
	s_or_saveexec_b64 s[38:39], s[38:39]
	v_cmp_ne_u32_e32 vcc, 1, v2
	s_xor_b64 exec, exec, s[38:39]
	s_cbranch_execnz .LBB0_464

; __device__ __forceinline__ unsigned cvt_pk_bf16(float lo, float hi) { unsigned r; asm volatile("v_cvt_pk_bf16_f32 %0, %1, %2" : "=v"(r) : "v"(lo), "v"(hi)); return r; }
;     __device__ __forceinline__ void operator()(const f32x4 (&acc)[2][2][4][2], const Unit& u, int wr, int wc, int fr, int fq) const {
;     ...
;                 const int r = row0 + ai * HALF + m * 16; const float rs = rsv[ai][m];
;                 bf16_t* rowp = H + (size_t)r * FF + u.pn * BM + wc * 32 + 8 * fq;
; #pragma unroll
;                 for (int bj = 0; bj < 2; ++bj) { f32x4 v0 = acc[ai][bj][m][0] * rs, v1 = acc[ai][bj][m][1] * rs;
; #pragma unroll
;                     for (int j = 0; j < 4; ++j) { const float a = fmaxf(v0[j], 0.f), b = fmaxf(v1[j], 0.f); v0[j] = a * a; v1[j] = b * b; }
;                     u32x4 w; w.x = cvt_pk_bf16(v0[0], v0[1]); w.y = cvt_pk_bf16(v0[2], v0[3]); w.z = cvt_pk_bf16(v1[0], v1[1]); w.w = cvt_pk_bf16(v1[2], v1[3]);
;                     *(u32x4*)(rowp + bj * HALF) = w; }
.LBB0_543:
	s_lshl_b32 s14, s65, 8
	s_ashr_i32 s15, s14, 31
	v_lshlrev_b64 v[134:135], 13, v[184:185]
	v_pk_mul_f32 v[120:121], v[120:121], v[190:191] op_sel_hi:[1,0]
	v_lshl_add_u64 v[134:135], s[60:61], 0, v[134:135]
	s_lshl_b64 s[46:47], s[14:15], 1
	v_pk_mul_f32 v[124:125], v[124:125], v[190:191] op_sel_hi:[1,0]
	v_pk_mul_f32 v[122:123], v[122:123], v[190:191] op_sel_hi:[1,0]
	v_max_f32_e32 v120, 0, v120
	v_lshl_add_u64 v[134:135], v[134:135], 0, s[46:47]
	v_pk_mul_f32 v[126:127], v[126:127], v[190:191] op_sel_hi:[1,0]
	v_mul_f32_e32 v129, v120, v120
	v_max_f32_e32 v120, 0, v125
	v_max_f32_e32 v121, 0, v121
	v_max_f32_e32 v122, 0, v122
	v_lshl_add_u64 v[134:135], v[134:135], 0, s[76:77]
	v_max_f32_e32 v124, 0, v124
	v_mul_f32_e32 v120, v120, v120
	v_mul_f32_e32 v125, v121, v121
	v_max_f32_e32 v121, 0, v126
	v_mul_f32_e32 v126, v122, v122
	v_max_f32_e32 v122, 0, v127
	v_max_f32_e32 v123, 0, v123
	v_pk_mul_f32 v[112:113], v[112:113], v[190:191] op_sel_hi:[1,0]
	v_lshl_add_u64 v[134:135], v[134:135], 0, v[152:153]
	v_mul_f32_e32 v124, v124, v124
	v_mul_f32_e32 v121, v121, v121
	v_mul_f32_e32 v122, v122, v122
	v_mul_f32_e32 v123, v123, v123
	v_cvt_pk_bf16_f32 v120, v124, v120
	v_pk_mul_f32 v[118:119], v[118:119], v[190:191] op_sel_hi:[1,0]
	v_pk_mul_f32 v[116:117], v[116:117], v[190:191] op_sel_hi:[1,0]
	v_pk_mul_f32 v[114:115], v[114:115], v[190:191] op_sel_hi:[1,0]
	v_max_f32_e32 v112, 0, v112
	v_max_f32_e32 v113, 0, v113
	v_cvt_pk_bf16_f32 v121, v121, v122
	v_cvt_pk_bf16_f32 v122, v129, v125
	v_cvt_pk_bf16_f32 v123, v126, v123
	global_store_dwordx4 v[134:135], v[120:123], off nt
	v_max_f32_e32 v114, 0, v114
	v_max_f32_e32 v116, 0, v116
	v_mul_f32_e32 v120, v112, v112
	v_max_f32_e32 v112, 0, v117
	v_mul_f32_e32 v117, v113, v113
	v_max_f32_e32 v113, 0, v118
	v_mul_f32_e32 v112, v112, v112
	v_mul_f32_e32 v113, v113, v113
	v_mul_f32_e32 v118, v114, v114
	v_max_f32_e32 v114, 0, v119
	v_max_f32_e32 v115, 0, v115
	v_mul_f32_e32 v116, v116, v116
	v_mul_f32_e32 v114, v114, v114
	v_mul_f32_e32 v115, v115, v115
	v_cvt_pk_bf16_f32 v112, v116, v112
	v_cvt_pk_bf16_f32 v113, v113, v114
	v_cvt_pk_bf16_f32 v114, v120, v117
	v_cvt_pk_bf16_f32 v115, v118, v115
	global_store_dwordx4 v[134:135], v[112:115], off offset:256 nt
	v_pk_mul_f32 v[104:105], v[104:105], v[188:189] op_sel_hi:[1,0]
	v_pk_mul_f32 v[108:109], v[108:109], v[188:189] op_sel_hi:[1,0]
	v_lshlrev_b64 v[112:113], 13, v[182:183]
	v_lshl_add_u64 v[112:113], s[60:61], 0, v[112:113]
	v_pk_mul_f32 v[106:107], v[106:107], v[188:189] op_sel_hi:[1,0]
	v_max_f32_e32 v104, 0, v104
	v_lshl_add_u64 v[112:113], v[112:113], 0, s[46:47]
	v_pk_mul_f32 v[110:111], v[110:111], v[188:189] op_sel_hi:[1,0]
	v_mul_f32_e32 v114, v104, v104
	v_max_f32_e32 v104, 0, v109
	v_max_f32_e32 v105, 0, v105
	v_max_f32_e32 v106, 0, v106
	v_lshl_add_u64 v[112:113], v[112:113], 0, s[76:77]
	v_max_f32_e32 v108, 0, v108
	v_mul_f32_e32 v104, v104, v104
	v_mul_f32_e32 v109, v105, v105
	v_max_f32_e32 v105, 0, v110
	v_mul_f32_e32 v110, v106, v106
	v_max_f32_e32 v106, 0, v111
	v_max_f32_e32 v107, 0, v107
	v_pk_mul_f32 v[96:97], v[96:97], v[188:189] op_sel_hi:[1,0]
	v_lshl_add_u64 v[112:113], v[112:113], 0, v[152:153]
	v_mul_f32_e32 v108, v108, v108
	v_mul_f32_e32 v105, v105, v105
	v_mul_f32_e32 v106, v106, v106
	v_mul_f32_e32 v107, v107, v107
	v_cvt_pk_bf16_f32 v104, v108, v104
	v_pk_mul_f32 v[102:103], v[102:103], v[188:189] op_sel_hi:[1,0]
	v_pk_mul_f32 v[100:101], v[100:101], v[188:189] op_sel_hi:[1,0]
	v_pk_mul_f32 v[98:99], v[98:99], v[188:189] op_sel_hi:[1,0]
	v_max_f32_e32 v96, 0, v96
	v_max_f32_e32 v97, 0, v97
	v_cvt_pk_bf16_f32 v105, v105, v106
	v_cvt_pk_bf16_f32 v106, v114, v109
	v_cvt_pk_bf16_f32 v107, v110, v107
	global_store_dwordx4 v[112:113], v[104:107], off nt
	v_max_f32_e32 v98, 0, v98
	v_max_f32_e32 v100, 0, v100
	v_mul_f32_e32 v104, v96, v96
	v_max_f32_e32 v96, 0, v101
	v_mul_f32_e32 v101, v97, v97
	v_max_f32_e32 v97, 0, v102
	v_mul_f32_e32 v96, v96, v96
	v_mul_f32_e32 v97, v97, v97
	v_mul_f32_e32 v102, v98, v98
	v_max_f32_e32 v98, 0, v103
	v_max_f32_e32 v99, 0, v99
	v_mul_f32_e32 v100, v100, v100
	v_mul_f32_e32 v98, v98, v98
	v_mul_f32_e32 v99, v99, v99
	v_cvt_pk_bf16_f32 v96, v100, v96
	v_cvt_pk_bf16_f32 v97, v97, v98
	v_cvt_pk_bf16_f32 v98, v104, v101
	v_cvt_pk_bf16_f32 v99, v102, v99
	global_store_dwordx4 v[112:113], v[96:99], off offset:256 nt
	v_pk_mul_f32 v[88:89], v[88:89], v[146:147] op_sel_hi:[1,0]
	v_pk_mul_f32 v[92:93], v[92:93], v[146:147] op_sel_hi:[1,0]
	v_lshlrev_b64 v[96:97], 13, v[180:181]
	v_lshl_add_u64 v[96:97], s[60:61], 0, v[96:97]
	v_pk_mul_f32 v[90:91], v[90:91], v[146:147] op_sel_hi:[1,0]
	v_max_f32_e32 v88, 0, v88
	v_lshl_add_u64 v[96:97], v[96:97], 0, s[46:47]
	v_pk_mul_f32 v[94:95], v[94:95], v[146:147] op_sel_hi:[1,0]
	v_mul_f32_e32 v98, v88, v88
	v_max_f32_e32 v88, 0, v93
	v_max_f32_e32 v89, 0, v89
	v_max_f32_e32 v90, 0, v90
	v_lshl_add_u64 v[96:97], v[96:97], 0, s[76:77]
	v_max_f32_e32 v92, 0, v92
	v_mul_f32_e32 v88, v88, v88
	v_mul_f32_e32 v93, v89, v89
	v_max_f32_e32 v89, 0, v94
	v_mul_f32_e32 v94, v90, v90
	v_max_f32_e32 v90, 0, v95
	v_max_f32_e32 v91, 0, v91
	v_pk_mul_f32 v[80:81], v[80:81], v[146:147] op_sel_hi:[1,0]
	v_lshl_add_u64 v[96:97], v[96:97], 0, v[152:153]
	v_mul_f32_e32 v92, v92, v92
	v_mul_f32_e32 v89, v89, v89
	v_mul_f32_e32 v90, v90, v90
	v_mul_f32_e32 v91, v91, v91
	v_cvt_pk_bf16_f32 v88, v92, v88
	v_pk_mul_f32 v[86:87], v[86:87], v[146:147] op_sel_hi:[1,0]
	v_pk_mul_f32 v[84:85], v[84:85], v[146:147] op_sel_hi:[1,0]
	v_pk_mul_f32 v[82:83], v[82:83], v[146:147] op_sel_hi:[1,0]
	v_max_f32_e32 v80, 0, v80
	v_max_f32_e32 v81, 0, v81
	v_cvt_pk_bf16_f32 v89, v89, v90
; __device__ __forceinline__ unsigned cvt_pk_bf16(float lo, float hi) { unsigned r; asm volatile("v_cvt_pk_bf16_f32 %0, %1, %2" : "=v"(r) : "v"(lo), "v"(hi)); return r; }
;     __device__ __forceinline__ void operator()(const f32x4 (&acc)[2][2][4][2], const Unit& u, int wr, int wc, int fr, int fq) const {
;     ...
;                 const int r = row0 + ai * HALF + m * 16; const float rs = rsv[ai][m];
;                 bf16_t* rowp = H + (size_t)r * FF + u.pn * BM + wc * 32 + 8 * fq;
; #pragma unroll
;                 for (int bj = 0; bj < 2; ++bj) { f32x4 v0 = acc[ai][bj][m][0] * rs, v1 = acc[ai][bj][m][1] * rs;
; #pragma unroll
;                     for (int j = 0; j < 4; ++j) { const float a = fmaxf(v0[j], 0.f), b = fmaxf(v1[j], 0.f); v0[j] = a * a; v1[j] = b * b; }
;                     u32x4 w; w.x = cvt_pk_bf16(v0[0], v0[1]); w.y = cvt_pk_bf16(v0[2], v0[3]); w.z = cvt_pk_bf16(v1[0], v1[1]); w.w = cvt_pk_bf16(v1[2], v1[3]);
;                     *(u32x4*)(rowp + bj * HALF) = w; }
	v_cvt_pk_bf16_f32 v90, v98, v93
	v_cvt_pk_bf16_f32 v91, v94, v91
	global_store_dwordx4 v[96:97], v[88:91], off nt
	v_max_f32_e32 v82, 0, v82
	v_max_f32_e32 v84, 0, v84
	v_mul_f32_e32 v88, v80, v80
	v_max_f32_e32 v80, 0, v85
	v_mul_f32_e32 v85, v81, v81
	v_max_f32_e32 v81, 0, v86
	v_mul_f32_e32 v80, v80, v80
	v_mul_f32_e32 v81, v81, v81
	v_mul_f32_e32 v86, v82, v82
	v_max_f32_e32 v82, 0, v87
	v_max_f32_e32 v83, 0, v83
	v_mul_f32_e32 v84, v84, v84
	v_mul_f32_e32 v82, v82, v82
	v_mul_f32_e32 v83, v83, v83
	v_cvt_pk_bf16_f32 v80, v84, v80
	v_cvt_pk_bf16_f32 v81, v81, v82
	v_cvt_pk_bf16_f32 v82, v88, v85
	v_cvt_pk_bf16_f32 v83, v86, v83
	global_store_dwordx4 v[96:97], v[80:83], off offset:256 nt
	v_pk_mul_f32 v[72:73], v[72:73], v[144:145] op_sel_hi:[1,0]
	v_pk_mul_f32 v[76:77], v[76:77], v[144:145] op_sel_hi:[1,0]
	v_lshlrev_b64 v[80:81], 13, v[178:179]
	v_lshl_add_u64 v[80:81], s[60:61], 0, v[80:81]
	v_pk_mul_f32 v[74:75], v[74:75], v[144:145] op_sel_hi:[1,0]
	v_max_f32_e32 v72, 0, v72
	v_lshl_add_u64 v[80:81], v[80:81], 0, s[46:47]
	v_pk_mul_f32 v[78:79], v[78:79], v[144:145] op_sel_hi:[1,0]
	v_mul_f32_e32 v82, v72, v72
	v_max_f32_e32 v72, 0, v77
	v_max_f32_e32 v73, 0, v73
	v_max_f32_e32 v74, 0, v74
	v_lshl_add_u64 v[80:81], v[80:81], 0, s[76:77]
	v_max_f32_e32 v76, 0, v76
	v_mul_f32_e32 v72, v72, v72
	v_mul_f32_e32 v77, v73, v73
	v_max_f32_e32 v73, 0, v78
	v_mul_f32_e32 v78, v74, v74
	v_max_f32_e32 v74, 0, v79
	v_max_f32_e32 v75, 0, v75
	v_pk_mul_f32 v[64:65], v[64:65], v[144:145] op_sel_hi:[1,0]
	v_lshl_add_u64 v[80:81], v[80:81], 0, v[152:153]
	v_mul_f32_e32 v76, v76, v76
	v_mul_f32_e32 v73, v73, v73
	v_mul_f32_e32 v74, v74, v74
	v_mul_f32_e32 v75, v75, v75
	v_cvt_pk_bf16_f32 v72, v76, v72
	v_pk_mul_f32 v[70:71], v[70:71], v[144:145] op_sel_hi:[1,0]
	v_pk_mul_f32 v[68:69], v[68:69], v[144:145] op_sel_hi:[1,0]
	v_pk_mul_f32 v[66:67], v[66:67], v[144:145] op_sel_hi:[1,0]
	v_max_f32_e32 v64, 0, v64
	v_max_f32_e32 v65, 0, v65
	v_cvt_pk_bf16_f32 v73, v73, v74
	v_cvt_pk_bf16_f32 v74, v82, v77
	v_cvt_pk_bf16_f32 v75, v78, v75
	global_store_dwordx4 v[80:81], v[72:75], off nt
	v_max_f32_e32 v66, 0, v66
	v_max_f32_e32 v68, 0, v68
	v_mul_f32_e32 v72, v64, v64
	v_max_f32_e32 v64, 0, v69
	v_mul_f32_e32 v69, v65, v65
	v_max_f32_e32 v65, 0, v70
	v_mul_f32_e32 v64, v64, v64
	v_mul_f32_e32 v65, v65, v65
	v_mul_f32_e32 v70, v66, v66
	v_max_f32_e32 v66, 0, v71
	v_max_f32_e32 v67, 0, v67
	v_mul_f32_e32 v68, v68, v68
	v_mul_f32_e32 v66, v66, v66
	v_mul_f32_e32 v67, v67, v67
	v_cvt_pk_bf16_f32 v64, v68, v64
	v_cvt_pk_bf16_f32 v65, v65, v66
	v_cvt_pk_bf16_f32 v66, v72, v69
	v_cvt_pk_bf16_f32 v67, v70, v67
	global_store_dwordx4 v[80:81], v[64:67], off offset:256 nt
	v_pk_mul_f32 v[56:57], v[56:57], v[138:139] op_sel_hi:[1,0]
	v_pk_mul_f32 v[60:61], v[60:61], v[138:139] op_sel_hi:[1,0]
	v_lshlrev_b64 v[64:65], 13, v[132:133]
	v_lshl_add_u64 v[64:65], s[60:61], 0, v[64:65]
	v_pk_mul_f32 v[58:59], v[58:59], v[138:139] op_sel_hi:[1,0]
	v_max_f32_e32 v56, 0, v56
	v_lshl_add_u64 v[64:65], v[64:65], 0, s[46:47]
	v_pk_mul_f32 v[62:63], v[62:63], v[138:139] op_sel_hi:[1,0]
	v_mul_f32_e32 v66, v56, v56
	v_max_f32_e32 v56, 0, v61
	v_max_f32_e32 v57, 0, v57
	v_max_f32_e32 v58, 0, v58
	v_lshl_add_u64 v[64:65], v[64:65], 0, s[76:77]
	v_max_f32_e32 v60, 0, v60
	v_mul_f32_e32 v56, v56, v56
	v_mul_f32_e32 v61, v57, v57
	v_max_f32_e32 v57, 0, v62
	v_mul_f32_e32 v62, v58, v58
	v_max_f32_e32 v58, 0, v63
	v_max_f32_e32 v59, 0, v59
	v_pk_mul_f32 v[48:49], v[48:49], v[138:139] op_sel_hi:[1,0]
	v_lshl_add_u64 v[64:65], v[64:65], 0, v[152:153]
	v_mul_f32_e32 v60, v60, v60
	v_mul_f32_e32 v57, v57, v57
	v_mul_f32_e32 v58, v58, v58
	v_mul_f32_e32 v59, v59, v59
	v_cvt_pk_bf16_f32 v56, v60, v56
	v_pk_mul_f32 v[54:55], v[54:55], v[138:139] op_sel_hi:[1,0]
	v_pk_mul_f32 v[52:53], v[52:53], v[138:139] op_sel_hi:[1,0]
	v_pk_mul_f32 v[50:51], v[50:51], v[138:139] op_sel_hi:[1,0]
	v_max_f32_e32 v48, 0, v48
	v_max_f32_e32 v49, 0, v49
	v_cvt_pk_bf16_f32 v57, v57, v58
	v_cvt_pk_bf16_f32 v58, v66, v61
	v_cvt_pk_bf16_f32 v59, v62, v59
	global_store_dwordx4 v[64:65], v[56:59], off nt
	v_max_f32_e32 v50, 0, v50
	v_max_f32_e32 v52, 0, v52
	v_mul_f32_e32 v56, v48, v48
	v_max_f32_e32 v48, 0, v53
	v_mul_f32_e32 v53, v49, v49
	v_max_f32_e32 v49, 0, v54
	v_mul_f32_e32 v48, v48, v48
	v_mul_f32_e32 v49, v49, v49
	v_mul_f32_e32 v54, v50, v50
	v_max_f32_e32 v50, 0, v55
	v_max_f32_e32 v51, 0, v51
	v_mul_f32_e32 v52, v52, v52
	v_mul_f32_e32 v50, v50, v50
	v_mul_f32_e32 v51, v51, v51
	v_cvt_pk_bf16_f32 v48, v52, v48
	v_cvt_pk_bf16_f32 v49, v49, v50
	v_ashrrev_i32_e32 v177, 31, v176
	v_cvt_pk_bf16_f32 v50, v56, v53
	v_cvt_pk_bf16_f32 v51, v54, v51
	global_store_dwordx4 v[64:65], v[48:51], off offset:256 nt
	v_pk_mul_f32 v[40:41], v[40:41], v[136:137] op_sel_hi:[1,0]
	v_pk_mul_f32 v[44:45], v[44:45], v[136:137] op_sel_hi:[1,0]
	v_lshlrev_b64 v[48:49], 13, v[176:177]
	v_lshl_add_u64 v[48:49], s[60:61], 0, v[48:49]
	v_lshl_add_u64 v[48:49], v[48:49], 0, s[46:47]
	v_lshl_add_u64 v[48:49], v[48:49], 0, s[76:77]
	v_pk_mul_f32 v[42:43], v[42:43], v[136:137] op_sel_hi:[1,0]
	v_max_f32_e32 v40, 0, v40
	v_lshl_add_u64 v[48:49], v[48:49], 0, v[152:153]
	s_mov_b64 s[14:15], 0x20000
	v_pk_mul_f32 v[46:47], v[46:47], v[136:137] op_sel_hi:[1,0]
	v_max_f32_e32 v44, 0, v44
	v_mul_f32_e32 v52, v40, v40
	v_max_f32_e32 v40, 0, v45
	v_max_f32_e32 v41, 0, v41
	v_max_f32_e32 v42, 0, v42
	v_lshl_add_u64 v[50:51], v[48:49], 0, s[14:15]
; __device__ __forceinline__ unsigned cvt_pk_bf16(float lo, float hi) { unsigned r; asm volatile("v_cvt_pk_bf16_f32 %0, %1, %2" : "=v"(r) : "v"(lo), "v"(hi)); return r; }
; #define PG8_BAR __builtin_amdgcn_s_barrier()
; template <class Epi, class Sched, bool ALIGN_EPI = false, bool SP2 = false>
; __device__ __forceinline__ void gemm_phase(LAS unsigned char* lds, const Gemm g, const Sched& S, const Epi& E) {
;     ...
;         E(acc, cur, wr, wc, fr, fq); S.done(cur);
;         if (!has_next) break;
; #pragma unroll
;         for (int a = 0; a < 2; ++a)
; #pragma unroll
;             for (int b = 0; b < 2; ++b)
; #pragma unroll
;                 for (int m = 0; m < 4; ++m)
; #pragma unroll
;                     for (int n = 0; n < 2; ++n) acc[a][b][m][n] = (f32x4){0.f, 0.f, 0.f, 0.f};
;         cur = nxt; cA = nA; cB = nB; ++ui;
;         if constexpr (ALIGN_EPI) { if (wr == 1) PG8_BAR; }
;     __device__ __forceinline__ void operator()(const f32x4 (&acc)[2][2][4][2], const Unit& u, int wr, int wc, int fr, int fq) const {
;     ...
;         for (int ai = 0; ai < 2; ++ai)
; #pragma unroll
;             for (int m = 0; m < 4; ++m) {
;                 const int r = row0 + ai * HALF + m * 16; const float rs = rsv[ai][m];
;                 bf16_t* rowp = H + (size_t)r * FF + u.pn * BM + wc * 32 + 8 * fq;
; #pragma unroll
;                 for (int bj = 0; bj < 2; ++bj) { f32x4 v0 = acc[ai][bj][m][0] * rs, v1 = acc[ai][bj][m][1] * rs;
; #pragma unroll
;                     for (int j = 0; j < 4; ++j) { const float a = fmaxf(v0[j], 0.f), b = fmaxf(v1[j], 0.f); v0[j] = a * a; v1[j] = b * b; }
;                     u32x4 w; w.x = cvt_pk_bf16(v0[0], v0[1]); w.y = cvt_pk_bf16(v0[2], v0[3]); w.z = cvt_pk_bf16(v1[0], v1[1]); w.w = cvt_pk_bf16(v1[2], v1[3]);
;                     *(u32x4*)(rowp + bj * HALF) = w; }
	v_mul_f32_e32 v44, v44, v44
	v_mul_f32_e32 v40, v40, v40
	v_mul_f32_e32 v45, v41, v41
	v_max_f32_e32 v41, 0, v46
	v_mul_f32_e32 v46, v42, v42
	v_max_f32_e32 v42, 0, v47
	s_mov_b32 s14, 0x20000
	v_mul_f32_e32 v41, v41, v41
	v_max_f32_e32 v43, 0, v43
	v_mul_f32_e32 v42, v42, v42
	v_cvt_pk_bf16_f32 v40, v44, v40
	v_add_co_u32_e32 v44, vcc, s14, v48
	v_pk_mul_f32 v[34:35], v[34:35], v[136:137] op_sel_hi:[1,0]
	v_pk_mul_f32 v[32:33], v[32:33], v[136:137] op_sel_hi:[1,0]
	v_mul_f32_e32 v43, v43, v43
	v_cvt_pk_bf16_f32 v41, v41, v42
	v_cvt_pk_bf16_f32 v42, v52, v45
	v_addc_co_u32_e32 v45, vcc, 0, v49, vcc
	v_pk_mul_f32 v[38:39], v[38:39], v[136:137] op_sel_hi:[1,0]
	v_pk_mul_f32 v[36:37], v[36:37], v[136:137] op_sel_hi:[1,0]
	v_max_f32_e32 v32, 0, v32
	v_max_f32_e32 v33, 0, v33
	v_max_f32_e32 v34, 0, v34
	v_cvt_pk_bf16_f32 v43, v46, v43
	global_store_dwordx4 v[44:45], v[40:43], off nt
	v_max_f32_e32 v36, 0, v36
	v_max_f32_e32 v35, 0, v35
	v_mul_f32_e32 v40, v32, v32
	v_max_f32_e32 v32, 0, v37
	v_mul_f32_e32 v37, v33, v33
	v_max_f32_e32 v33, 0, v38
	v_mul_f32_e32 v38, v34, v34
	v_max_f32_e32 v34, 0, v39
	v_mul_f32_e32 v32, v32, v32
	v_mul_f32_e32 v33, v33, v33
	v_mul_f32_e32 v34, v34, v34
	v_pk_mul_f32 v[24:25], v[24:25], v[130:131] op_sel_hi:[1,0]
	v_mul_f32_e32 v36, v36, v36
	v_mul_f32_e32 v35, v35, v35
	v_cvt_pk_bf16_f32 v32, v36, v32
	v_cvt_pk_bf16_f32 v33, v33, v34
	v_cvt_pk_bf16_f32 v34, v40, v37
	v_pk_mul_f32 v[28:29], v[28:29], v[130:131] op_sel_hi:[1,0]
	v_pk_mul_f32 v[26:27], v[26:27], v[130:131] op_sel_hi:[1,0]
	v_max_f32_e32 v24, 0, v24
	v_cvt_pk_bf16_f32 v35, v38, v35
	global_store_dwordx4 v[50:51], v[32:35], off offset:256 nt
	s_mov_b64 s[14:15], 0x40000
	v_pk_mul_f32 v[30:31], v[30:31], v[130:131] op_sel_hi:[1,0]
	v_max_f32_e32 v28, 0, v28
	v_mul_f32_e32 v34, v24, v24
	v_max_f32_e32 v24, 0, v29
	v_max_f32_e32 v25, 0, v25
	v_max_f32_e32 v26, 0, v26
	v_lshl_add_u64 v[32:33], v[48:49], 0, s[14:15]
	v_mul_f32_e32 v28, v28, v28
	v_mul_f32_e32 v24, v24, v24
	v_mul_f32_e32 v29, v25, v25
	v_max_f32_e32 v25, 0, v30
	v_mul_f32_e32 v30, v26, v26
	v_max_f32_e32 v26, 0, v31
	s_mov_b32 s14, 0x40000
	v_mul_f32_e32 v25, v25, v25
	v_max_f32_e32 v27, 0, v27
	v_mul_f32_e32 v26, v26, v26
	v_cvt_pk_bf16_f32 v24, v28, v24
	v_add_co_u32_e32 v28, vcc, s14, v48
	v_pk_mul_f32 v[18:19], v[18:19], v[130:131] op_sel_hi:[1,0]
	v_pk_mul_f32 v[16:17], v[16:17], v[130:131] op_sel_hi:[1,0]
	v_mul_f32_e32 v27, v27, v27
	v_cvt_pk_bf16_f32 v25, v25, v26
	v_cvt_pk_bf16_f32 v26, v34, v29
	v_addc_co_u32_e32 v29, vcc, 0, v49, vcc
	v_pk_mul_f32 v[22:23], v[22:23], v[130:131] op_sel_hi:[1,0]
	v_pk_mul_f32 v[20:21], v[20:21], v[130:131] op_sel_hi:[1,0]
	v_max_f32_e32 v16, 0, v16
	v_max_f32_e32 v17, 0, v17
	v_max_f32_e32 v18, 0, v18
	v_cvt_pk_bf16_f32 v27, v30, v27
	global_store_dwordx4 v[28:29], v[24:27], off nt
	v_max_f32_e32 v20, 0, v20
	v_max_f32_e32 v19, 0, v19
	v_mul_f32_e32 v24, v16, v16
	v_max_f32_e32 v16, 0, v21
	v_mul_f32_e32 v21, v17, v17
	v_max_f32_e32 v17, 0, v22
	v_mul_f32_e32 v22, v18, v18
	v_max_f32_e32 v18, 0, v23
	v_mul_f32_e32 v16, v16, v16
	v_mul_f32_e32 v17, v17, v17
	v_mul_f32_e32 v18, v18, v18
	v_pk_mul_f32 v[8:9], v[8:9], v[128:129] op_sel_hi:[1,0]
	v_mul_f32_e32 v20, v20, v20
	v_mul_f32_e32 v19, v19, v19
	v_cvt_pk_bf16_f32 v16, v20, v16
	v_cvt_pk_bf16_f32 v17, v17, v18
	v_cvt_pk_bf16_f32 v18, v24, v21
	v_pk_mul_f32 v[12:13], v[12:13], v[128:129] op_sel_hi:[1,0]
	v_pk_mul_f32 v[10:11], v[10:11], v[128:129] op_sel_hi:[1,0]
	v_max_f32_e32 v8, 0, v8
	v_cvt_pk_bf16_f32 v19, v22, v19
	global_store_dwordx4 v[32:33], v[16:19], off offset:256 nt
	s_mov_b64 s[14:15], 0x60000
	v_pk_mul_f32 v[14:15], v[14:15], v[128:129] op_sel_hi:[1,0]
	v_max_f32_e32 v12, 0, v12
	v_mul_f32_e32 v18, v8, v8
	v_max_f32_e32 v8, 0, v13
	v_max_f32_e32 v9, 0, v9
	v_max_f32_e32 v10, 0, v10
	v_lshl_add_u64 v[16:17], v[48:49], 0, s[14:15]
	v_mul_f32_e32 v12, v12, v12
	v_mul_f32_e32 v8, v8, v8
	v_mul_f32_e32 v13, v9, v9
	v_max_f32_e32 v9, 0, v14
	v_mul_f32_e32 v14, v10, v10
	v_max_f32_e32 v10, 0, v15
	s_mov_b32 s14, 0x60000
	v_mul_f32_e32 v9, v9, v9
	v_max_f32_e32 v11, 0, v11
	v_mul_f32_e32 v10, v10, v10
	v_cvt_pk_bf16_f32 v8, v12, v8
	v_add_co_u32_e32 v12, vcc, s14, v48
	v_pk_mul_f32 v[2:3], v[2:3], v[128:129] op_sel_hi:[1,0]
	v_pk_mul_f32 v[0:1], v[0:1], v[128:129] op_sel_hi:[1,0]
	v_mul_f32_e32 v11, v11, v11
	v_cvt_pk_bf16_f32 v9, v9, v10
	v_cvt_pk_bf16_f32 v10, v18, v13
	v_addc_co_u32_e32 v13, vcc, 0, v49, vcc
	v_pk_mul_f32 v[6:7], v[6:7], v[128:129] op_sel_hi:[1,0]
	v_pk_mul_f32 v[4:5], v[4:5], v[128:129] op_sel_hi:[1,0]
	v_max_f32_e32 v0, 0, v0
	v_max_f32_e32 v1, 0, v1
	v_max_f32_e32 v2, 0, v2
	v_cvt_pk_bf16_f32 v11, v14, v11
	global_store_dwordx4 v[12:13], v[8:11], off nt
	v_max_f32_e32 v3, 0, v3
	v_max_f32_e32 v4, 0, v4
	v_mul_f32_e32 v8, v0, v0
	v_max_f32_e32 v0, 0, v5
	v_mul_f32_e32 v5, v1, v1
	v_max_f32_e32 v1, 0, v6
	v_mul_f32_e32 v6, v2, v2
	v_max_f32_e32 v2, 0, v7
	v_mul_f32_e32 v0, v0, v0
	v_mul_f32_e32 v1, v1, v1
	v_mul_f32_e32 v2, v2, v2
	v_mul_f32_e32 v3, v3, v3
	s_andn2_b64 vcc, exec, s[44:45]
	s_mov_b64 s[44:45], -1
	v_mul_f32_e32 v4, v4, v4
	v_cvt_pk_bf16_f32 v0, v4, v0
	v_cvt_pk_bf16_f32 v1, v1, v2
	v_cvt_pk_bf16_f32 v2, v8, v5
	v_cvt_pk_bf16_f32 v3, v6, v3
	global_store_dwordx4 v[16:17], v[0:3], off offset:256 nt
	s_cbranch_vccnz .LBB0_526
	s_andn2_b64 vcc, exec, s[26:27]
	s_cbranch_vccnz .LBB0_525
	s_barrier
	s_branch .LBB0_525

; __device__ __forceinline__ unsigned cvt_pk_bf16(float lo, float hi) { unsigned r; asm volatile("v_cvt_pk_bf16_f32 %0, %1, %2" : "=v"(r) : "v"(lo), "v"(hi)); return r; }
; __device__ __forceinline__ float bflo(unsigned w) { return __uint_as_float(w << 16); }
; __device__ __forceinline__ float bfhi(unsigned w) { return __uint_as_float(w & 0xffff0000u); }
; template <bool RD32>
; __device__ __forceinline__ void res_rows(const float* __restrict__ xold32, const bf16_t* __restrict__ xoldb, bf16_t* __restrict__ xb, float* __restrict__ ssq, const f32x4 (&acc)[2][2][4][2], int row0, int col0, int slot) {
;     ...
;     auto ld = [&](size_t o, f32x4& a, f32x4& b) { if (RD32) { a = *(const f32x4*)(xold32 + o); b = *(const f32x4*)(xold32 + o + 4); }
;         else { const u32x4 w = *(const u32x4*)(xoldb + o); a = (f32x4){bflo(w.x), bfhi(w.x), bflo(w.y), bfhi(w.y)}; b = (f32x4){bflo(w.z), bfhi(w.z), bflo(w.w), bfhi(w.w)}; } };
; #pragma unroll
;     for (int bj = 0; bj < 2; ++bj) ld((size_t)row0 * D + col0 + bj * HALF, xo[0][bj][0], xo[0][bj][1]);
; #pragma unroll
;     for (int idx = 0; idx < 8; ++idx) {
;         const int ai = idx >> 2, m = idx & 3; const int r = row0 + ai * HALF + m * 16; const size_t off = (size_t)r * D + col0;
;         if (idx < 7) { const int ai2 = (idx + 1) >> 2, m2 = (idx + 1) & 3; const size_t off2 = (size_t)(row0 + ai2 * HALF + m2 * 16) * D + col0;
; #pragma unroll
;             for (int bj = 0; bj < 2; ++bj) ld(off2 + bj * HALF, xo[(idx + 1) & 1][bj][0], xo[(idx + 1) & 1][bj][1]); }
;         float ss = 0.f;
; #pragma unroll
;         for (int bj = 0; bj < 2; ++bj) { const f32x4 x0 = xo[idx & 1][bj][0] + acc[ai][bj][m][0], x1 = xo[idx & 1][bj][1] + acc[ai][bj][m][1];
;             u32x4 w; w.x = cvt_pk_bf16(x0[0], x0[1]); w.y = cvt_pk_bf16(x0[2], x0[3]); w.z = cvt_pk_bf16(x1[0], x1[1]); w.w = cvt_pk_bf16(x1[2], x1[3]);
;             *(u32x4*)(xb + off + bj * HALF) = w;
;             ss += ((x0[0] * x0[0] + x0[1] * x0[1]) + (x0[2] * x0[2] + x0[3] * x0[3])) + ((x1[0] * x1[0] + x1[1] * x1[1]) + (x1[2] * x1[2] + x1[3] * x1[3])); }
;         ss += __shfl_xor(ss, 16); ss += __shfl_xor(ss, 32);
.LBB0_615:
	v_lshl_add_u32 v164, s51, 8, v174
	v_lshl_or_b32 v128, s50, 8, v176
	v_ashrrev_i32_e32 v165, 31, v164
	v_ashrrev_i32_e32 v129, 31, v128
	v_lshlrev_b64 v[166:167], 11, v[164:165]
	v_lshl_add_u64 v[130:131], s[58:59], 0, v[166:167]
	v_lshlrev_b64 v[128:129], 1, v[128:129]
	v_lshl_add_u64 v[130:131], v[130:131], 0, v[128:129]
	global_load_dwordx4 v[136:139], v[130:131], off
	global_load_dwordx4 v[140:143], v[130:131], off offset:256
	v_or_b32_e32 v130, 16, v164
	v_ashrrev_i32_e32 v131, 31, v130
	v_lshl_add_u64 v[168:169], s[58:59], 0, v[128:129]
	v_lshlrev_b64 v[128:129], 11, v[130:131]
	v_lshl_add_u64 v[170:171], v[168:169], 0, v[128:129]
	global_load_dwordx4 v[128:131], v[170:171], off
	global_load_dwordx4 v[132:135], v[170:171], off offset:256
	v_and_b32_e32 v172, 64, v209
	v_xor_b32_e32 v173, 16, v209
	v_add_u32_e32 v194, 64, v172
	v_or_b32_e32 v172, 32, v164
	v_or_b32_e32 v182, 48, v164
	v_cmp_lt_i32_e32 vcc, v173, v194
	v_ashrrev_i32_e32 v183, 31, v182
	v_lshlrev_b64 v[182:183], 11, v[182:183]
	v_cndmask_b32_e32 v180, v209, v173, vcc
	v_ashrrev_i32_e32 v173, 31, v172
	v_lshlrev_b64 v[172:173], 11, v[172:173]
	v_lshl_add_u64 v[166:167], v[168:169], 0, v[166:167]
	v_lshl_add_u64 v[172:173], v[168:169], 0, v[172:173]
	v_lshl_add_u64 v[168:169], v[168:169], 0, v[182:183]
	v_lshlrev_b32_e32 v180, 2, v180
	s_mov_b32 s14, 0x40000
	v_xor_b32_e32 v181, 32, v209
	s_lshl_b32 s29, s50, 2
	v_or_b32_e32 v179, s29, v177
	s_waitcnt vmcnt(0)
	v_lshlrev_b32_e32 v182, 16, v136
	v_and_b32_e32 v183, 0xffff0000, v136
	v_lshlrev_b32_e32 v136, 16, v137
	v_and_b32_e32 v137, 0xffff0000, v137
	v_lshlrev_b32_e32 v184, 16, v138
	v_and_b32_e32 v185, 0xffff0000, v138
	v_lshlrev_b32_e32 v138, 16, v139
	v_and_b32_e32 v139, 0xffff0000, v139
	v_lshlrev_b32_e32 v188, 16, v142
	v_and_b32_e32 v189, 0xffff0000, v142
	v_lshlrev_b32_e32 v142, 16, v143
	v_and_b32_e32 v143, 0xffff0000, v143
	v_lshlrev_b32_e32 v186, 16, v140
	v_and_b32_e32 v187, 0xffff0000, v140
	v_lshlrev_b32_e32 v140, 16, v141
	v_and_b32_e32 v141, 0xffff0000, v141
	v_pk_add_f32 v[126:127], v[126:127], v[136:137]
	v_pk_add_f32 v[124:125], v[124:125], v[182:183]
	v_pk_add_f32 v[136:137], v[122:123], v[138:139]
	v_pk_add_f32 v[138:139], v[120:121], v[184:185]
	v_pk_add_f32 v[142:143], v[110:111], v[142:143]
	v_pk_add_f32 v[184:185], v[108:109], v[188:189]
	v_cvt_pk_bf16_f32 v108, v124, v125
	v_cvt_pk_bf16_f32 v109, v126, v127
	v_cvt_pk_bf16_f32 v110, v138, v139
	v_cvt_pk_bf16_f32 v111, v136, v137
	v_pk_add_f32 v[140:141], v[118:119], v[140:141]
	v_pk_add_f32 v[182:183], v[116:117], v[186:187]
	global_store_dwordx4 v[166:167], v[108:111], off nt
	v_lshlrev_b32_e32 v190, 16, v128
	v_and_b32_e32 v191, 0xffff0000, v128
	v_cvt_pk_bf16_f32 v108, v182, v183
	v_cvt_pk_bf16_f32 v109, v140, v141
	v_cvt_pk_bf16_f32 v110, v184, v185
	v_cvt_pk_bf16_f32 v111, v142, v143
	global_load_dwordx4 v[116:119], v[172:173], off
	global_load_dwordx4 v[120:123], v[172:173], off offset:256
	v_lshlrev_b32_e32 v128, 16, v129
	v_and_b32_e32 v129, 0xffff0000, v129
	v_lshlrev_b32_e32 v186, 16, v130
	v_and_b32_e32 v187, 0xffff0000, v130
	v_lshlrev_b32_e32 v130, 16, v131
	v_and_b32_e32 v131, 0xffff0000, v131
	v_lshlrev_b32_e32 v188, 16, v132
	v_and_b32_e32 v189, 0xffff0000, v132
	v_lshlrev_b32_e32 v192, 16, v134
	v_and_b32_e32 v193, 0xffff0000, v134
	v_lshlrev_b32_e32 v134, 16, v135
	v_and_b32_e32 v135, 0xffff0000, v135
	v_lshlrev_b32_e32 v132, 16, v133
	v_and_b32_e32 v133, 0xffff0000, v133
	v_pk_add_f32 v[114:115], v[114:115], v[128:129]
	v_pk_add_f32 v[112:113], v[112:113], v[190:191]
	v_pk_add_f32 v[128:129], v[106:107], v[130:131]
	v_pk_add_f32 v[130:131], v[104:105], v[186:187]
	v_pk_add_f32 v[186:187], v[100:101], v[188:189]
	v_pk_add_f32 v[134:135], v[98:99], v[134:135]
	v_pk_add_f32 v[188:189], v[96:97], v[192:193]
	global_store_dwordx4 v[166:167], v[108:111], off offset:256 nt
	v_cvt_pk_bf16_f32 v96, v112, v113
	v_cvt_pk_bf16_f32 v97, v114, v115
	v_cvt_pk_bf16_f32 v98, v130, v131
	v_cvt_pk_bf16_f32 v99, v128, v129
	v_pk_add_f32 v[132:133], v[102:103], v[132:133]
	global_store_dwordx4 v[170:171], v[96:99], off nt
	v_mul_f32_e32 v125, v125, v125
	v_mul_f32_e32 v127, v127, v127
	v_cvt_pk_bf16_f32 v96, v186, v187
	v_cvt_pk_bf16_f32 v97, v132, v133
	v_cvt_pk_bf16_f32 v98, v188, v189
	v_cvt_pk_bf16_f32 v99, v134, v135
	global_load_dwordx4 v[100:103], v[168:169], off
	global_load_dwordx4 v[104:107], v[168:169], off offset:256
	v_mul_f32_e32 v139, v139, v139
	v_mul_f32_e32 v137, v137, v137
	v_mul_f32_e32 v183, v183, v183
	v_mul_f32_e32 v141, v141, v141
	v_mul_f32_e32 v185, v185, v185
	v_mul_f32_e32 v143, v143, v143
	v_fmac_f32_e32 v125, v124, v124
	v_fmac_f32_e32 v127, v126, v126
	v_fmac_f32_e32 v139, v138, v138
	v_fmac_f32_e32 v137, v136, v136
	v_fmac_f32_e32 v183, v182, v182
	v_fmac_f32_e32 v141, v140, v140
	v_fmac_f32_e32 v185, v184, v184
	v_fmac_f32_e32 v143, v142, v142
	v_add_f32_e32 v108, v125, v127
	v_add_f32_e32 v109, v139, v137
	v_add_f32_e32 v110, v183, v141
	v_add_f32_e32 v111, v185, v143
	v_add_f32_e32 v108, v108, v109
	v_add_f32_e32 v109, v110, v111
	v_mul_f32_e32 v190, v113, v113
	v_mul_f32_e32 v191, v115, v115
	v_mul_f32_e32 v192, v131, v131
	v_mul_f32_e32 v193, v129, v129
	v_add_f32_e32 v108, v108, v109
	v_fmac_f32_e32 v190, v112, v112
	v_fmac_f32_e32 v191, v114, v114
	v_fmac_f32_e32 v192, v130, v130
	v_fmac_f32_e32 v193, v128, v128
	ds_bpermute_b32 v109, v180, v108
	v_add_f32_e32 v112, v190, v191
	v_add_f32_e32 v110, v192, v193
	v_add_f32_e32 v127, v112, v110
	v_mul_f32_e32 v195, v187, v187
	v_mul_f32_e32 v196, v133, v133
	v_mul_f32_e32 v197, v189, v189
	v_fmac_f32_e32 v195, v186, v186
	v_fmac_f32_e32 v196, v132, v132
	v_fmac_f32_e32 v197, v188, v188
	v_add_f32_e32 v126, v195, v196
	global_store_dwordx4 v[170:171], v[96:99], off offset:256 nt
	s_waitcnt vmcnt(6)
; __device__ __forceinline__ unsigned cvt_pk_bf16(float lo, float hi) { unsigned r; asm volatile("v_cvt_pk_bf16_f32 %0, %1, %2" : "=v"(r) : "v"(lo), "v"(hi)); return r; }
; template <bool RD32>
; __device__ __forceinline__ void res_rows(const float* __restrict__ xold32, const bf16_t* __restrict__ xoldb, bf16_t* __restrict__ xb, float* __restrict__ ssq, const f32x4 (&acc)[2][2][4][2], int row0, int col0, int slot) {
;     ...
;     for (int idx = 0; idx < 8; ++idx) {
;         const int ai = idx >> 2, m = idx & 3; const int r = row0 + ai * HALF + m * 16; const size_t off = (size_t)r * D + col0;
;         if (idx < 7) { const int ai2 = (idx + 1) >> 2, m2 = (idx + 1) & 3; const size_t off2 = (size_t)(row0 + ai2 * HALF + m2 * 16) * D + col0;
; #pragma unroll
;             for (int bj = 0; bj < 2; ++bj) ld(off2 + bj * HALF, xo[(idx + 1) & 1][bj][0], xo[(idx + 1) & 1][bj][1]); }
;         float ss = 0.f;
; #pragma unroll
;         for (int bj = 0; bj < 2; ++bj) { const f32x4 x0 = xo[idx & 1][bj][0] + acc[ai][bj][m][0], x1 = xo[idx & 1][bj][1] + acc[ai][bj][m][1];
;             u32x4 w; w.x = cvt_pk_bf16(x0[0], x0[1]); w.y = cvt_pk_bf16(x0[2], x0[3]); w.z = cvt_pk_bf16(x1[0], x1[1]); w.w = cvt_pk_bf16(x1[2], x1[3]);
;             *(u32x4*)(xb + off + bj * HALF) = w;
;             ss += ((x0[0] * x0[0] + x0[1] * x0[1]) + (x0[2] * x0[2] + x0[3] * x0[3])) + ((x1[0] * x1[0] + x1[1] * x1[1]) + (x1[2] * x1[2] + x1[3] * x1[3])); }
;         ss += __shfl_xor(ss, 16); ss += __shfl_xor(ss, 32);
;         ssv[idx] = ss;
	v_lshlrev_b32_e32 v110, 16, v118
	v_and_b32_e32 v111, 0xffff0000, v118
	v_lshlrev_b32_e32 v112, 16, v119
	v_and_b32_e32 v113, 0xffff0000, v119
	s_waitcnt vmcnt(5)
	v_lshlrev_b32_e32 v118, 16, v122
	v_and_b32_e32 v119, 0xffff0000, v122
	v_pk_add_f32 v[118:119], v[80:81], v[118:119]
	v_mul_f32_e32 v80, v135, v135
	v_fmac_f32_e32 v80, v134, v134
	s_waitcnt lgkmcnt(0)
	v_add_f32_e32 v96, v108, v109
	v_lshlrev_b32_e32 v98, 16, v116
	v_and_b32_e32 v99, 0xffff0000, v116
	v_lshlrev_b32_e32 v108, 16, v117
	v_and_b32_e32 v109, 0xffff0000, v117
	v_lshlrev_b32_e32 v114, 16, v120
	v_and_b32_e32 v115, 0xffff0000, v120
	v_lshlrev_b32_e32 v116, 16, v121
	v_and_b32_e32 v117, 0xffff0000, v121
	v_lshlrev_b32_e32 v120, 16, v123
	v_and_b32_e32 v121, 0xffff0000, v123
	v_add_f32_e32 v80, v197, v80
	v_pk_add_f32 v[120:121], v[82:83], v[120:121]
	v_add_co_u32_e32 v82, vcc, s14, v166
	v_add_f32_e32 v80, v126, v80
	s_mov_b64 s[14:15], 0x40000
	v_pk_add_f32 v[122:123], v[94:95], v[108:109]
	v_pk_add_f32 v[98:99], v[92:93], v[98:99]
	v_pk_add_f32 v[90:91], v[90:91], v[112:113]
	v_pk_add_f32 v[88:89], v[88:89], v[110:111]
	v_cvt_pk_bf16_f32 v92, v98, v99
	v_cvt_pk_bf16_f32 v93, v122, v123
	v_pk_add_f32 v[124:125], v[84:85], v[114:115]
	v_cvt_pk_bf16_f32 v94, v88, v89
	v_cvt_pk_bf16_f32 v95, v90, v91
	v_addc_co_u32_e32 v83, vcc, 0, v167, vcc
	v_add_f32_e32 v84, v127, v80
	v_lshl_add_u64 v[80:81], v[166:167], 0, s[14:15]
	global_store_dwordx4 v[172:173], v[92:95], off nt
	v_pk_add_f32 v[116:117], v[86:87], v[116:117]
	v_mul_f32_e32 v97, v99, v99
	v_cvt_pk_bf16_f32 v92, v124, v125
	v_cvt_pk_bf16_f32 v93, v116, v117
	v_cvt_pk_bf16_f32 v94, v118, v119
	v_cvt_pk_bf16_f32 v95, v120, v121
	global_load_dwordx4 v[108:111], v[82:83], off
	global_load_dwordx4 v[112:115], v[80:81], off offset:256
	s_waitcnt vmcnt(4)
	v_lshlrev_b32_e32 v132, 16, v106
	v_and_b32_e32 v133, 0xffff0000, v106
	v_fmac_f32_e32 v97, v98, v98
	v_mul_f32_e32 v98, v123, v123
	v_fmac_f32_e32 v98, v122, v122
	v_mul_f32_e32 v89, v89, v89
	v_pk_add_f32 v[122:123], v[64:65], v[132:133]
	v_mul_f32_e32 v64, v91, v91
	v_cmp_lt_i32_e32 vcc, v181, v194
	v_lshlrev_b32_e32 v106, 16, v107
	v_and_b32_e32 v107, 0xffff0000, v107
	s_mov_b32 s14, 0x48000
	v_fmac_f32_e32 v89, v88, v88
	v_fmac_f32_e32 v64, v90, v90
	v_cndmask_b32_e32 v85, v209, v181, vcc
	v_lshlrev_b32_e32 v126, 16, v100
	v_and_b32_e32 v127, 0xffff0000, v100
	v_lshlrev_b32_e32 v100, 16, v101
	v_and_b32_e32 v101, 0xffff0000, v101
	v_lshlrev_b32_e32 v128, 16, v102
	v_and_b32_e32 v129, 0xffff0000, v102
	v_lshlrev_b32_e32 v102, 16, v103
	v_and_b32_e32 v103, 0xffff0000, v103
	v_add_f32_e32 v97, v97, v98
	v_pk_add_f32 v[106:107], v[66:67], v[106:107]
	v_add_co_u32_e32 v66, vcc, s14, v166
	v_add_f32_e32 v64, v89, v64
	s_mov_b64 s[14:15], 0x48000
	v_lshlrev_b32_e32 v130, 16, v104
	v_and_b32_e32 v131, 0xffff0000, v104
	v_lshlrev_b32_e32 v104, 16, v105
	v_and_b32_e32 v105, 0xffff0000, v105
	global_store_dwordx4 v[172:173], v[92:95], off offset:256 nt
	v_pk_add_f32 v[98:99], v[74:75], v[102:103]
	v_addc_co_u32_e32 v67, vcc, 0, v167, vcc
	v_pk_add_f32 v[92:93], v[78:79], v[100:101]
	v_pk_add_f32 v[94:95], v[76:77], v[126:127]
	v_pk_add_f32 v[100:101], v[72:73], v[128:129]
	v_cvt_pk_bf16_f32 v72, v94, v95
	v_cvt_pk_bf16_f32 v73, v92, v93
	v_add_f32_e32 v88, v97, v64
	v_cvt_pk_bf16_f32 v74, v100, v101
	v_cvt_pk_bf16_f32 v75, v98, v99
	v_lshl_add_u64 v[64:65], v[166:167], 0, s[14:15]
	global_store_dwordx4 v[168:169], v[72:75], off nt
	v_pk_add_f32 v[102:103], v[70:71], v[104:105]
	v_pk_add_f32 v[104:105], v[68:69], v[130:131]
	v_mul_f32_e32 v89, v125, v125
	v_cvt_pk_bf16_f32 v68, v104, v105
	v_cvt_pk_bf16_f32 v69, v102, v103
	v_cvt_pk_bf16_f32 v70, v122, v123
	v_cvt_pk_bf16_f32 v71, v106, v107
	global_load_dwordx4 v[72:75], v[66:67], off
	global_load_dwordx4 v[76:79], v[64:65], off offset:256
	v_mul_f32_e32 v90, v117, v117
	v_fmac_f32_e32 v89, v124, v124
	v_fmac_f32_e32 v90, v116, v116
	v_add_f32_e32 v89, v89, v90
	v_mul_f32_e32 v90, v119, v119
	v_mul_f32_e32 v91, v121, v121
	v_mul_f32_e32 v95, v95, v95
	v_mul_f32_e32 v93, v93, v93
	v_fmac_f32_e32 v90, v118, v118
	v_fmac_f32_e32 v91, v120, v120
	v_fmac_f32_e32 v95, v94, v94
	v_fmac_f32_e32 v93, v92, v92
	v_add_f32_e32 v90, v90, v91
	v_add_f32_e32 v92, v95, v93
	v_mul_f32_e32 v93, v101, v101
	v_mul_f32_e32 v94, v99, v99
	v_add_f32_e32 v89, v89, v90
	v_fmac_f32_e32 v93, v100, v100
	v_fmac_f32_e32 v94, v98, v98
	global_store_dwordx4 v[168:169], v[68:71], off offset:256 nt
	s_mov_b32 s14, 0x50000
	v_add_f32_e32 v97, v88, v89
	v_mul_f32_e32 v68, v105, v105
	s_waitcnt vmcnt(5)
	v_lshlrev_b32_e32 v118, 16, v114
	v_and_b32_e32 v119, 0xffff0000, v114
	v_lshlrev_b32_e32 v114, 16, v115
	v_and_b32_e32 v115, 0xffff0000, v115
	v_mul_f32_e32 v69, v103, v103
	v_lshlrev_b32_e32 v88, 16, v108
	v_and_b32_e32 v89, 0xffff0000, v108
	v_lshlrev_b32_e32 v90, 16, v109
	v_and_b32_e32 v91, 0xffff0000, v109
	v_lshlrev_b32_e32 v108, 16, v110
	v_and_b32_e32 v109, 0xffff0000, v110
	v_lshlrev_b32_e32 v110, 16, v111
	v_and_b32_e32 v111, 0xffff0000, v111
	v_add_f32_e32 v93, v93, v94
	v_fmac_f32_e32 v68, v104, v104
	v_fmac_f32_e32 v69, v102, v102
	v_pk_add_f32 v[94:95], v[50:51], v[114:115]
	v_add_co_u32_e32 v50, vcc, s14, v166
	v_lshlrev_b32_e32 v116, 16, v112
	v_and_b32_e32 v117, 0xffff0000, v112
	v_lshlrev_b32_e32 v112, 16, v113
	v_and_b32_e32 v113, 0xffff0000, v113
	v_add_f32_e32 v124, v68, v69
	v_pk_add_f32 v[62:63], v[62:63], v[90:91]
	v_pk_add_f32 v[60:61], v[60:61], v[88:89]
	v_pk_add_f32 v[58:59], v[58:59], v[110:111]
	v_pk_add_f32 v[56:57], v[56:57], v[108:109]
	v_cvt_pk_bf16_f32 v68, v60, v61
	v_cvt_pk_bf16_f32 v69, v62, v63
	v_addc_co_u32_e32 v51, vcc, 0, v167, vcc
	v_cvt_pk_bf16_f32 v70, v56, v57
	v_cvt_pk_bf16_f32 v71, v58, v59
	v_add_f32_e32 v121, v92, v93
	global_store_dwordx4 v[82:83], v[68:71], off nt
	v_pk_add_f32 v[82:83], v[54:55], v[112:113]
	v_pk_add_f32 v[92:93], v[52:53], v[116:117]
	v_pk_add_f32 v[98:99], v[48:49], v[118:119]
	v_cvt_pk_bf16_f32 v52, v92, v93
	v_cvt_pk_bf16_f32 v53, v82, v83
	s_mov_b64 s[14:15], 0x50000
	v_cvt_pk_bf16_f32 v54, v98, v99
	v_cvt_pk_bf16_f32 v55, v94, v95
	global_load_dwordx4 v[68:71], v[50:51], off
	v_lshl_add_u64 v[48:49], v[166:167], 0, s[14:15]
	global_load_dwordx4 v[88:91], v[48:49], off offset:256
	s_mov_b32 s14, 0x58000
	v_mul_f32_e32 v108, v107, v107
	v_fmac_f32_e32 v108, v106, v106
	global_store_dwordx4 v[80:81], v[52:55], off offset:256 nt
	v_mul_f32_e32 v123, v123, v123
	v_fmac_f32_e32 v123, v122, v122
	ds_bpermute_b32 v86, v180, v84
	ds_bpermute_b32 v120, v180, v97
	s_waitcnt vmcnt(6)
; __device__ __forceinline__ unsigned cvt_pk_bf16(float lo, float hi) { unsigned r; asm volatile("v_cvt_pk_bf16_f32 %0, %1, %2" : "=v"(r) : "v"(lo), "v"(hi)); return r; }
; template <bool RD32>
; __device__ __forceinline__ void res_rows(const float* __restrict__ xold32, const bf16_t* __restrict__ xoldb, bf16_t* __restrict__ xb, float* __restrict__ ssq, const f32x4 (&acc)[2][2][4][2], int row0, int col0, int slot) {
;     ...
;     for (int idx = 0; idx < 8; ++idx) {
;         const int ai = idx >> 2, m = idx & 3; const int r = row0 + ai * HALF + m * 16; const size_t off = (size_t)r * D + col0;
;         if (idx < 7) { const int ai2 = (idx + 1) >> 2, m2 = (idx + 1) & 3; const size_t off2 = (size_t)(row0 + ai2 * HALF + m2 * 16) * D + col0;
; #pragma unroll
;             for (int bj = 0; bj < 2; ++bj) ld(off2 + bj * HALF, xo[(idx + 1) & 1][bj][0], xo[(idx + 1) & 1][bj][1]); }
;         float ss = 0.f;
; #pragma unroll
;         for (int bj = 0; bj < 2; ++bj) { const f32x4 x0 = xo[idx & 1][bj][0] + acc[ai][bj][m][0], x1 = xo[idx & 1][bj][1] + acc[ai][bj][m][1];
;             u32x4 w; w.x = cvt_pk_bf16(x0[0], x0[1]); w.y = cvt_pk_bf16(x0[2], x0[3]); w.z = cvt_pk_bf16(x1[0], x1[1]); w.w = cvt_pk_bf16(x1[2], x1[3]);
;             *(u32x4*)(xb + off + bj * HALF) = w;
;             ss += ((x0[0] * x0[0] + x0[1] * x0[1]) + (x0[2] * x0[2] + x0[3] * x0[3])) + ((x1[0] * x1[0] + x1[1] * x1[1]) + (x1[2] * x1[2] + x1[3] * x1[3])); }
;         ss += __shfl_xor(ss, 16); ss += __shfl_xor(ss, 32);
	v_lshlrev_b32_e32 v100, 16, v72
	s_waitcnt vmcnt(5)
	v_lshlrev_b32_e32 v104, 16, v76
	v_and_b32_e32 v105, 0xffff0000, v76
	v_and_b32_e32 v101, 0xffff0000, v72
	v_lshlrev_b32_e32 v72, 16, v73
	v_and_b32_e32 v73, 0xffff0000, v73
	v_lshlrev_b32_e32 v102, 16, v74
	v_and_b32_e32 v103, 0xffff0000, v74
	v_lshlrev_b32_e32 v74, 16, v75
	v_and_b32_e32 v75, 0xffff0000, v75
	v_pk_add_f32 v[36:37], v[36:37], v[104:105]
	v_add_co_u32_e32 v104, vcc, s14, v166
	v_lshlrev_b32_e32 v76, 16, v77
	v_and_b32_e32 v77, 0xffff0000, v77
	v_lshlrev_b32_e32 v106, 16, v78
	v_and_b32_e32 v107, 0xffff0000, v78
	v_lshlrev_b32_e32 v78, 16, v79
	v_and_b32_e32 v79, 0xffff0000, v79
	v_pk_add_f32 v[46:47], v[46:47], v[72:73]
	v_pk_add_f32 v[80:81], v[44:45], v[100:101]
	v_pk_add_f32 v[100:101], v[42:43], v[74:75]
	v_pk_add_f32 v[102:103], v[40:41], v[102:103]
	v_cvt_pk_bf16_f32 v40, v80, v81
	v_cvt_pk_bf16_f32 v41, v46, v47
	v_addc_co_u32_e32 v105, vcc, 0, v167, vcc
	v_cvt_pk_bf16_f32 v42, v102, v103
	v_cvt_pk_bf16_f32 v43, v100, v101
	global_store_dwordx4 v[66:67], v[40:43], off nt
	v_pk_add_f32 v[66:67], v[38:39], v[76:77]
	v_pk_add_f32 v[76:77], v[34:35], v[78:79]
	v_pk_add_f32 v[78:79], v[32:33], v[106:107]
	v_cvt_pk_bf16_f32 v42, v36, v37
	v_cvt_pk_bf16_f32 v43, v66, v67
	v_add_f32_e32 v32, v123, v108
	v_cvt_pk_bf16_f32 v44, v78, v79
	v_cvt_pk_bf16_f32 v45, v76, v77
	global_load_dwordx4 v[52:55], v[104:105], off
	v_add_f32_e32 v32, v124, v32
	s_mov_b64 s[14:15], 0x58000
	v_add_f32_e32 v34, v121, v32
	v_lshl_add_u64 v[32:33], v[166:167], 0, s[14:15]
	global_load_dwordx4 v[72:75], v[32:33], off offset:256
	v_mul_f32_e32 v38, v61, v61
	v_mul_f32_e32 v39, v63, v63
	v_mul_f32_e32 v81, v81, v81
	v_mul_f32_e32 v47, v47, v47
	v_fmac_f32_e32 v38, v60, v60
	v_fmac_f32_e32 v39, v62, v62
	v_fmac_f32_e32 v81, v80, v80
	v_fmac_f32_e32 v47, v46, v46
	v_add_f32_e32 v38, v38, v39
	v_mul_f32_e32 v39, v57, v57
	v_mul_f32_e32 v40, v59, v59
	v_add_f32_e32 v46, v81, v47
	v_mul_f32_e32 v47, v103, v103
	v_mul_f32_e32 v80, v101, v101
	v_mul_f32_e32 v37, v37, v37
	v_fmac_f32_e32 v39, v56, v56
	v_fmac_f32_e32 v40, v58, v58
	v_fmac_f32_e32 v47, v102, v102
	v_fmac_f32_e32 v80, v100, v100
	v_fmac_f32_e32 v37, v36, v36
	v_mul_f32_e32 v36, v67, v67
	v_add_f32_e32 v47, v47, v80
	v_fmac_f32_e32 v36, v66, v66
	global_store_dwordx4 v[64:65], v[42:45], off offset:256 nt
	v_add_f32_e32 v46, v46, v47
	s_waitcnt vmcnt(6)
	v_lshlrev_b32_e32 v56, 16, v68
	v_and_b32_e32 v57, 0xffff0000, v68
	v_lshlrev_b32_e32 v58, 16, v69
	v_and_b32_e32 v59, 0xffff0000, v69
	v_lshlrev_b32_e32 v60, 16, v70
	v_and_b32_e32 v61, 0xffff0000, v70
	v_lshlrev_b32_e32 v62, 16, v71
	v_and_b32_e32 v63, 0xffff0000, v71
	v_pk_add_f32 v[30:31], v[30:31], v[58:59]
	v_pk_add_f32 v[28:29], v[28:29], v[56:57]
	v_pk_add_f32 v[58:59], v[24:25], v[60:61]
	v_cvt_pk_bf16_f32 v24, v28, v29
	v_cvt_pk_bf16_f32 v25, v30, v31
	v_add_f32_e32 v36, v37, v36
	v_mul_f32_e32 v37, v79, v79
	v_mul_f32_e32 v47, v77, v77
	v_pk_add_f32 v[56:57], v[26:27], v[62:63]
	v_cvt_pk_bf16_f32 v26, v58, v59
	v_fmac_f32_e32 v37, v78, v78
	v_cvt_pk_bf16_f32 v27, v56, v57
	global_store_dwordx4 v[50:51], v[24:27], off nt
	v_fmac_f32_e32 v47, v76, v76
	v_add_f32_e32 v37, v37, v47
	v_mul_f32_e32 v24, v29, v29
	v_mul_f32_e32 v25, v31, v31
	v_fmac_f32_e32 v24, v28, v28
	v_fmac_f32_e32 v25, v30, v30
	v_add_f32_e32 v24, v24, v25
	v_mul_f32_e32 v25, v59, v59
	v_mul_f32_e32 v26, v57, v57
	v_add_f32_e32 v39, v39, v40
	v_mul_f32_e32 v40, v83, v83
	s_waitcnt vmcnt(6)
	v_lshlrev_b32_e32 v68, 16, v88
	v_and_b32_e32 v69, 0xffff0000, v88
	v_add_f32_e32 v36, v36, v37
	v_fmac_f32_e32 v25, v58, v58
	v_fmac_f32_e32 v26, v56, v56
	v_fmac_f32_e32 v40, v82, v82
	v_lshlrev_b32_e32 v70, 16, v89
	v_and_b32_e32 v71, 0xffff0000, v89
	v_lshlrev_b32_e32 v82, 16, v90
	v_add_f32_e32 v36, v46, v36
	v_and_b32_e32 v83, 0xffff0000, v90
	v_lshlrev_b32_e32 v46, 16, v91
	v_and_b32_e32 v47, 0xffff0000, v91
	v_add_f32_e32 v25, v25, v26
	v_pk_add_f32 v[20:21], v[20:21], v[68:69]
	v_add_f32_e32 v26, v24, v25
	v_pk_add_f32 v[22:23], v[22:23], v[70:71]
	v_pk_add_f32 v[24:25], v[18:19], v[46:47]
	v_pk_add_f32 v[18:19], v[16:17], v[82:83]
	v_mul_f32_e32 v17, v21, v21
	v_cvt_pk_bf16_f32 v16, v20, v21
	v_fmac_f32_e32 v17, v20, v20
	v_mul_f32_e32 v20, v23, v23
	v_fmac_f32_e32 v20, v22, v22
	v_add_f32_e32 v17, v17, v20
	v_mul_f32_e32 v20, v19, v19
	v_mul_f32_e32 v21, v25, v25
	v_fmac_f32_e32 v20, v18, v18
	v_fmac_f32_e32 v21, v24, v24
	v_add_f32_e32 v20, v20, v21
	v_add_f32_e32 v17, v17, v20
	v_add_f32_e32 v20, v26, v17
	ds_bpermute_b32 v21, v180, v20
	s_waitcnt vmcnt(3)
; __device__ __forceinline__ unsigned cvt_pk_bf16(float lo, float hi) { unsigned r; asm volatile("v_cvt_pk_bf16_f32 %0, %1, %2" : "=v"(r) : "v"(lo), "v"(hi)); return r; }
; template <bool RD32>
; __device__ __forceinline__ void res_rows(const float* __restrict__ xold32, const bf16_t* __restrict__ xoldb, bf16_t* __restrict__ xb, float* __restrict__ ssq, const f32x4 (&acc)[2][2][4][2], int row0, int col0, int slot) {
;     ...
;         for (int bj = 0; bj < 2; ++bj) { const f32x4 x0 = xo[idx & 1][bj][0] + acc[ai][bj][m][0], x1 = xo[idx & 1][bj][1] + acc[ai][bj][m][1];
;             u32x4 w; w.x = cvt_pk_bf16(x0[0], x0[1]); w.y = cvt_pk_bf16(x0[2], x0[3]); w.z = cvt_pk_bf16(x1[0], x1[1]); w.w = cvt_pk_bf16(x1[2], x1[3]);
;             *(u32x4*)(xb + off + bj * HALF) = w;
;             ss += ((x0[0] * x0[0] + x0[1] * x0[1]) + (x0[2] * x0[2] + x0[3] * x0[3])) + ((x1[0] * x1[0] + x1[1] * x1[1]) + (x1[2] * x1[2] + x1[3] * x1[3])); }
;         ss += __shfl_xor(ss, 16); ss += __shfl_xor(ss, 32);
;         ssv[idx] = ss;
;     }
;     const int fq = slot >> 6;
; #pragma unroll
;     for (int j = 0; j < 2; ++j) { const float v = fq == 0 ? ssv[j] : fq == 1 ? ssv[2 + j] : fq == 2 ? ssv[4 + j] : ssv[6 + j]; const int idx = 2 * fq + j;
;         ssq[(size_t)(row0 + (idx >> 2) * HALF + (idx & 3) * 16) * 16 + (slot & 15)] = v; }
	v_lshlrev_b32_e32 v42, 16, v52
	v_and_b32_e32 v43, 0xffff0000, v52
	v_lshlrev_b32_e32 v44, 16, v53
	v_and_b32_e32 v45, 0xffff0000, v53
	v_lshlrev_b32_e32 v52, 16, v54
	v_and_b32_e32 v53, 0xffff0000, v54
	v_lshlrev_b32_e32 v54, 16, v55
	v_and_b32_e32 v55, 0xffff0000, v55
	v_cvt_pk_bf16_f32 v17, v22, v23
	v_cvt_pk_bf16_f32 v18, v18, v19
	v_cvt_pk_bf16_f32 v19, v24, v25
	global_store_dwordx4 v[48:49], v[16:19], off offset:256 nt
	v_pk_add_f32 v[14:15], v[14:15], v[44:45]
	v_pk_add_f32 v[12:13], v[12:13], v[42:43]
	s_waitcnt lgkmcnt(0)
	v_add_f32_e32 v16, v20, v21
	v_pk_add_f32 v[20:21], v[8:9], v[52:53]
	v_cvt_pk_bf16_f32 v8, v12, v13
	v_cvt_pk_bf16_f32 v9, v14, v15
	v_pk_add_f32 v[18:19], v[10:11], v[54:55]
	v_cvt_pk_bf16_f32 v10, v20, v21
	s_waitcnt vmcnt(3)
	v_lshlrev_b32_e32 v64, 16, v72
	v_cvt_pk_bf16_f32 v11, v18, v19
	global_store_dwordx4 v[104:105], v[8:11], off nt
	v_and_b32_e32 v65, 0xffff0000, v72
	v_lshlrev_b32_e32 v66, 16, v73
	v_mul_f32_e32 v8, v13, v13
	v_mul_f32_e32 v9, v15, v15
	v_fmac_f32_e32 v8, v12, v12
	v_fmac_f32_e32 v9, v14, v14
	v_add_f32_e32 v8, v8, v9
	v_mul_f32_e32 v9, v21, v21
	v_mul_f32_e32 v10, v19, v19
	v_fmac_f32_e32 v9, v20, v20
	v_fmac_f32_e32 v10, v18, v18
	v_and_b32_e32 v67, 0xffff0000, v73
	v_lshlrev_b32_e32 v72, 16, v74
	v_and_b32_e32 v73, 0xffff0000, v74
	v_lshlrev_b32_e32 v74, 16, v75
	v_and_b32_e32 v75, 0xffff0000, v75
	v_add_f32_e32 v9, v9, v10
	v_pk_add_f32 v[4:5], v[4:5], v[64:65]
	v_add_f32_e32 v10, v8, v9
	v_pk_add_f32 v[6:7], v[6:7], v[66:67]
	v_pk_add_f32 v[8:9], v[2:3], v[74:75]
	v_pk_add_f32 v[2:3], v[0:1], v[72:73]
	v_mul_f32_e32 v1, v5, v5
	v_add_f32_e32 v38, v38, v39
	v_mul_f32_e32 v39, v93, v93
	v_cvt_pk_bf16_f32 v0, v4, v5
	v_fmac_f32_e32 v1, v4, v4
	v_mul_f32_e32 v4, v7, v7
	v_fmac_f32_e32 v39, v92, v92
	v_fmac_f32_e32 v4, v6, v6
	v_add_f32_e32 v39, v39, v40
	v_mul_f32_e32 v40, v99, v99
	v_mul_f32_e32 v41, v95, v95
	v_add_f32_e32 v1, v1, v4
	v_mul_f32_e32 v4, v3, v3
	v_mul_f32_e32 v5, v9, v9
	v_fmac_f32_e32 v40, v98, v98
	v_fmac_f32_e32 v41, v94, v94
	v_fmac_f32_e32 v4, v2, v2
	v_fmac_f32_e32 v5, v8, v8
	v_add_f32_e32 v40, v40, v41
	v_add_f32_e32 v4, v4, v5
	v_add_f32_e32 v39, v39, v40
	v_add_f32_e32 v1, v1, v4
	v_add_f32_e32 v40, v38, v39
	v_add_f32_e32 v4, v10, v1
	ds_bpermute_b32 v35, v180, v34
	ds_bpermute_b32 v41, v180, v40
	ds_bpermute_b32 v37, v180, v36
	ds_bpermute_b32 v5, v180, v4
	v_cvt_pk_bf16_f32 v1, v6, v7
	v_cvt_pk_bf16_f32 v2, v2, v3
	v_lshlrev_b32_e32 v87, 2, v85
	v_add_f32_e32 v84, v84, v86
	v_add_f32_e32 v38, v97, v120
	s_waitcnt lgkmcnt(3)
	v_add_f32_e32 v34, v34, v35
	s_waitcnt lgkmcnt(2)
	v_add_f32_e32 v40, v40, v41
	s_waitcnt lgkmcnt(1)
	v_add_f32_e32 v36, v36, v37
	v_cvt_pk_bf16_f32 v3, v8, v9
	global_store_dwordx4 v[32:33], v[0:3], off offset:256 nt
	ds_bpermute_b32 v85, v87, v96
	ds_bpermute_b32 v86, v87, v84
	s_waitcnt lgkmcnt(2)
	v_add_f32_e32 v2, v4, v5
	ds_bpermute_b32 v39, v87, v38
	ds_bpermute_b32 v35, v87, v34
	ds_bpermute_b32 v41, v87, v40
	ds_bpermute_b32 v37, v87, v36
	ds_bpermute_b32 v17, v87, v16
	ds_bpermute_b32 v3, v87, v2
	s_and_b32 s14, s29, 12
	s_or_b32 s14, s14, s11
	s_lshl_b32 s14, s14, 2
	v_bitop3_b32 v0, s29, v216, v177 bitop3:0xc8
	s_add_u32 s46, s18, s14
	v_cmp_lt_u32_e32 vcc, 63, v179
	v_add_u32_e32 v0, v164, v0
	s_addc_u32 s47, s19, 0
	s_and_saveexec_b64 s[14:15], vcc
	s_xor_b64 s[48:49], exec, s[14:15]
	s_cbranch_execz .LBB0_626
	v_ashrrev_i32_e32 v4, 6, v179
	v_cmp_lt_i32_e32 vcc, 1, v4
	s_mov_b64 s[42:43], 0
	s_and_saveexec_b64 s[14:15], vcc
	s_xor_b64 s[50:51], exec, s[14:15]
	s_cbranch_execnz .LBB0_631
	s_or_saveexec_b64 s[50:51], s[50:51]
	v_cmp_ne_u32_e32 vcc, 1, v4
	s_xor_b64 exec, exec, s[50:51]
	s_cbranch_execnz .LBB0_634
